# loop-edge edit: the 13 GEMM K-loops' counter/pointer SALU block moved above the loop-back s_barrier (only the branch stays after it)
# baseline (speedup 1.0000x reference)
.LBB0_338:
	v_add_u32_e32 v138, s61, v1
	ds_read_b128 v[148:151], v138
	ds_read_b128 v[152:155], v138 offset:1024
	ds_read_b128 v[156:159], v138 offset:2048
	ds_read_b128 v[160:163], v138 offset:3072
	v_add_u32_e32 v138, s62, v1
	ds_read_b128 v[164:167], v138
	ds_read_b128 v[170:173], v138 offset:1024
	ds_read_b128 v[174:177], v138 offset:2048
	ds_read_b128 v[178:181], v138 offset:3072
	s_add_i32 s44, s4, 2
	s_add_u32 s45, s2, 0x80
	s_addc_u32 s5, s3, 0
	s_cmp_eq_u32 s54, s4
	s_cselect_b32 s4, s36, s45
	s_cselect_b32 s5, s37, s5
	s_cselect_b32 s49, s39, s43
	s_cselect_b32 s48, s38, s42
	v_lshl_add_u64 v[198:199], s[2:3], 0, v[140:141]
	s_add_i32 m0, s81, 0xc000
	ds_read_b128 v[182:185], v169
	ds_read_b128 v[186:189], v169 offset:1024
	ds_read_b128 v[190:193], v169 offset:2048
	ds_read_b128 v[194:197], v169 offset:3072
	ds_read_b128 v[202:205], v169 offset:4096
	ds_read_b128 v[206:209], v169 offset:5120
	ds_read_b128 v[210:213], v169 offset:6144
	ds_read_b128 v[214:217], v169 offset:7168
	global_load_lds_dwordx4 v[198:199], off
	v_lshl_add_u64 v[198:199], s[2:3], 0, v[142:143]
	s_add_i32 m0, s81, 0xe000
	s_nop 0
	global_load_lds_dwordx4 v[198:199], off
	s_waitcnt vmcnt(8)
	s_waitcnt lgkmcnt(0)
	s_barrier
	s_setprio 1
	s_waitcnt lgkmcnt(0)
	v_mfma_i32_16x16x64_i8 v[126:129], v[148:151], v[182:185], v[126:129]
	v_mfma_i32_16x16x64_i8 v[122:125], v[156:159], v[182:185], v[122:125]
	v_mfma_i32_16x16x64_i8 v[118:121], v[148:151], v[190:193], v[118:121]
	v_mfma_i32_16x16x64_i8 v[114:117], v[156:159], v[190:193], v[114:117]
	v_mfma_i32_16x16x64_i8 v[106:109], v[148:151], v[202:205], v[106:109]
	v_mfma_i32_16x16x64_i8 v[98:101], v[156:159], v[202:205], v[98:101]
	v_mfma_i32_16x16x64_i8 v[90:93], v[148:151], v[210:213], v[90:93]
	v_mfma_i32_16x16x64_i8 v[82:85], v[156:159], v[210:213], v[82:85]
	v_mfma_i32_16x16x64_i8 v[126:129], v[152:155], v[186:189], v[126:129]
	v_mfma_i32_16x16x64_i8 v[122:125], v[160:163], v[186:189], v[122:125]
	v_mfma_i32_16x16x64_i8 v[118:121], v[152:155], v[194:197], v[118:121]
	v_mfma_i32_16x16x64_i8 v[114:117], v[160:163], v[194:197], v[114:117]
	v_mfma_i32_16x16x64_i8 v[106:109], v[152:155], v[206:209], v[106:109]
	v_mfma_i32_16x16x64_i8 v[98:101], v[160:163], v[206:209], v[98:101]
	v_mfma_i32_16x16x64_i8 v[90:93], v[152:155], v[214:217], v[90:93]
	v_mfma_i32_16x16x64_i8 v[82:85], v[160:163], v[214:217], v[82:85]
	s_setprio 0
	s_setprio 1
	v_mfma_i32_16x16x64_i8 v[110:113], v[164:167], v[182:185], v[110:113]
	v_mfma_i32_16x16x64_i8 v[102:105], v[174:177], v[182:185], v[102:105]
	v_mfma_i32_16x16x64_i8 v[94:97], v[164:167], v[190:193], v[94:97]
	v_mfma_i32_16x16x64_i8 v[86:89], v[174:177], v[190:193], v[86:89]
	v_mfma_i32_16x16x64_i8 v[78:81], v[164:167], v[202:205], v[78:81]
	v_mfma_i32_16x16x64_i8 v[74:77], v[174:177], v[202:205], v[74:77]
	v_mfma_i32_16x16x64_i8 v[70:73], v[164:167], v[210:213], v[70:73]
	v_mfma_i32_16x16x64_i8 v[66:69], v[174:177], v[210:213], v[66:69]
	v_mfma_i32_16x16x64_i8 v[110:113], v[170:173], v[186:189], v[110:113]
	v_mfma_i32_16x16x64_i8 v[102:105], v[178:181], v[186:189], v[102:105]
	v_mfma_i32_16x16x64_i8 v[94:97], v[170:173], v[194:197], v[94:97]
	v_mfma_i32_16x16x64_i8 v[86:89], v[178:181], v[194:197], v[86:89]
	v_mfma_i32_16x16x64_i8 v[78:81], v[170:173], v[206:209], v[78:81]
	v_mfma_i32_16x16x64_i8 v[74:77], v[178:181], v[206:209], v[74:77]
	v_mfma_i32_16x16x64_i8 v[70:73], v[170:173], v[214:217], v[70:73]
	v_mfma_i32_16x16x64_i8 v[66:69], v[178:181], v[214:217], v[66:69]
	s_setprio 0
	s_barrier
	s_add_i32 s45, s61, s67
	v_lshl_add_u64 v[198:199], s[48:49], 0, v[132:133]
	s_mov_b32 m0, s45
	ds_read_b128 v[182:185], v169 offset:16384
	ds_read_b128 v[186:189], v169 offset:17408
	ds_read_b128 v[190:193], v169 offset:18432
	ds_read_b128 v[194:197], v169 offset:19456
	ds_read_b128 v[202:205], v169 offset:20480
	ds_read_b128 v[206:209], v169 offset:21504
	ds_read_b128 v[210:213], v169 offset:22528
	ds_read_b128 v[214:217], v169 offset:23552
	global_load_lds_dwordx4 v[198:199], off
	s_add_i32 m0, s45, 0x2000
	v_lshl_add_u64 v[218:219], s[48:49], 0, v[136:137]
	s_add_u32 s48, s48, s16
	s_addc_u32 s49, s49, s17
	s_add_i32 s45, s62, s67
	global_load_lds_dwordx4 v[218:219], off
	v_lshl_add_u64 v[220:221], s[48:49], 0, v[132:133]
	s_mov_b32 m0, s45
	v_lshl_add_u64 v[222:223], s[48:49], 0, v[136:137]
	global_load_lds_dwordx4 v[220:221], off
	s_add_i32 m0, s45, 0x2000
	v_lshl_add_u64 v[224:225], s[4:5], 0, v[130:131]
	global_load_lds_dwordx4 v[222:223], off
	s_mov_b32 m0, s81
	v_lshl_add_u64 v[226:227], s[4:5], 0, v[134:135]
	global_load_lds_dwordx4 v[224:225], off
	s_mov_b32 m0, s90
	s_nop 0
	global_load_lds_dwordx4 v[226:227], off
	s_waitcnt vmcnt(8)
	s_waitcnt lgkmcnt(0)
	s_barrier
	s_setprio 1
	s_waitcnt lgkmcnt(0)
	v_mfma_i32_16x16x64_i8 v[62:65], v[148:151], v[182:185], v[62:65]
	v_mfma_i32_16x16x64_i8 v[58:61], v[156:159], v[182:185], v[58:61]
	v_mfma_i32_16x16x64_i8 v[54:57], v[148:151], v[190:193], v[54:57]
	v_mfma_i32_16x16x64_i8 v[50:53], v[156:159], v[190:193], v[50:53]
	v_mfma_i32_16x16x64_i8 v[42:45], v[148:151], v[202:205], v[42:45]
	v_mfma_i32_16x16x64_i8 v[34:37], v[156:159], v[202:205], v[34:37]
	v_mfma_i32_16x16x64_i8 v[26:29], v[148:151], v[210:213], v[26:29]
	v_mfma_i32_16x16x64_i8 v[18:21], v[156:159], v[210:213], v[18:21]
	v_mfma_i32_16x16x64_i8 v[62:65], v[152:155], v[186:189], v[62:65]
	v_mfma_i32_16x16x64_i8 v[58:61], v[160:163], v[186:189], v[58:61]
	v_mfma_i32_16x16x64_i8 v[54:57], v[152:155], v[194:197], v[54:57]
	v_mfma_i32_16x16x64_i8 v[50:53], v[160:163], v[194:197], v[50:53]
	v_mfma_i32_16x16x64_i8 v[42:45], v[152:155], v[206:209], v[42:45]
	v_mfma_i32_16x16x64_i8 v[34:37], v[160:163], v[206:209], v[34:37]
	v_mfma_i32_16x16x64_i8 v[26:29], v[152:155], v[214:217], v[26:29]
	v_mfma_i32_16x16x64_i8 v[18:21], v[160:163], v[214:217], v[18:21]
	s_setprio 0
	s_setprio 1
	v_mfma_i32_16x16x64_i8 v[46:49], v[164:167], v[182:185], v[46:49]
	v_mfma_i32_16x16x64_i8 v[38:41], v[174:177], v[182:185], v[38:41]
	v_mfma_i32_16x16x64_i8 v[30:33], v[164:167], v[190:193], v[30:33]
	v_mfma_i32_16x16x64_i8 v[22:25], v[174:177], v[190:193], v[22:25]
	v_mfma_i32_16x16x64_i8 v[14:17], v[164:167], v[202:205], v[14:17]
	v_mfma_i32_16x16x64_i8 v[10:13], v[174:177], v[202:205], v[10:13]
	v_mfma_i32_16x16x64_i8 v[6:9], v[164:167], v[210:213], v[6:9]
	v_mfma_i32_16x16x64_i8 v[2:5], v[174:177], v[210:213], v[2:5]
	v_mfma_i32_16x16x64_i8 v[46:49], v[170:173], v[186:189], v[46:49]
	v_mfma_i32_16x16x64_i8 v[38:41], v[178:181], v[186:189], v[38:41]
	v_mfma_i32_16x16x64_i8 v[30:33], v[170:173], v[194:197], v[30:33]
	v_mfma_i32_16x16x64_i8 v[22:25], v[178:181], v[194:197], v[22:25]
	v_mfma_i32_16x16x64_i8 v[14:17], v[170:173], v[206:209], v[14:17]
	v_mfma_i32_16x16x64_i8 v[10:13], v[178:181], v[206:209], v[10:13]
	v_mfma_i32_16x16x64_i8 v[6:9], v[170:173], v[214:217], v[6:9]
	v_mfma_i32_16x16x64_i8 v[2:5], v[178:181], v[214:217], v[2:5]
	s_setprio 0
	s_barrier
	s_add_i32 s45, 0, 0x18000
	v_add_u32_e32 v138, s45, v1
	s_add_i32 s47, 0, 0x1c000
	ds_read_b128 v[148:151], v138
	ds_read_b128 v[152:155], v138 offset:1024
	ds_read_b128 v[156:159], v138 offset:2048
	ds_read_b128 v[160:163], v138 offset:3072
	v_add_u32_e32 v138, s47, v1
	ds_read_b128 v[164:167], v138
	ds_read_b128 v[170:173], v138 offset:1024
	ds_read_b128 v[174:177], v138 offset:2048
	ds_read_b128 v[178:181], v138 offset:3072
	s_add_u32 s4, s4, s16
	s_addc_u32 s5, s5, s17
	s_mov_b32 m0, s91
	v_lshl_add_u64 v[228:229], s[4:5], 0, v[130:131]
	ds_read_b128 v[182:185], v169 offset:32768
	ds_read_b128 v[186:189], v169 offset:33792
	ds_read_b128 v[190:193], v169 offset:34816
	ds_read_b128 v[194:197], v169 offset:35840
	ds_read_b128 v[202:205], v169 offset:36864
	ds_read_b128 v[206:209], v169 offset:37888
	ds_read_b128 v[210:213], v169 offset:38912
	ds_read_b128 v[214:217], v169 offset:39936
	global_load_lds_dwordx4 v[228:229], off
	v_lshl_add_u64 v[228:229], s[4:5], 0, v[134:135]
	s_mov_b32 m0, s92
	s_nop 0
	global_load_lds_dwordx4 v[228:229], off
	s_waitcnt vmcnt(8)
	s_waitcnt lgkmcnt(0)
	s_barrier
	s_setprio 1
	s_waitcnt lgkmcnt(0)
	v_mfma_i32_16x16x64_i8 v[126:129], v[148:151], v[182:185], v[126:129]
	v_mfma_i32_16x16x64_i8 v[122:125], v[156:159], v[182:185], v[122:125]
	v_mfma_i32_16x16x64_i8 v[118:121], v[148:151], v[190:193], v[118:121]
	v_mfma_i32_16x16x64_i8 v[114:117], v[156:159], v[190:193], v[114:117]
	v_mfma_i32_16x16x64_i8 v[106:109], v[148:151], v[202:205], v[106:109]
	v_mfma_i32_16x16x64_i8 v[98:101], v[156:159], v[202:205], v[98:101]
	v_mfma_i32_16x16x64_i8 v[90:93], v[148:151], v[210:213], v[90:93]
	v_mfma_i32_16x16x64_i8 v[82:85], v[156:159], v[210:213], v[82:85]
	v_mfma_i32_16x16x64_i8 v[126:129], v[152:155], v[186:189], v[126:129]
	v_mfma_i32_16x16x64_i8 v[122:125], v[160:163], v[186:189], v[122:125]
	v_mfma_i32_16x16x64_i8 v[118:121], v[152:155], v[194:197], v[118:121]
	v_mfma_i32_16x16x64_i8 v[114:117], v[160:163], v[194:197], v[114:117]
	v_mfma_i32_16x16x64_i8 v[106:109], v[152:155], v[206:209], v[106:109]
	v_mfma_i32_16x16x64_i8 v[98:101], v[160:163], v[206:209], v[98:101]
	v_mfma_i32_16x16x64_i8 v[90:93], v[152:155], v[214:217], v[90:93]
	v_mfma_i32_16x16x64_i8 v[82:85], v[160:163], v[214:217], v[82:85]
	s_setprio 0
	s_setprio 1
	v_mfma_i32_16x16x64_i8 v[110:113], v[164:167], v[182:185], v[110:113]
	v_mfma_i32_16x16x64_i8 v[102:105], v[174:177], v[182:185], v[102:105]
	v_mfma_i32_16x16x64_i8 v[94:97], v[164:167], v[190:193], v[94:97]
	v_mfma_i32_16x16x64_i8 v[86:89], v[174:177], v[190:193], v[86:89]
	v_mfma_i32_16x16x64_i8 v[78:81], v[164:167], v[202:205], v[78:81]
	v_mfma_i32_16x16x64_i8 v[74:77], v[174:177], v[202:205], v[74:77]
	v_mfma_i32_16x16x64_i8 v[70:73], v[164:167], v[210:213], v[70:73]
	v_mfma_i32_16x16x64_i8 v[66:69], v[174:177], v[210:213], v[66:69]
	v_mfma_i32_16x16x64_i8 v[110:113], v[170:173], v[186:189], v[110:113]
	v_mfma_i32_16x16x64_i8 v[102:105], v[178:181], v[186:189], v[102:105]
	v_mfma_i32_16x16x64_i8 v[94:97], v[170:173], v[194:197], v[94:97]
	v_mfma_i32_16x16x64_i8 v[86:89], v[178:181], v[194:197], v[86:89]
	v_mfma_i32_16x16x64_i8 v[78:81], v[170:173], v[206:209], v[78:81]
	v_mfma_i32_16x16x64_i8 v[74:77], v[178:181], v[206:209], v[74:77]
	v_mfma_i32_16x16x64_i8 v[70:73], v[170:173], v[214:217], v[70:73]
	v_mfma_i32_16x16x64_i8 v[66:69], v[178:181], v[214:217], v[66:69]
	s_setprio 0
	s_barrier
	s_add_i32 s4, s45, s67
	v_lshl_add_u64 v[198:199], v[198:199], 0, s[26:27]
	s_mov_b32 m0, s4
	ds_read_b128 v[182:185], v169 offset:49152
	ds_read_b128 v[186:189], v169 offset:50176
	ds_read_b128 v[190:193], v169 offset:51200
	ds_read_b128 v[194:197], v169 offset:52224
	ds_read_b128 v[202:205], v169 offset:53248
	ds_read_b128 v[206:209], v169 offset:54272
	ds_read_b128 v[210:213], v169 offset:55296
	ds_read_b128 v[214:217], v169 offset:56320
	global_load_lds_dwordx4 v[198:199], off
	v_lshl_add_u64 v[198:199], v[218:219], 0, s[26:27]
	s_add_i32 m0, s4, 0x2000
	s_add_i32 s4, s47, s67
	global_load_lds_dwordx4 v[198:199], off
	v_lshl_add_u64 v[198:199], v[220:221], 0, s[26:27]
	s_mov_b32 m0, s4
	s_nop 0
	global_load_lds_dwordx4 v[198:199], off
	v_lshl_add_u64 v[198:199], v[222:223], 0, s[26:27]
	s_add_i32 m0, s4, 0x2000
	s_nop 0
	global_load_lds_dwordx4 v[198:199], off
	v_lshl_add_u64 v[198:199], v[224:225], 0, s[26:27]
	s_mov_b32 m0, s97
	s_nop 0
	global_load_lds_dwordx4 v[198:199], off
	v_lshl_add_u64 v[198:199], v[226:227], 0, s[26:27]
	s_mov_b32 m0, s6
	s_nop 0
	global_load_lds_dwordx4 v[198:199], off
	s_waitcnt vmcnt(8)
	s_waitcnt lgkmcnt(0)
	s_barrier
	s_setprio 1
	s_waitcnt lgkmcnt(0)
	v_mfma_i32_16x16x64_i8 v[62:65], v[148:151], v[182:185], v[62:65]
	v_mfma_i32_16x16x64_i8 v[58:61], v[156:159], v[182:185], v[58:61]
	v_mfma_i32_16x16x64_i8 v[54:57], v[148:151], v[190:193], v[54:57]
	v_mfma_i32_16x16x64_i8 v[50:53], v[156:159], v[190:193], v[50:53]
	v_mfma_i32_16x16x64_i8 v[42:45], v[148:151], v[202:205], v[42:45]
	v_mfma_i32_16x16x64_i8 v[34:37], v[156:159], v[202:205], v[34:37]
	v_mfma_i32_16x16x64_i8 v[26:29], v[148:151], v[210:213], v[26:29]
	v_mfma_i32_16x16x64_i8 v[18:21], v[156:159], v[210:213], v[18:21]
	v_mfma_i32_16x16x64_i8 v[62:65], v[152:155], v[186:189], v[62:65]
	v_mfma_i32_16x16x64_i8 v[58:61], v[160:163], v[186:189], v[58:61]
	v_mfma_i32_16x16x64_i8 v[54:57], v[152:155], v[194:197], v[54:57]
	v_mfma_i32_16x16x64_i8 v[50:53], v[160:163], v[194:197], v[50:53]
	v_mfma_i32_16x16x64_i8 v[42:45], v[152:155], v[206:209], v[42:45]
	v_mfma_i32_16x16x64_i8 v[34:37], v[160:163], v[206:209], v[34:37]
	v_mfma_i32_16x16x64_i8 v[26:29], v[152:155], v[214:217], v[26:29]
	v_mfma_i32_16x16x64_i8 v[18:21], v[160:163], v[214:217], v[18:21]
	s_setprio 0
	s_setprio 1
	v_mfma_i32_16x16x64_i8 v[46:49], v[164:167], v[182:185], v[46:49]
	v_mfma_i32_16x16x64_i8 v[38:41], v[174:177], v[182:185], v[38:41]
	v_mfma_i32_16x16x64_i8 v[30:33], v[164:167], v[190:193], v[30:33]
	v_mfma_i32_16x16x64_i8 v[22:25], v[174:177], v[190:193], v[22:25]
	v_mfma_i32_16x16x64_i8 v[14:17], v[164:167], v[202:205], v[14:17]
	v_mfma_i32_16x16x64_i8 v[10:13], v[174:177], v[202:205], v[10:13]
	v_mfma_i32_16x16x64_i8 v[6:9], v[164:167], v[210:213], v[6:9]
	v_mfma_i32_16x16x64_i8 v[2:5], v[174:177], v[210:213], v[2:5]
	v_mfma_i32_16x16x64_i8 v[46:49], v[170:173], v[186:189], v[46:49]
	v_mfma_i32_16x16x64_i8 v[38:41], v[178:181], v[186:189], v[38:41]
	v_mfma_i32_16x16x64_i8 v[30:33], v[170:173], v[194:197], v[30:33]
	v_mfma_i32_16x16x64_i8 v[22:25], v[178:181], v[194:197], v[22:25]
	v_mfma_i32_16x16x64_i8 v[14:17], v[170:173], v[206:209], v[14:17]
	v_mfma_i32_16x16x64_i8 v[10:13], v[178:181], v[206:209], v[10:13]
	v_mfma_i32_16x16x64_i8 v[6:9], v[170:173], v[214:217], v[6:9]
	v_mfma_i32_16x16x64_i8 v[2:5], v[178:181], v[214:217], v[2:5]
	s_setprio 0
	s_add_u32 s2, s2, 0x100
	s_addc_u32 s3, s3, 0
	s_add_u32 s42, s42, 0x100
	s_addc_u32 s43, s43, 0
	s_cmp_ge_i32 s44, s7
	s_mov_b32 s4, s44
	s_barrier
	s_cbranch_scc0 .LBB0_338
	v_cvt_f32_i32_e32 v182, v126
	v_cvt_f32_i32_e32 v183, v127
	v_cvt_f32_i32_e32 v180, v128
	v_cvt_f32_i32_e32 v181, v129
	v_cvt_f32_i32_e32 v184, v122
	v_cvt_f32_i32_e32 v185, v123
	v_cvt_f32_i32_e32 v186, v124
	v_cvt_f32_i32_e32 v187, v125
	v_cvt_f32_i32_e32 v170, v110
	v_cvt_f32_i32_e32 v171, v111
	v_cvt_f32_i32_e32 v174, v112
	v_cvt_f32_i32_e32 v175, v113
	v_cvt_f32_i32_e32 v172, v102
	v_cvt_f32_i32_e32 v173, v103
	v_cvt_f32_i32_e32 v166, v104
	v_cvt_f32_i32_e32 v167, v105
	v_cvt_f32_i32_e32 v162, v118
	v_cvt_f32_i32_e32 v163, v119
	v_cvt_f32_i32_e32 v164, v120
	v_cvt_f32_i32_e32 v165, v121
	v_cvt_f32_i32_e32 v158, v114
	v_cvt_f32_i32_e32 v159, v115
	v_cvt_f32_i32_e32 v160, v116
	v_cvt_f32_i32_e32 v161, v117
	v_cvt_f32_i32_e32 v150, v94
	v_cvt_f32_i32_e32 v151, v95
	v_cvt_f32_i32_e32 v154, v96
	v_cvt_f32_i32_e32 v155, v97
	v_cvt_f32_i32_e32 v128, v86
	v_cvt_f32_i32_e32 v129, v87
	v_cvt_f32_i32_e32 v148, v88
	v_cvt_f32_i32_e32 v149, v89
	v_cvt_f32_i32_e32 v124, v106
	v_cvt_f32_i32_e32 v125, v107
	v_cvt_f32_i32_e32 v126, v108
	v_cvt_f32_i32_e32 v127, v109
	v_cvt_f32_i32_e32 v120, v98
	v_cvt_f32_i32_e32 v121, v99
	v_cvt_f32_i32_e32 v122, v100
	v_cvt_f32_i32_e32 v123, v101
	v_cvt_f32_i32_e32 v114, v78
	v_cvt_f32_i32_e32 v115, v79
	v_cvt_f32_i32_e32 v116, v80
	v_cvt_f32_i32_e32 v117, v81
	v_cvt_f32_i32_e32 v110, v74
	v_cvt_f32_i32_e32 v111, v75
	v_cvt_f32_i32_e32 v112, v76
	v_cvt_f32_i32_e32 v113, v77
	v_cvt_f32_i32_e32 v104, v90
	v_cvt_f32_i32_e32 v105, v91
	v_cvt_f32_i32_e32 v106, v92
	v_cvt_f32_i32_e32 v107, v93
	v_cvt_f32_i32_e32 v100, v82
	v_cvt_f32_i32_e32 v101, v83
	v_cvt_f32_i32_e32 v102, v84
	v_cvt_f32_i32_e32 v103, v85
	v_cvt_f32_i32_e32 v96, v70
	v_cvt_f32_i32_e32 v97, v71
	v_cvt_f32_i32_e32 v98, v72
	v_cvt_f32_i32_e32 v99, v73
	v_cvt_f32_i32_e32 v92, v66
	v_cvt_f32_i32_e32 v93, v67
	v_cvt_f32_i32_e32 v94, v68
	v_cvt_f32_i32_e32 v95, v69
	v_cvt_f32_i32_e32 v86, v62
	v_cvt_f32_i32_e32 v87, v63
	v_cvt_f32_i32_e32 v88, v64
	v_cvt_f32_i32_e32 v89, v65
	v_cvt_f32_i32_e32 v82, v58
	v_cvt_f32_i32_e32 v83, v59
	v_cvt_f32_i32_e32 v84, v60
	v_cvt_f32_i32_e32 v85, v61
	v_cvt_f32_i32_e32 v78, v46
	v_cvt_f32_i32_e32 v79, v47
	v_cvt_f32_i32_e32 v80, v48
	v_cvt_f32_i32_e32 v81, v49
	v_cvt_f32_i32_e32 v74, v38
	v_cvt_f32_i32_e32 v75, v39
	v_cvt_f32_i32_e32 v76, v40
	v_cvt_f32_i32_e32 v77, v41
	v_cvt_f32_i32_e32 v68, v54
	v_cvt_f32_i32_e32 v69, v55
	v_cvt_f32_i32_e32 v70, v56
	v_cvt_f32_i32_e32 v71, v57
	v_cvt_f32_i32_e32 v64, v50
	v_cvt_f32_i32_e32 v65, v51
	v_cvt_f32_i32_e32 v66, v52
	v_cvt_f32_i32_e32 v67, v53
	v_cvt_f32_i32_e32 v60, v30
	v_cvt_f32_i32_e32 v61, v31
	v_cvt_f32_i32_e32 v62, v32
	v_cvt_f32_i32_e32 v63, v33
	v_cvt_f32_i32_e32 v56, v22
	v_cvt_f32_i32_e32 v57, v23
	v_cvt_f32_i32_e32 v58, v24
	v_cvt_f32_i32_e32 v59, v25
	v_cvt_f32_i32_e32 v50, v42
	v_cvt_f32_i32_e32 v51, v43
	v_cvt_f32_i32_e32 v52, v44
	v_cvt_f32_i32_e32 v53, v45
	v_cvt_f32_i32_e32 v46, v34
	v_cvt_f32_i32_e32 v47, v35
	v_cvt_f32_i32_e32 v48, v36
	v_cvt_f32_i32_e32 v49, v37
	v_cvt_f32_i32_e32 v34, v14
	v_cvt_f32_i32_e32 v35, v15
	v_cvt_f32_i32_e32 v36, v16
	v_cvt_f32_i32_e32 v37, v17
	v_cvt_f32_i32_e32 v30, v10
	v_cvt_f32_i32_e32 v31, v11
	v_cvt_f32_i32_e32 v32, v12
	v_cvt_f32_i32_e32 v33, v13
	v_cvt_f32_i32_e32 v22, v26
	v_cvt_f32_i32_e32 v23, v27
	v_cvt_f32_i32_e32 v24, v28
	v_cvt_f32_i32_e32 v25, v29
	v_cvt_f32_i32_e32 v18, v18
	v_cvt_f32_i32_e32 v19, v19
	v_cvt_f32_i32_e32 v20, v20
	v_cvt_f32_i32_e32 v21, v21
	v_cvt_f32_i32_e32 v14, v6
	v_cvt_f32_i32_e32 v15, v7
	v_cvt_f32_i32_e32 v16, v8
	v_cvt_f32_i32_e32 v17, v9
	v_cvt_f32_i32_e32 v10, v2
	v_cvt_f32_i32_e32 v11, v3
	v_cvt_f32_i32_e32 v12, v4
	v_cvt_f32_i32_e32 v13, v5

.LBB0_549:
	ds_read_b128 v[148:151], v154
	ds_read_b128 v[158:161], v154 offset:1024
	ds_read_b128 v[162:165], v154 offset:2048
	ds_read_b128 v[170:173], v154 offset:3072
	ds_read_b128 v[174:177], v155
	ds_read_b128 v[178:181], v155 offset:1024
	ds_read_b128 v[182:185], v155 offset:2048
	ds_read_b128 v[186:189], v155 offset:3072
	s_add_u32 s64, s56, 0xfff00080
	s_addc_u32 s65, s57, -1
	s_cmp_eq_u32 s93, 60
	s_cselect_b32 s67, s45, s65
	s_cselect_b32 s66, s51, s64
	s_cselect_b32 s65, s43, s83
	s_cselect_b32 s64, s79, s82
	v_lshl_add_u64 v[152:153], s[56:57], 0, v[140:141]
	s_add_i32 m0, s7, 0xc000
	ds_read_b128 v[190:193], v156
	ds_read_b128 v[194:197], v156 offset:1024
	ds_read_b128 v[198:201], v156 offset:2048
	ds_read_b128 v[202:205], v156 offset:3072
	ds_read_b128 v[206:209], v156 offset:4096
	ds_read_b128 v[210:213], v156 offset:5120
	ds_read_b128 v[214:217], v156 offset:6144
	ds_read_b128 v[218:221], v156 offset:7168
	global_load_lds_dwordx4 v[152:153], off
	v_lshl_add_u64 v[152:153], s[56:57], 0, v[142:143]
	s_add_i32 m0, s7, 0xe000
	s_nop 0
	global_load_lds_dwordx4 v[152:153], off
	s_waitcnt vmcnt(8)
	s_waitcnt lgkmcnt(0)
	s_barrier
	s_setprio 1
	s_waitcnt lgkmcnt(0)
	v_mfma_f32_16x16x32_bf16 v[126:129], v[148:151], v[190:193], v[126:129]
	v_mfma_f32_16x16x32_bf16 v[122:125], v[162:165], v[190:193], v[122:125]
	v_mfma_f32_16x16x32_bf16 v[118:121], v[148:151], v[198:201], v[118:121]
	v_mfma_f32_16x16x32_bf16 v[114:117], v[162:165], v[198:201], v[114:117]
	v_mfma_f32_16x16x32_bf16 v[102:105], v[148:151], v[206:209], v[102:105]
	v_mfma_f32_16x16x32_bf16 v[98:101], v[162:165], v[206:209], v[98:101]
	v_mfma_f32_16x16x32_bf16 v[86:89], v[148:151], v[214:217], v[86:89]
	v_mfma_f32_16x16x32_bf16 v[82:85], v[162:165], v[214:217], v[82:85]
	v_mfma_f32_16x16x32_bf16 v[126:129], v[158:161], v[194:197], v[126:129]
	v_mfma_f32_16x16x32_bf16 v[122:125], v[170:173], v[194:197], v[122:125]
	v_mfma_f32_16x16x32_bf16 v[118:121], v[158:161], v[202:205], v[118:121]
	v_mfma_f32_16x16x32_bf16 v[114:117], v[170:173], v[202:205], v[114:117]
	v_mfma_f32_16x16x32_bf16 v[102:105], v[158:161], v[210:213], v[102:105]
	v_mfma_f32_16x16x32_bf16 v[98:101], v[170:173], v[210:213], v[98:101]
	v_mfma_f32_16x16x32_bf16 v[86:89], v[158:161], v[218:221], v[86:89]
	v_mfma_f32_16x16x32_bf16 v[82:85], v[170:173], v[218:221], v[82:85]
	s_setprio 0
	s_setprio 1
	v_mfma_f32_16x16x32_bf16 v[110:113], v[174:177], v[190:193], v[110:113]
	v_mfma_f32_16x16x32_bf16 v[106:109], v[182:185], v[190:193], v[106:109]
	v_mfma_f32_16x16x32_bf16 v[94:97], v[174:177], v[198:201], v[94:97]
	v_mfma_f32_16x16x32_bf16 v[90:93], v[182:185], v[198:201], v[90:93]
	v_mfma_f32_16x16x32_bf16 v[78:81], v[174:177], v[206:209], v[78:81]
	v_mfma_f32_16x16x32_bf16 v[74:77], v[182:185], v[206:209], v[74:77]
	v_mfma_f32_16x16x32_bf16 v[70:73], v[174:177], v[214:217], v[70:73]
	v_mfma_f32_16x16x32_bf16 v[66:69], v[182:185], v[214:217], v[66:69]
	v_mfma_f32_16x16x32_bf16 v[110:113], v[178:181], v[194:197], v[110:113]
	v_mfma_f32_16x16x32_bf16 v[106:109], v[186:189], v[194:197], v[106:109]
	v_mfma_f32_16x16x32_bf16 v[94:97], v[178:181], v[202:205], v[94:97]
	v_mfma_f32_16x16x32_bf16 v[90:93], v[186:189], v[202:205], v[90:93]
	v_mfma_f32_16x16x32_bf16 v[78:81], v[178:181], v[210:213], v[78:81]
	v_mfma_f32_16x16x32_bf16 v[74:77], v[186:189], v[210:213], v[74:77]
	v_mfma_f32_16x16x32_bf16 v[70:73], v[178:181], v[218:221], v[70:73]
	v_mfma_f32_16x16x32_bf16 v[66:69], v[186:189], v[218:221], v[66:69]
	s_setprio 0
	s_barrier
	s_add_i32 s95, s71, s6
	v_lshl_add_u64 v[152:153], s[64:65], 0, v[132:133]
	s_mov_b32 m0, s95
	ds_read_b128 v[190:193], v156 offset:16384
	ds_read_b128 v[194:197], v156 offset:17408
	ds_read_b128 v[198:201], v156 offset:18432
	ds_read_b128 v[202:205], v156 offset:19456
	ds_read_b128 v[206:209], v156 offset:20480
	ds_read_b128 v[210:213], v156 offset:21504
	ds_read_b128 v[214:217], v156 offset:22528
	ds_read_b128 v[218:221], v156 offset:23552
	global_load_lds_dwordx4 v[152:153], off
	s_add_i32 m0, s95, 0x2000
	s_add_u32 vcc_lo, s64, 0x100000
	v_lshl_add_u64 v[166:167], s[64:65], 0, v[136:137]
	s_addc_u32 vcc_hi, s65, 0
	s_add_i32 s95, s72, s6
	global_load_lds_dwordx4 v[166:167], off
	v_lshl_add_u64 v[222:223], vcc, 0, v[132:133]
	s_mov_b32 m0, s95
	v_lshl_add_u64 v[224:225], s[66:67], 0, v[134:135]
	global_load_lds_dwordx4 v[222:223], off
	v_lshl_add_u64 v[222:223], vcc, 0, v[136:137]
	s_add_i32 m0, s95, 0x2000
	s_nop 0
	global_load_lds_dwordx4 v[222:223], off
	v_lshl_add_u64 v[222:223], s[66:67], 0, v[130:131]
	s_mov_b32 m0, s7
	s_nop 0
	global_load_lds_dwordx4 v[222:223], off
	s_mov_b32 m0, s52
	s_nop 0
	global_load_lds_dwordx4 v[224:225], off
	s_waitcnt vmcnt(8)
	s_waitcnt lgkmcnt(0)
	s_barrier
	s_setprio 1
	s_waitcnt lgkmcnt(0)
	v_mfma_f32_16x16x32_bf16 v[62:65], v[148:151], v[190:193], v[62:65]
	v_mfma_f32_16x16x32_bf16 v[58:61], v[162:165], v[190:193], v[58:61]
	v_mfma_f32_16x16x32_bf16 v[54:57], v[148:151], v[198:201], v[54:57]
	v_mfma_f32_16x16x32_bf16 v[50:53], v[162:165], v[198:201], v[50:53]
	v_mfma_f32_16x16x32_bf16 v[38:41], v[148:151], v[206:209], v[38:41]
	v_mfma_f32_16x16x32_bf16 v[34:37], v[162:165], v[206:209], v[34:37]
	v_mfma_f32_16x16x32_bf16 v[22:25], v[148:151], v[214:217], v[22:25]
	v_mfma_f32_16x16x32_bf16 v[18:21], v[162:165], v[214:217], v[18:21]
	v_mfma_f32_16x16x32_bf16 v[62:65], v[158:161], v[194:197], v[62:65]
	v_mfma_f32_16x16x32_bf16 v[58:61], v[170:173], v[194:197], v[58:61]
	v_mfma_f32_16x16x32_bf16 v[54:57], v[158:161], v[202:205], v[54:57]
	v_mfma_f32_16x16x32_bf16 v[50:53], v[170:173], v[202:205], v[50:53]
	v_mfma_f32_16x16x32_bf16 v[38:41], v[158:161], v[210:213], v[38:41]
	v_mfma_f32_16x16x32_bf16 v[34:37], v[170:173], v[210:213], v[34:37]
	v_mfma_f32_16x16x32_bf16 v[22:25], v[158:161], v[218:221], v[22:25]
	v_mfma_f32_16x16x32_bf16 v[18:21], v[170:173], v[218:221], v[18:21]
	s_setprio 0
	s_setprio 1
	v_mfma_f32_16x16x32_bf16 v[46:49], v[174:177], v[190:193], v[46:49]
	v_mfma_f32_16x16x32_bf16 v[42:45], v[182:185], v[190:193], v[42:45]
	v_mfma_f32_16x16x32_bf16 v[30:33], v[174:177], v[198:201], v[30:33]
	v_mfma_f32_16x16x32_bf16 v[26:29], v[182:185], v[198:201], v[26:29]
	v_mfma_f32_16x16x32_bf16 v[14:17], v[174:177], v[206:209], v[14:17]
	v_mfma_f32_16x16x32_bf16 v[10:13], v[182:185], v[206:209], v[10:13]
	v_mfma_f32_16x16x32_bf16 v[6:9], v[174:177], v[214:217], v[6:9]
	v_mfma_f32_16x16x32_bf16 v[2:5], v[182:185], v[214:217], v[2:5]
	v_mfma_f32_16x16x32_bf16 v[46:49], v[178:181], v[194:197], v[46:49]
	v_mfma_f32_16x16x32_bf16 v[42:45], v[186:189], v[194:197], v[42:45]
	v_mfma_f32_16x16x32_bf16 v[30:33], v[178:181], v[202:205], v[30:33]
	v_mfma_f32_16x16x32_bf16 v[26:29], v[186:189], v[202:205], v[26:29]
	v_mfma_f32_16x16x32_bf16 v[14:17], v[178:181], v[210:213], v[14:17]
	v_mfma_f32_16x16x32_bf16 v[10:13], v[186:189], v[210:213], v[10:13]
	v_mfma_f32_16x16x32_bf16 v[6:9], v[178:181], v[218:221], v[6:9]
	v_mfma_f32_16x16x32_bf16 v[2:5], v[186:189], v[218:221], v[2:5]
	s_setprio 0
	s_barrier
	s_add_i32 s95, 0, 0x18000
	v_add_u32_e32 v138, s95, v1
	s_add_i32 s97, 0, 0x1c000
	ds_read_b128 v[148:151], v138
	ds_read_b128 v[158:161], v138 offset:1024
	ds_read_b128 v[162:165], v138 offset:2048
	ds_read_b128 v[170:173], v138 offset:3072
	v_add_u32_e32 v138, s97, v1
	ds_read_b128 v[174:177], v138
	ds_read_b128 v[178:181], v138 offset:1024
	ds_read_b128 v[182:185], v138 offset:2048
	ds_read_b128 v[186:189], v138 offset:3072
	s_add_u32 s66, s66, 0x100000
	s_addc_u32 s67, s67, 0
	s_mov_b32 m0, s53
	v_lshl_add_u64 v[226:227], s[66:67], 0, v[130:131]
	ds_read_b128 v[190:193], v156 offset:32768
	ds_read_b128 v[194:197], v156 offset:33792
	ds_read_b128 v[198:201], v156 offset:34816
	ds_read_b128 v[202:205], v156 offset:35840
	ds_read_b128 v[206:209], v156 offset:36864
	ds_read_b128 v[210:213], v156 offset:37888
	ds_read_b128 v[214:217], v156 offset:38912
	ds_read_b128 v[218:221], v156 offset:39936
	global_load_lds_dwordx4 v[226:227], off
	v_lshl_add_u64 v[226:227], s[66:67], 0, v[134:135]
	s_mov_b32 m0, s54
	s_nop 0
	global_load_lds_dwordx4 v[226:227], off
	s_waitcnt vmcnt(8)
	s_waitcnt lgkmcnt(0)
	s_barrier
	s_setprio 1
	s_waitcnt lgkmcnt(0)
	v_mfma_f32_16x16x32_bf16 v[126:129], v[148:151], v[190:193], v[126:129]
	v_mfma_f32_16x16x32_bf16 v[122:125], v[162:165], v[190:193], v[122:125]
	v_mfma_f32_16x16x32_bf16 v[118:121], v[148:151], v[198:201], v[118:121]
	v_mfma_f32_16x16x32_bf16 v[114:117], v[162:165], v[198:201], v[114:117]
	v_mfma_f32_16x16x32_bf16 v[102:105], v[148:151], v[206:209], v[102:105]
	v_mfma_f32_16x16x32_bf16 v[98:101], v[162:165], v[206:209], v[98:101]
	v_mfma_f32_16x16x32_bf16 v[86:89], v[148:151], v[214:217], v[86:89]
	v_mfma_f32_16x16x32_bf16 v[82:85], v[162:165], v[214:217], v[82:85]
	v_mfma_f32_16x16x32_bf16 v[126:129], v[158:161], v[194:197], v[126:129]
	v_mfma_f32_16x16x32_bf16 v[122:125], v[170:173], v[194:197], v[122:125]
	v_mfma_f32_16x16x32_bf16 v[118:121], v[158:161], v[202:205], v[118:121]
	v_mfma_f32_16x16x32_bf16 v[114:117], v[170:173], v[202:205], v[114:117]
	v_mfma_f32_16x16x32_bf16 v[102:105], v[158:161], v[210:213], v[102:105]
	v_mfma_f32_16x16x32_bf16 v[98:101], v[170:173], v[210:213], v[98:101]
	v_mfma_f32_16x16x32_bf16 v[86:89], v[158:161], v[218:221], v[86:89]
	v_mfma_f32_16x16x32_bf16 v[82:85], v[170:173], v[218:221], v[82:85]
	s_setprio 0
	s_setprio 1
	v_mfma_f32_16x16x32_bf16 v[110:113], v[174:177], v[190:193], v[110:113]
	v_mfma_f32_16x16x32_bf16 v[106:109], v[182:185], v[190:193], v[106:109]
	v_mfma_f32_16x16x32_bf16 v[94:97], v[174:177], v[198:201], v[94:97]
	v_mfma_f32_16x16x32_bf16 v[90:93], v[182:185], v[198:201], v[90:93]
	v_mfma_f32_16x16x32_bf16 v[78:81], v[174:177], v[206:209], v[78:81]
	v_mfma_f32_16x16x32_bf16 v[74:77], v[182:185], v[206:209], v[74:77]
	v_mfma_f32_16x16x32_bf16 v[70:73], v[174:177], v[214:217], v[70:73]
	v_mfma_f32_16x16x32_bf16 v[66:69], v[182:185], v[214:217], v[66:69]
	v_mfma_f32_16x16x32_bf16 v[110:113], v[178:181], v[194:197], v[110:113]
	v_mfma_f32_16x16x32_bf16 v[106:109], v[186:189], v[194:197], v[106:109]
	v_mfma_f32_16x16x32_bf16 v[94:97], v[178:181], v[202:205], v[94:97]
	v_mfma_f32_16x16x32_bf16 v[90:93], v[186:189], v[202:205], v[90:93]
	v_mfma_f32_16x16x32_bf16 v[78:81], v[178:181], v[210:213], v[78:81]
	v_mfma_f32_16x16x32_bf16 v[74:77], v[186:189], v[210:213], v[74:77]
	v_mfma_f32_16x16x32_bf16 v[70:73], v[178:181], v[218:221], v[70:73]
	v_mfma_f32_16x16x32_bf16 v[66:69], v[186:189], v[218:221], v[66:69]
	s_setprio 0
	s_barrier
	s_add_i32 s66, s95, s6
	v_lshl_add_u64 v[152:153], v[152:153], 0, s[24:25]
	s_mov_b32 m0, s66
	ds_read_b128 v[190:193], v156 offset:49152
	ds_read_b128 v[194:197], v156 offset:50176
	ds_read_b128 v[198:201], v156 offset:51200
	ds_read_b128 v[202:205], v156 offset:52224
	ds_read_b128 v[206:209], v156 offset:53248
	ds_read_b128 v[210:213], v156 offset:54272
	ds_read_b128 v[214:217], v156 offset:55296
	ds_read_b128 v[218:221], v156 offset:56320
	global_load_lds_dwordx4 v[152:153], off
	s_add_i32 m0, s66, 0x2000
	s_add_u32 s64, s64, 0x100080
	v_lshl_add_u64 v[152:153], v[166:167], 0, s[24:25]
	s_addc_u32 s65, s65, 0
	s_add_i32 s66, s97, s6
	global_load_lds_dwordx4 v[152:153], off
	v_lshl_add_u64 v[152:153], s[64:65], 0, v[132:133]
	s_mov_b32 m0, s66
	s_nop 0
	global_load_lds_dwordx4 v[152:153], off
	v_lshl_add_u64 v[152:153], s[64:65], 0, v[136:137]
	s_add_i32 m0, s66, 0x2000
	s_nop 0
	global_load_lds_dwordx4 v[152:153], off
	v_lshl_add_u64 v[152:153], v[222:223], 0, s[24:25]
	s_mov_b32 m0, s63
	s_nop 0
	global_load_lds_dwordx4 v[152:153], off
	v_lshl_add_u64 v[152:153], v[224:225], 0, s[24:25]
	s_mov_b32 m0, s68
	s_nop 0
	global_load_lds_dwordx4 v[152:153], off
	s_waitcnt vmcnt(8)
	s_waitcnt lgkmcnt(0)
	s_barrier
	s_setprio 1
	s_waitcnt lgkmcnt(0)
	v_mfma_f32_16x16x32_bf16 v[62:65], v[148:151], v[190:193], v[62:65]
	v_mfma_f32_16x16x32_bf16 v[58:61], v[162:165], v[190:193], v[58:61]
	v_mfma_f32_16x16x32_bf16 v[54:57], v[148:151], v[198:201], v[54:57]
	v_mfma_f32_16x16x32_bf16 v[50:53], v[162:165], v[198:201], v[50:53]
	v_mfma_f32_16x16x32_bf16 v[38:41], v[148:151], v[206:209], v[38:41]
	v_mfma_f32_16x16x32_bf16 v[34:37], v[162:165], v[206:209], v[34:37]
	v_mfma_f32_16x16x32_bf16 v[22:25], v[148:151], v[214:217], v[22:25]
	v_mfma_f32_16x16x32_bf16 v[18:21], v[162:165], v[214:217], v[18:21]
	v_mfma_f32_16x16x32_bf16 v[62:65], v[158:161], v[194:197], v[62:65]
	v_mfma_f32_16x16x32_bf16 v[58:61], v[170:173], v[194:197], v[58:61]
	v_mfma_f32_16x16x32_bf16 v[54:57], v[158:161], v[202:205], v[54:57]
	v_mfma_f32_16x16x32_bf16 v[50:53], v[170:173], v[202:205], v[50:53]
	v_mfma_f32_16x16x32_bf16 v[38:41], v[158:161], v[210:213], v[38:41]
	v_mfma_f32_16x16x32_bf16 v[34:37], v[170:173], v[210:213], v[34:37]
	v_mfma_f32_16x16x32_bf16 v[22:25], v[158:161], v[218:221], v[22:25]
	v_mfma_f32_16x16x32_bf16 v[18:21], v[170:173], v[218:221], v[18:21]
	s_setprio 0
	s_setprio 1
	v_mfma_f32_16x16x32_bf16 v[46:49], v[174:177], v[190:193], v[46:49]
	v_mfma_f32_16x16x32_bf16 v[42:45], v[182:185], v[190:193], v[42:45]
	v_mfma_f32_16x16x32_bf16 v[30:33], v[174:177], v[198:201], v[30:33]
	v_mfma_f32_16x16x32_bf16 v[26:29], v[182:185], v[198:201], v[26:29]
	v_mfma_f32_16x16x32_bf16 v[14:17], v[174:177], v[206:209], v[14:17]
	v_mfma_f32_16x16x32_bf16 v[10:13], v[182:185], v[206:209], v[10:13]
	v_mfma_f32_16x16x32_bf16 v[6:9], v[174:177], v[214:217], v[6:9]
	v_mfma_f32_16x16x32_bf16 v[2:5], v[182:185], v[214:217], v[2:5]
	v_mfma_f32_16x16x32_bf16 v[46:49], v[178:181], v[194:197], v[46:49]
	v_mfma_f32_16x16x32_bf16 v[42:45], v[186:189], v[194:197], v[42:45]
	v_mfma_f32_16x16x32_bf16 v[30:33], v[178:181], v[202:205], v[30:33]
	v_mfma_f32_16x16x32_bf16 v[26:29], v[186:189], v[202:205], v[26:29]
	v_mfma_f32_16x16x32_bf16 v[14:17], v[178:181], v[210:213], v[14:17]
	v_mfma_f32_16x16x32_bf16 v[10:13], v[186:189], v[210:213], v[10:13]
	v_mfma_f32_16x16x32_bf16 v[6:9], v[178:181], v[218:221], v[6:9]
	v_mfma_f32_16x16x32_bf16 v[2:5], v[186:189], v[218:221], v[2:5]
	s_setprio 0
	s_add_i32 s93, s93, 2
	s_add_u32 s56, s56, 0x100
	s_addc_u32 s57, s57, 0
	s_add_u32 s82, s82, 0x100
	s_addc_u32 s83, s83, 0
	s_cmp_gt_u32 s93, 61
	s_barrier
	s_cbranch_scc0 .LBB0_549
	s_and_b64 vcc, exec, s[26:27]
	s_cbranch_vccz .LBB0_552
	s_barrier

.LBB0_736:
	ds_read_b128 v[118:121], v164
	ds_read_b128 v[122:125], v164 offset:1024
	ds_read_b128 v[138:141], v164 offset:2048
	ds_read_b128 v[142:145], v164 offset:3072
	ds_read_b128 v[160:163], v165
	ds_read_b128 v[170:173], v165 offset:1024
	ds_read_b128 v[174:177], v165 offset:2048
	ds_read_b128 v[178:181], v165 offset:3072
	s_add_i32 s58, s22, 2
	s_add_u32 s59, s20, 0x80
	s_addc_u32 s23, s21, 0
	s_cmp_eq_u32 s47, s22
	s_cselect_b32 s22, s16, s59
	s_cselect_b32 s23, s17, s23
	s_cselect_b32 s61, s19, s57
	s_cselect_b32 s60, s18, s56
	v_lshl_add_u64 v[214:215], s[20:21], 0, v[156:157]
	s_add_i32 m0, s29, 0xc000
	ds_read_b128 v[182:185], v166
	ds_read_b128 v[186:189], v166 offset:1024
	ds_read_b128 v[190:193], v166 offset:2048
	ds_read_b128 v[194:197], v166 offset:3072
	ds_read_b128 v[198:201], v166 offset:4096
	ds_read_b128 v[202:205], v166 offset:5120
	ds_read_b128 v[206:209], v166 offset:6144
	ds_read_b128 v[210:213], v166 offset:7168
	global_load_lds_dwordx4 v[214:215], off
	v_lshl_add_u64 v[214:215], s[20:21], 0, v[158:159]
	s_add_i32 m0, s29, 0xe000
	s_nop 0
	global_load_lds_dwordx4 v[214:215], off
	s_waitcnt vmcnt(8)
	s_waitcnt lgkmcnt(0)
	s_barrier
	s_setprio 1
	s_waitcnt lgkmcnt(0)
	v_mfma_f32_16x16x32_bf16 v[134:137], v[118:121], v[182:185], v[134:137]
	v_mfma_f32_16x16x32_bf16 v[130:133], v[138:141], v[182:185], v[130:133]
	v_mfma_f32_16x16x32_bf16 v[110:113], v[118:121], v[190:193], v[110:113]
	v_mfma_f32_16x16x32_bf16 v[106:109], v[138:141], v[190:193], v[106:109]
	v_mfma_f32_16x16x32_bf16 v[94:97], v[118:121], v[198:201], v[94:97]
	v_mfma_f32_16x16x32_bf16 v[90:93], v[138:141], v[198:201], v[90:93]
	v_mfma_f32_16x16x32_bf16 v[78:81], v[118:121], v[206:209], v[78:81]
	v_mfma_f32_16x16x32_bf16 v[74:77], v[138:141], v[206:209], v[74:77]
	v_mfma_f32_16x16x32_bf16 v[134:137], v[122:125], v[186:189], v[134:137]
	v_mfma_f32_16x16x32_bf16 v[130:133], v[142:145], v[186:189], v[130:133]
	v_mfma_f32_16x16x32_bf16 v[110:113], v[122:125], v[194:197], v[110:113]
	v_mfma_f32_16x16x32_bf16 v[106:109], v[142:145], v[194:197], v[106:109]
	v_mfma_f32_16x16x32_bf16 v[94:97], v[122:125], v[202:205], v[94:97]
	v_mfma_f32_16x16x32_bf16 v[90:93], v[142:145], v[202:205], v[90:93]
	v_mfma_f32_16x16x32_bf16 v[78:81], v[122:125], v[210:213], v[78:81]
	v_mfma_f32_16x16x32_bf16 v[74:77], v[142:145], v[210:213], v[74:77]
	s_setprio 0
	s_setprio 1
	v_mfma_f32_16x16x32_bf16 v[126:129], v[160:163], v[182:185], v[126:129]
	v_mfma_f32_16x16x32_bf16 v[114:117], v[174:177], v[182:185], v[114:117]
	v_mfma_f32_16x16x32_bf16 v[102:105], v[160:163], v[190:193], v[102:105]
	v_mfma_f32_16x16x32_bf16 v[98:101], v[174:177], v[190:193], v[98:101]
	v_mfma_f32_16x16x32_bf16 v[86:89], v[160:163], v[198:201], v[86:89]
	v_mfma_f32_16x16x32_bf16 v[82:85], v[174:177], v[198:201], v[82:85]
	v_mfma_f32_16x16x32_bf16 v[70:73], v[160:163], v[206:209], v[70:73]
	v_mfma_f32_16x16x32_bf16 v[66:69], v[174:177], v[206:209], v[66:69]
	v_mfma_f32_16x16x32_bf16 v[126:129], v[170:173], v[186:189], v[126:129]
	v_mfma_f32_16x16x32_bf16 v[114:117], v[178:181], v[186:189], v[114:117]
	v_mfma_f32_16x16x32_bf16 v[102:105], v[170:173], v[194:197], v[102:105]
	v_mfma_f32_16x16x32_bf16 v[98:101], v[178:181], v[194:197], v[98:101]
	v_mfma_f32_16x16x32_bf16 v[86:89], v[170:173], v[202:205], v[86:89]
	v_mfma_f32_16x16x32_bf16 v[82:85], v[178:181], v[202:205], v[82:85]
	v_mfma_f32_16x16x32_bf16 v[70:73], v[170:173], v[210:213], v[70:73]
	v_mfma_f32_16x16x32_bf16 v[66:69], v[178:181], v[210:213], v[66:69]
	s_setprio 0
	s_barrier
	s_add_i32 s59, s48, s28
	v_lshl_add_u64 v[214:215], s[60:61], 0, v[150:151]
	s_mov_b32 m0, s59
	ds_read_b128 v[182:185], v166 offset:16384
	ds_read_b128 v[186:189], v166 offset:17408
	ds_read_b128 v[190:193], v166 offset:18432
	ds_read_b128 v[194:197], v166 offset:19456
	ds_read_b128 v[198:201], v166 offset:20480
	ds_read_b128 v[202:205], v166 offset:21504
	ds_read_b128 v[206:209], v166 offset:22528
	ds_read_b128 v[210:213], v166 offset:23552
	global_load_lds_dwordx4 v[214:215], off
	s_add_i32 m0, s59, 0x2000
	v_lshl_add_u64 v[216:217], s[60:61], 0, v[146:147]
	s_add_u32 s60, s60, s6
	s_addc_u32 s61, s61, s7
	s_add_i32 s59, s49, s28
	global_load_lds_dwordx4 v[216:217], off
	v_lshl_add_u64 v[218:219], s[60:61], 0, v[150:151]
	s_mov_b32 m0, s59
	v_lshl_add_u64 v[220:221], s[60:61], 0, v[146:147]
	global_load_lds_dwordx4 v[218:219], off
	s_add_i32 m0, s59, 0x2000
	v_lshl_add_u64 v[222:223], s[22:23], 0, v[152:153]
	global_load_lds_dwordx4 v[220:221], off
	s_mov_b32 m0, s29
	v_lshl_add_u64 v[224:225], s[22:23], 0, v[148:149]
	global_load_lds_dwordx4 v[222:223], off
	s_mov_b32 m0, s30
	s_nop 0
	global_load_lds_dwordx4 v[224:225], off
	s_waitcnt vmcnt(8)
	s_waitcnt lgkmcnt(0)
	s_barrier
	s_setprio 1
	s_waitcnt lgkmcnt(0)
	v_mfma_f32_16x16x32_bf16 v[62:65], v[118:121], v[182:185], v[62:65]
	v_mfma_f32_16x16x32_bf16 v[58:61], v[138:141], v[182:185], v[58:61]
	v_mfma_f32_16x16x32_bf16 v[46:49], v[118:121], v[190:193], v[46:49]
	v_mfma_f32_16x16x32_bf16 v[42:45], v[138:141], v[190:193], v[42:45]
	v_mfma_f32_16x16x32_bf16 v[30:33], v[118:121], v[198:201], v[30:33]
	v_mfma_f32_16x16x32_bf16 v[26:29], v[138:141], v[198:201], v[26:29]
	v_mfma_f32_16x16x32_bf16 v[14:17], v[118:121], v[206:209], v[14:17]
	v_mfma_f32_16x16x32_bf16 v[10:13], v[138:141], v[206:209], v[10:13]
	v_mfma_f32_16x16x32_bf16 v[62:65], v[122:125], v[186:189], v[62:65]
	v_mfma_f32_16x16x32_bf16 v[58:61], v[142:145], v[186:189], v[58:61]
	v_mfma_f32_16x16x32_bf16 v[46:49], v[122:125], v[194:197], v[46:49]
	v_mfma_f32_16x16x32_bf16 v[42:45], v[142:145], v[194:197], v[42:45]
	v_mfma_f32_16x16x32_bf16 v[30:33], v[122:125], v[202:205], v[30:33]
	v_mfma_f32_16x16x32_bf16 v[26:29], v[142:145], v[202:205], v[26:29]
	v_mfma_f32_16x16x32_bf16 v[14:17], v[122:125], v[210:213], v[14:17]
	v_mfma_f32_16x16x32_bf16 v[10:13], v[142:145], v[210:213], v[10:13]
	s_setprio 0
	s_setprio 1
	v_mfma_f32_16x16x32_bf16 v[54:57], v[160:163], v[182:185], v[54:57]
	v_mfma_f32_16x16x32_bf16 v[50:53], v[174:177], v[182:185], v[50:53]
	v_mfma_f32_16x16x32_bf16 v[38:41], v[160:163], v[190:193], v[38:41]
	v_mfma_f32_16x16x32_bf16 v[34:37], v[174:177], v[190:193], v[34:37]
	v_mfma_f32_16x16x32_bf16 v[22:25], v[160:163], v[198:201], v[22:25]
	v_mfma_f32_16x16x32_bf16 v[18:21], v[174:177], v[198:201], v[18:21]
	v_mfma_f32_16x16x32_bf16 v[6:9], v[160:163], v[206:209], v[6:9]
	v_mfma_f32_16x16x32_bf16 v[2:5], v[174:177], v[206:209], v[2:5]
	v_mfma_f32_16x16x32_bf16 v[54:57], v[170:173], v[186:189], v[54:57]
	v_mfma_f32_16x16x32_bf16 v[50:53], v[178:181], v[186:189], v[50:53]
	v_mfma_f32_16x16x32_bf16 v[38:41], v[170:173], v[194:197], v[38:41]
	v_mfma_f32_16x16x32_bf16 v[34:37], v[178:181], v[194:197], v[34:37]
	v_mfma_f32_16x16x32_bf16 v[22:25], v[170:173], v[202:205], v[22:25]
	v_mfma_f32_16x16x32_bf16 v[18:21], v[178:181], v[202:205], v[18:21]
	v_mfma_f32_16x16x32_bf16 v[6:9], v[170:173], v[210:213], v[6:9]
	v_mfma_f32_16x16x32_bf16 v[2:5], v[178:181], v[210:213], v[2:5]
	s_setprio 0
	s_barrier
	s_add_i32 s59, 0, 0x18000
	s_add_i32 s60, 0, 0x1c000
	v_add_u32_e32 v142, s59, v1
	v_add_u32_e32 v154, s60, v1
	ds_read_b128 v[118:121], v142
	ds_read_b128 v[122:125], v142 offset:1024
	ds_read_b128 v[138:141], v142 offset:2048
	ds_read_b128 v[142:145], v142 offset:3072
	ds_read_b128 v[160:163], v154
	ds_read_b128 v[170:173], v154 offset:1024
	ds_read_b128 v[174:177], v154 offset:2048
	ds_read_b128 v[178:181], v154 offset:3072
	s_add_u32 s22, s22, s6
	s_addc_u32 s23, s23, s7
	s_mov_b32 m0, s31
	v_lshl_add_u64 v[226:227], s[22:23], 0, v[152:153]
	ds_read_b128 v[182:185], v166 offset:32768
	ds_read_b128 v[186:189], v166 offset:33792
	ds_read_b128 v[190:193], v166 offset:34816
	ds_read_b128 v[194:197], v166 offset:35840
	ds_read_b128 v[198:201], v166 offset:36864
	ds_read_b128 v[202:205], v166 offset:37888
	ds_read_b128 v[206:209], v166 offset:38912
	ds_read_b128 v[210:213], v166 offset:39936
	global_load_lds_dwordx4 v[226:227], off
	v_lshl_add_u64 v[226:227], s[22:23], 0, v[148:149]
	s_mov_b32 m0, s34
	s_nop 0
	global_load_lds_dwordx4 v[226:227], off
	s_waitcnt vmcnt(8)
	s_waitcnt lgkmcnt(0)
	s_barrier
	s_setprio 1
	s_waitcnt lgkmcnt(0)
	v_mfma_f32_16x16x32_bf16 v[134:137], v[118:121], v[182:185], v[134:137]
	v_mfma_f32_16x16x32_bf16 v[130:133], v[138:141], v[182:185], v[130:133]
	v_mfma_f32_16x16x32_bf16 v[110:113], v[118:121], v[190:193], v[110:113]
	v_mfma_f32_16x16x32_bf16 v[106:109], v[138:141], v[190:193], v[106:109]
	v_mfma_f32_16x16x32_bf16 v[94:97], v[118:121], v[198:201], v[94:97]
	v_mfma_f32_16x16x32_bf16 v[90:93], v[138:141], v[198:201], v[90:93]
	v_mfma_f32_16x16x32_bf16 v[78:81], v[118:121], v[206:209], v[78:81]
	v_mfma_f32_16x16x32_bf16 v[74:77], v[138:141], v[206:209], v[74:77]
	v_mfma_f32_16x16x32_bf16 v[134:137], v[122:125], v[186:189], v[134:137]
	v_mfma_f32_16x16x32_bf16 v[130:133], v[142:145], v[186:189], v[130:133]
	v_mfma_f32_16x16x32_bf16 v[110:113], v[122:125], v[194:197], v[110:113]
	v_mfma_f32_16x16x32_bf16 v[106:109], v[142:145], v[194:197], v[106:109]
	v_mfma_f32_16x16x32_bf16 v[94:97], v[122:125], v[202:205], v[94:97]
	v_mfma_f32_16x16x32_bf16 v[90:93], v[142:145], v[202:205], v[90:93]
	v_mfma_f32_16x16x32_bf16 v[78:81], v[122:125], v[210:213], v[78:81]
	v_mfma_f32_16x16x32_bf16 v[74:77], v[142:145], v[210:213], v[74:77]
	s_setprio 0
	s_setprio 1
	v_mfma_f32_16x16x32_bf16 v[126:129], v[160:163], v[182:185], v[126:129]
	v_mfma_f32_16x16x32_bf16 v[114:117], v[174:177], v[182:185], v[114:117]
	v_mfma_f32_16x16x32_bf16 v[102:105], v[160:163], v[190:193], v[102:105]
	v_mfma_f32_16x16x32_bf16 v[98:101], v[174:177], v[190:193], v[98:101]
	v_mfma_f32_16x16x32_bf16 v[86:89], v[160:163], v[198:201], v[86:89]
	v_mfma_f32_16x16x32_bf16 v[82:85], v[174:177], v[198:201], v[82:85]
	v_mfma_f32_16x16x32_bf16 v[70:73], v[160:163], v[206:209], v[70:73]
	v_mfma_f32_16x16x32_bf16 v[66:69], v[174:177], v[206:209], v[66:69]
	v_mfma_f32_16x16x32_bf16 v[126:129], v[170:173], v[186:189], v[126:129]
	v_mfma_f32_16x16x32_bf16 v[114:117], v[178:181], v[186:189], v[114:117]
	v_mfma_f32_16x16x32_bf16 v[102:105], v[170:173], v[194:197], v[102:105]
	v_mfma_f32_16x16x32_bf16 v[98:101], v[178:181], v[194:197], v[98:101]
	v_mfma_f32_16x16x32_bf16 v[86:89], v[170:173], v[202:205], v[86:89]
	v_mfma_f32_16x16x32_bf16 v[82:85], v[178:181], v[202:205], v[82:85]
	v_mfma_f32_16x16x32_bf16 v[70:73], v[170:173], v[210:213], v[70:73]
	v_mfma_f32_16x16x32_bf16 v[66:69], v[178:181], v[210:213], v[66:69]
	s_setprio 0
	s_barrier
	s_add_i32 s22, s59, s28
	v_lshl_add_u64 v[214:215], v[214:215], 0, s[12:13]
	s_mov_b32 m0, s22
	ds_read_b128 v[182:185], v166 offset:49152
	ds_read_b128 v[186:189], v166 offset:50176
	ds_read_b128 v[190:193], v166 offset:51200
	ds_read_b128 v[194:197], v166 offset:52224
	ds_read_b128 v[198:201], v166 offset:53248
	ds_read_b128 v[202:205], v166 offset:54272
	ds_read_b128 v[206:209], v166 offset:55296
	ds_read_b128 v[210:213], v166 offset:56320
	global_load_lds_dwordx4 v[214:215], off
	v_lshl_add_u64 v[214:215], v[216:217], 0, s[12:13]
	s_add_i32 m0, s22, 0x2000
	s_add_i32 s22, s60, s28
	global_load_lds_dwordx4 v[214:215], off
	v_lshl_add_u64 v[214:215], v[218:219], 0, s[12:13]
	s_mov_b32 m0, s22
	s_nop 0
	global_load_lds_dwordx4 v[214:215], off
	v_lshl_add_u64 v[214:215], v[220:221], 0, s[12:13]
	s_add_i32 m0, s22, 0x2000
	s_nop 0
	global_load_lds_dwordx4 v[214:215], off
	v_lshl_add_u64 v[214:215], v[222:223], 0, s[12:13]
	s_mov_b32 m0, s45
	s_nop 0
	global_load_lds_dwordx4 v[214:215], off
	v_lshl_add_u64 v[214:215], v[224:225], 0, s[12:13]
	s_mov_b32 m0, s46
	s_nop 0
	global_load_lds_dwordx4 v[214:215], off
	s_waitcnt vmcnt(8)
	s_waitcnt lgkmcnt(0)
	s_barrier
	s_setprio 1
	s_waitcnt lgkmcnt(0)
	v_mfma_f32_16x16x32_bf16 v[62:65], v[118:121], v[182:185], v[62:65]
	v_mfma_f32_16x16x32_bf16 v[58:61], v[138:141], v[182:185], v[58:61]
	v_mfma_f32_16x16x32_bf16 v[46:49], v[118:121], v[190:193], v[46:49]
	v_mfma_f32_16x16x32_bf16 v[42:45], v[138:141], v[190:193], v[42:45]
	v_mfma_f32_16x16x32_bf16 v[30:33], v[118:121], v[198:201], v[30:33]
	v_mfma_f32_16x16x32_bf16 v[26:29], v[138:141], v[198:201], v[26:29]
	v_mfma_f32_16x16x32_bf16 v[14:17], v[118:121], v[206:209], v[14:17]
	v_mfma_f32_16x16x32_bf16 v[10:13], v[138:141], v[206:209], v[10:13]
	v_mfma_f32_16x16x32_bf16 v[62:65], v[122:125], v[186:189], v[62:65]
	v_mfma_f32_16x16x32_bf16 v[58:61], v[142:145], v[186:189], v[58:61]
	v_mfma_f32_16x16x32_bf16 v[46:49], v[122:125], v[194:197], v[46:49]
	v_mfma_f32_16x16x32_bf16 v[42:45], v[142:145], v[194:197], v[42:45]
	v_mfma_f32_16x16x32_bf16 v[30:33], v[122:125], v[202:205], v[30:33]
	v_mfma_f32_16x16x32_bf16 v[26:29], v[142:145], v[202:205], v[26:29]
	v_mfma_f32_16x16x32_bf16 v[14:17], v[122:125], v[210:213], v[14:17]
	v_mfma_f32_16x16x32_bf16 v[10:13], v[142:145], v[210:213], v[10:13]
	s_setprio 0
	s_setprio 1
	v_mfma_f32_16x16x32_bf16 v[54:57], v[160:163], v[182:185], v[54:57]
	v_mfma_f32_16x16x32_bf16 v[50:53], v[174:177], v[182:185], v[50:53]
	v_mfma_f32_16x16x32_bf16 v[38:41], v[160:163], v[190:193], v[38:41]
	v_mfma_f32_16x16x32_bf16 v[34:37], v[174:177], v[190:193], v[34:37]
	v_mfma_f32_16x16x32_bf16 v[22:25], v[160:163], v[198:201], v[22:25]
	v_mfma_f32_16x16x32_bf16 v[18:21], v[174:177], v[198:201], v[18:21]
	v_mfma_f32_16x16x32_bf16 v[6:9], v[160:163], v[206:209], v[6:9]
	v_mfma_f32_16x16x32_bf16 v[2:5], v[174:177], v[206:209], v[2:5]
	v_mfma_f32_16x16x32_bf16 v[54:57], v[170:173], v[186:189], v[54:57]
	v_mfma_f32_16x16x32_bf16 v[50:53], v[178:181], v[186:189], v[50:53]
	v_mfma_f32_16x16x32_bf16 v[38:41], v[170:173], v[194:197], v[38:41]
	v_mfma_f32_16x16x32_bf16 v[34:37], v[178:181], v[194:197], v[34:37]
	v_mfma_f32_16x16x32_bf16 v[22:25], v[170:173], v[202:205], v[22:25]
	v_mfma_f32_16x16x32_bf16 v[18:21], v[178:181], v[202:205], v[18:21]
	v_mfma_f32_16x16x32_bf16 v[6:9], v[170:173], v[210:213], v[6:9]
	v_mfma_f32_16x16x32_bf16 v[2:5], v[178:181], v[210:213], v[2:5]
	s_setprio 0
	s_add_u32 s20, s20, 0x100
	s_addc_u32 s21, s21, 0
	s_add_u32 s56, s56, 0x100
	s_addc_u32 s57, s57, 0
	s_cmp_ge_i32 s58, s42
	s_mov_b32 s22, s58
	s_barrier
	s_cbranch_scc0 .LBB0_736

.LBB0_757:
	ds_read_b128 v[152:155], v148
	ds_read_b128 v[156:159], v148 offset:1024
	ds_read_b128 v[160:163], v148 offset:2048
	ds_read_b128 v[164:167], v148 offset:3072
	ds_read_b128 v[170:173], v149
	ds_read_b128 v[174:177], v149 offset:1024
	ds_read_b128 v[178:181], v149 offset:2048
	ds_read_b128 v[182:185], v149 offset:3072
	s_add_i32 s60, s26, 2
	s_add_u32 s61, s24, 0x80
	s_addc_u32 s27, s25, 0
	s_cmp_eq_u32 s51, s26
	s_cselect_b32 s26, s2, s61
	s_cselect_b32 s27, s3, s27
	s_cselect_b32 s63, s23, s59
	s_cselect_b32 s62, s22, s58
	v_lshl_add_u64 v[218:219], s[24:25], 0, v[140:141]
	s_add_i32 m0, s38, 0xc000
	ds_read_b128 v[186:189], v150
	ds_read_b128 v[190:193], v150 offset:1024
	ds_read_b128 v[194:197], v150 offset:2048
	ds_read_b128 v[198:201], v150 offset:3072
	ds_read_b128 v[202:205], v150 offset:4096
	ds_read_b128 v[206:209], v150 offset:5120
	ds_read_b128 v[210:213], v150 offset:6144
	ds_read_b128 v[214:217], v150 offset:7168
	global_load_lds_dwordx4 v[218:219], off
	v_lshl_add_u64 v[218:219], s[24:25], 0, v[142:143]
	s_add_i32 m0, s38, 0xe000
	s_nop 0
	global_load_lds_dwordx4 v[218:219], off
	s_waitcnt vmcnt(8)
	s_waitcnt lgkmcnt(0)
	s_barrier
	s_setprio 1
	s_waitcnt lgkmcnt(0)
	v_mfma_f32_16x16x32_bf16 v[122:125], v[152:155], v[186:189], v[122:125]
	v_mfma_f32_16x16x32_bf16 v[126:129], v[160:163], v[186:189], v[126:129]
	v_mfma_f32_16x16x32_bf16 v[110:113], v[152:155], v[194:197], v[110:113]
	v_mfma_f32_16x16x32_bf16 v[106:109], v[160:163], v[194:197], v[106:109]
	v_mfma_f32_16x16x32_bf16 v[94:97], v[152:155], v[202:205], v[94:97]
	v_mfma_f32_16x16x32_bf16 v[90:93], v[160:163], v[202:205], v[90:93]
	v_mfma_f32_16x16x32_bf16 v[78:81], v[152:155], v[210:213], v[78:81]
	v_mfma_f32_16x16x32_bf16 v[74:77], v[160:163], v[210:213], v[74:77]
	v_mfma_f32_16x16x32_bf16 v[122:125], v[156:159], v[190:193], v[122:125]
	v_mfma_f32_16x16x32_bf16 v[126:129], v[164:167], v[190:193], v[126:129]
	v_mfma_f32_16x16x32_bf16 v[110:113], v[156:159], v[198:201], v[110:113]
	v_mfma_f32_16x16x32_bf16 v[106:109], v[164:167], v[198:201], v[106:109]
	v_mfma_f32_16x16x32_bf16 v[94:97], v[156:159], v[206:209], v[94:97]
	v_mfma_f32_16x16x32_bf16 v[90:93], v[164:167], v[206:209], v[90:93]
	v_mfma_f32_16x16x32_bf16 v[78:81], v[156:159], v[214:217], v[78:81]
	v_mfma_f32_16x16x32_bf16 v[74:77], v[164:167], v[214:217], v[74:77]
	s_setprio 0
	s_setprio 1
	v_mfma_f32_16x16x32_bf16 v[118:121], v[170:173], v[186:189], v[118:121]
	v_mfma_f32_16x16x32_bf16 v[114:117], v[178:181], v[186:189], v[114:117]
	v_mfma_f32_16x16x32_bf16 v[102:105], v[170:173], v[194:197], v[102:105]
	v_mfma_f32_16x16x32_bf16 v[98:101], v[178:181], v[194:197], v[98:101]
	v_mfma_f32_16x16x32_bf16 v[86:89], v[170:173], v[202:205], v[86:89]
	v_mfma_f32_16x16x32_bf16 v[82:85], v[178:181], v[202:205], v[82:85]
	v_mfma_f32_16x16x32_bf16 v[70:73], v[170:173], v[210:213], v[70:73]
	v_mfma_f32_16x16x32_bf16 v[66:69], v[178:181], v[210:213], v[66:69]
	v_mfma_f32_16x16x32_bf16 v[118:121], v[174:177], v[190:193], v[118:121]
	v_mfma_f32_16x16x32_bf16 v[114:117], v[182:185], v[190:193], v[114:117]
	v_mfma_f32_16x16x32_bf16 v[102:105], v[174:177], v[198:201], v[102:105]
	v_mfma_f32_16x16x32_bf16 v[98:101], v[182:185], v[198:201], v[98:101]
	v_mfma_f32_16x16x32_bf16 v[86:89], v[174:177], v[206:209], v[86:89]
	v_mfma_f32_16x16x32_bf16 v[82:85], v[182:185], v[206:209], v[82:85]
	v_mfma_f32_16x16x32_bf16 v[70:73], v[174:177], v[214:217], v[70:73]
	v_mfma_f32_16x16x32_bf16 v[66:69], v[182:185], v[214:217], v[66:69]
	s_setprio 0
	s_barrier
	s_add_i32 s61, s53, s36
	v_lshl_add_u64 v[218:219], s[62:63], 0, v[134:135]
	s_mov_b32 m0, s61
	ds_read_b128 v[186:189], v150 offset:16384
	ds_read_b128 v[190:193], v150 offset:17408
	ds_read_b128 v[194:197], v150 offset:18432
	ds_read_b128 v[198:201], v150 offset:19456
	ds_read_b128 v[202:205], v150 offset:20480
	ds_read_b128 v[206:209], v150 offset:21504
	ds_read_b128 v[210:213], v150 offset:22528
	ds_read_b128 v[214:217], v150 offset:23552
	global_load_lds_dwordx4 v[218:219], off
	s_add_i32 m0, s61, 0x2000
	v_lshl_add_u64 v[220:221], s[62:63], 0, v[130:131]
	s_add_u32 s62, s62, s6
	s_addc_u32 s63, s63, s7
	s_add_i32 s61, s54, s36
	global_load_lds_dwordx4 v[220:221], off
	v_lshl_add_u64 v[222:223], s[62:63], 0, v[134:135]
	s_mov_b32 m0, s61
	v_lshl_add_u64 v[224:225], s[62:63], 0, v[130:131]
	global_load_lds_dwordx4 v[222:223], off
	s_add_i32 m0, s61, 0x2000
	v_lshl_add_u64 v[226:227], s[26:27], 0, v[136:137]
	global_load_lds_dwordx4 v[224:225], off
	s_mov_b32 m0, s38
	v_lshl_add_u64 v[228:229], s[26:27], 0, v[132:133]
	global_load_lds_dwordx4 v[226:227], off
	s_mov_b32 m0, s39
	s_nop 0
	global_load_lds_dwordx4 v[228:229], off
	s_waitcnt vmcnt(8)
	s_waitcnt lgkmcnt(0)
	s_barrier
	s_setprio 1
	s_waitcnt lgkmcnt(0)
	v_mfma_f32_16x16x32_bf16 v[62:65], v[152:155], v[186:189], v[62:65]
	v_mfma_f32_16x16x32_bf16 v[58:61], v[160:163], v[186:189], v[58:61]
	v_mfma_f32_16x16x32_bf16 v[46:49], v[152:155], v[194:197], v[46:49]
	v_mfma_f32_16x16x32_bf16 v[42:45], v[160:163], v[194:197], v[42:45]
	v_mfma_f32_16x16x32_bf16 v[30:33], v[152:155], v[202:205], v[30:33]
	v_mfma_f32_16x16x32_bf16 v[26:29], v[160:163], v[202:205], v[26:29]
	v_mfma_f32_16x16x32_bf16 v[14:17], v[152:155], v[210:213], v[14:17]
	v_mfma_f32_16x16x32_bf16 v[10:13], v[160:163], v[210:213], v[10:13]
	v_mfma_f32_16x16x32_bf16 v[62:65], v[156:159], v[190:193], v[62:65]
	v_mfma_f32_16x16x32_bf16 v[58:61], v[164:167], v[190:193], v[58:61]
	v_mfma_f32_16x16x32_bf16 v[46:49], v[156:159], v[198:201], v[46:49]
	v_mfma_f32_16x16x32_bf16 v[42:45], v[164:167], v[198:201], v[42:45]
	v_mfma_f32_16x16x32_bf16 v[30:33], v[156:159], v[206:209], v[30:33]
	v_mfma_f32_16x16x32_bf16 v[26:29], v[164:167], v[206:209], v[26:29]
	v_mfma_f32_16x16x32_bf16 v[14:17], v[156:159], v[214:217], v[14:17]
	v_mfma_f32_16x16x32_bf16 v[10:13], v[164:167], v[214:217], v[10:13]
	s_setprio 0
	s_setprio 1
	v_mfma_f32_16x16x32_bf16 v[54:57], v[170:173], v[186:189], v[54:57]
	v_mfma_f32_16x16x32_bf16 v[50:53], v[178:181], v[186:189], v[50:53]
	v_mfma_f32_16x16x32_bf16 v[38:41], v[170:173], v[194:197], v[38:41]
	v_mfma_f32_16x16x32_bf16 v[34:37], v[178:181], v[194:197], v[34:37]
	v_mfma_f32_16x16x32_bf16 v[22:25], v[170:173], v[202:205], v[22:25]
	v_mfma_f32_16x16x32_bf16 v[18:21], v[178:181], v[202:205], v[18:21]
	v_mfma_f32_16x16x32_bf16 v[6:9], v[170:173], v[210:213], v[6:9]
	v_mfma_f32_16x16x32_bf16 v[2:5], v[178:181], v[210:213], v[2:5]
	v_mfma_f32_16x16x32_bf16 v[54:57], v[174:177], v[190:193], v[54:57]
	v_mfma_f32_16x16x32_bf16 v[50:53], v[182:185], v[190:193], v[50:53]
	v_mfma_f32_16x16x32_bf16 v[38:41], v[174:177], v[198:201], v[38:41]
	v_mfma_f32_16x16x32_bf16 v[34:37], v[182:185], v[198:201], v[34:37]
	v_mfma_f32_16x16x32_bf16 v[22:25], v[174:177], v[206:209], v[22:25]
	v_mfma_f32_16x16x32_bf16 v[18:21], v[182:185], v[206:209], v[18:21]
	v_mfma_f32_16x16x32_bf16 v[6:9], v[174:177], v[214:217], v[6:9]
	v_mfma_f32_16x16x32_bf16 v[2:5], v[182:185], v[214:217], v[2:5]
	s_setprio 0
	s_barrier
	s_add_i32 s61, 0, 0x18000
	v_add_u32_e32 v138, s61, v1
	s_add_i32 s62, 0, 0x1c000
	ds_read_b128 v[152:155], v138
	ds_read_b128 v[156:159], v138 offset:1024
	ds_read_b128 v[160:163], v138 offset:2048
	ds_read_b128 v[164:167], v138 offset:3072
	v_add_u32_e32 v138, s62, v1
	ds_read_b128 v[170:173], v138
	ds_read_b128 v[174:177], v138 offset:1024
	ds_read_b128 v[178:181], v138 offset:2048
	ds_read_b128 v[182:185], v138 offset:3072
	s_add_u32 s26, s26, s6
	s_addc_u32 s27, s27, s7
	s_mov_b32 m0, s42
	v_lshl_add_u64 v[230:231], s[26:27], 0, v[136:137]
	ds_read_b128 v[186:189], v150 offset:32768
	ds_read_b128 v[190:193], v150 offset:33792
	ds_read_b128 v[194:197], v150 offset:34816
	ds_read_b128 v[198:201], v150 offset:35840
	ds_read_b128 v[202:205], v150 offset:36864
	ds_read_b128 v[206:209], v150 offset:37888
	ds_read_b128 v[210:213], v150 offset:38912
	ds_read_b128 v[214:217], v150 offset:39936
	global_load_lds_dwordx4 v[230:231], off
	v_lshl_add_u64 v[230:231], s[26:27], 0, v[132:133]
	s_mov_b32 m0, s43
	s_nop 0
	global_load_lds_dwordx4 v[230:231], off
	s_waitcnt vmcnt(8)
	s_waitcnt lgkmcnt(0)
	s_barrier
	s_setprio 1
	s_waitcnt lgkmcnt(0)
	v_mfma_f32_16x16x32_bf16 v[122:125], v[152:155], v[186:189], v[122:125]
	v_mfma_f32_16x16x32_bf16 v[126:129], v[160:163], v[186:189], v[126:129]
	v_mfma_f32_16x16x32_bf16 v[110:113], v[152:155], v[194:197], v[110:113]
	v_mfma_f32_16x16x32_bf16 v[106:109], v[160:163], v[194:197], v[106:109]
	v_mfma_f32_16x16x32_bf16 v[94:97], v[152:155], v[202:205], v[94:97]
	v_mfma_f32_16x16x32_bf16 v[90:93], v[160:163], v[202:205], v[90:93]
	v_mfma_f32_16x16x32_bf16 v[78:81], v[152:155], v[210:213], v[78:81]
	v_mfma_f32_16x16x32_bf16 v[74:77], v[160:163], v[210:213], v[74:77]
	v_mfma_f32_16x16x32_bf16 v[122:125], v[156:159], v[190:193], v[122:125]
	v_mfma_f32_16x16x32_bf16 v[126:129], v[164:167], v[190:193], v[126:129]
	v_mfma_f32_16x16x32_bf16 v[110:113], v[156:159], v[198:201], v[110:113]
	v_mfma_f32_16x16x32_bf16 v[106:109], v[164:167], v[198:201], v[106:109]
	v_mfma_f32_16x16x32_bf16 v[94:97], v[156:159], v[206:209], v[94:97]
	v_mfma_f32_16x16x32_bf16 v[90:93], v[164:167], v[206:209], v[90:93]
	v_mfma_f32_16x16x32_bf16 v[78:81], v[156:159], v[214:217], v[78:81]
	v_mfma_f32_16x16x32_bf16 v[74:77], v[164:167], v[214:217], v[74:77]
	s_setprio 0
	s_setprio 1
	v_mfma_f32_16x16x32_bf16 v[118:121], v[170:173], v[186:189], v[118:121]
	v_mfma_f32_16x16x32_bf16 v[114:117], v[178:181], v[186:189], v[114:117]
	v_mfma_f32_16x16x32_bf16 v[102:105], v[170:173], v[194:197], v[102:105]
	v_mfma_f32_16x16x32_bf16 v[98:101], v[178:181], v[194:197], v[98:101]
	v_mfma_f32_16x16x32_bf16 v[86:89], v[170:173], v[202:205], v[86:89]
	v_mfma_f32_16x16x32_bf16 v[82:85], v[178:181], v[202:205], v[82:85]
	v_mfma_f32_16x16x32_bf16 v[70:73], v[170:173], v[210:213], v[70:73]
	v_mfma_f32_16x16x32_bf16 v[66:69], v[178:181], v[210:213], v[66:69]
	v_mfma_f32_16x16x32_bf16 v[118:121], v[174:177], v[190:193], v[118:121]
	v_mfma_f32_16x16x32_bf16 v[114:117], v[182:185], v[190:193], v[114:117]
	v_mfma_f32_16x16x32_bf16 v[102:105], v[174:177], v[198:201], v[102:105]
	v_mfma_f32_16x16x32_bf16 v[98:101], v[182:185], v[198:201], v[98:101]
	v_mfma_f32_16x16x32_bf16 v[86:89], v[174:177], v[206:209], v[86:89]
	v_mfma_f32_16x16x32_bf16 v[82:85], v[182:185], v[206:209], v[82:85]
	v_mfma_f32_16x16x32_bf16 v[70:73], v[174:177], v[214:217], v[70:73]
	v_mfma_f32_16x16x32_bf16 v[66:69], v[182:185], v[214:217], v[66:69]
	s_setprio 0
	s_barrier
	s_add_i32 s26, s61, s36
	v_lshl_add_u64 v[218:219], v[218:219], 0, s[14:15]
	s_mov_b32 m0, s26
	ds_read_b128 v[186:189], v150 offset:49152
	ds_read_b128 v[190:193], v150 offset:50176
	ds_read_b128 v[194:197], v150 offset:51200
	ds_read_b128 v[198:201], v150 offset:52224
	ds_read_b128 v[202:205], v150 offset:53248
	ds_read_b128 v[206:209], v150 offset:54272
	ds_read_b128 v[210:213], v150 offset:55296
	ds_read_b128 v[214:217], v150 offset:56320
	global_load_lds_dwordx4 v[218:219], off
	v_lshl_add_u64 v[218:219], v[220:221], 0, s[14:15]
	s_add_i32 m0, s26, 0x2000
	s_add_i32 s26, s62, s36
	global_load_lds_dwordx4 v[218:219], off
	v_lshl_add_u64 v[218:219], v[222:223], 0, s[14:15]
	s_mov_b32 m0, s26
	s_nop 0
	global_load_lds_dwordx4 v[218:219], off
	v_lshl_add_u64 v[218:219], v[224:225], 0, s[14:15]
	s_add_i32 m0, s26, 0x2000
	s_nop 0
	global_load_lds_dwordx4 v[218:219], off
	v_lshl_add_u64 v[218:219], v[226:227], 0, s[14:15]
	s_mov_b32 m0, s48
	s_nop 0
	global_load_lds_dwordx4 v[218:219], off
	v_lshl_add_u64 v[218:219], v[228:229], 0, s[14:15]
	s_mov_b32 m0, s49
	s_nop 0
	global_load_lds_dwordx4 v[218:219], off
	s_waitcnt vmcnt(8)
	s_waitcnt lgkmcnt(0)
	s_barrier
	s_setprio 1
	s_waitcnt lgkmcnt(0)
	v_mfma_f32_16x16x32_bf16 v[62:65], v[152:155], v[186:189], v[62:65]
	v_mfma_f32_16x16x32_bf16 v[58:61], v[160:163], v[186:189], v[58:61]
	v_mfma_f32_16x16x32_bf16 v[46:49], v[152:155], v[194:197], v[46:49]
	v_mfma_f32_16x16x32_bf16 v[42:45], v[160:163], v[194:197], v[42:45]
	v_mfma_f32_16x16x32_bf16 v[30:33], v[152:155], v[202:205], v[30:33]
	v_mfma_f32_16x16x32_bf16 v[26:29], v[160:163], v[202:205], v[26:29]
	v_mfma_f32_16x16x32_bf16 v[14:17], v[152:155], v[210:213], v[14:17]
	v_mfma_f32_16x16x32_bf16 v[10:13], v[160:163], v[210:213], v[10:13]
	v_mfma_f32_16x16x32_bf16 v[62:65], v[156:159], v[190:193], v[62:65]
	v_mfma_f32_16x16x32_bf16 v[58:61], v[164:167], v[190:193], v[58:61]
	v_mfma_f32_16x16x32_bf16 v[46:49], v[156:159], v[198:201], v[46:49]
	v_mfma_f32_16x16x32_bf16 v[42:45], v[164:167], v[198:201], v[42:45]
	v_mfma_f32_16x16x32_bf16 v[30:33], v[156:159], v[206:209], v[30:33]
	v_mfma_f32_16x16x32_bf16 v[26:29], v[164:167], v[206:209], v[26:29]
	v_mfma_f32_16x16x32_bf16 v[14:17], v[156:159], v[214:217], v[14:17]
	v_mfma_f32_16x16x32_bf16 v[10:13], v[164:167], v[214:217], v[10:13]
	s_setprio 0
	s_setprio 1
	v_mfma_f32_16x16x32_bf16 v[54:57], v[170:173], v[186:189], v[54:57]
	v_mfma_f32_16x16x32_bf16 v[50:53], v[178:181], v[186:189], v[50:53]
	v_mfma_f32_16x16x32_bf16 v[38:41], v[170:173], v[194:197], v[38:41]
	v_mfma_f32_16x16x32_bf16 v[34:37], v[178:181], v[194:197], v[34:37]
	v_mfma_f32_16x16x32_bf16 v[22:25], v[170:173], v[202:205], v[22:25]
	v_mfma_f32_16x16x32_bf16 v[18:21], v[178:181], v[202:205], v[18:21]
	v_mfma_f32_16x16x32_bf16 v[6:9], v[170:173], v[210:213], v[6:9]
	v_mfma_f32_16x16x32_bf16 v[2:5], v[178:181], v[210:213], v[2:5]
	v_mfma_f32_16x16x32_bf16 v[54:57], v[174:177], v[190:193], v[54:57]
	v_mfma_f32_16x16x32_bf16 v[50:53], v[182:185], v[190:193], v[50:53]
	v_mfma_f32_16x16x32_bf16 v[38:41], v[174:177], v[198:201], v[38:41]
	v_mfma_f32_16x16x32_bf16 v[34:37], v[182:185], v[198:201], v[34:37]
	v_mfma_f32_16x16x32_bf16 v[22:25], v[174:177], v[206:209], v[22:25]
	v_mfma_f32_16x16x32_bf16 v[18:21], v[182:185], v[206:209], v[18:21]
	v_mfma_f32_16x16x32_bf16 v[6:9], v[174:177], v[214:217], v[6:9]
	v_mfma_f32_16x16x32_bf16 v[2:5], v[182:185], v[214:217], v[2:5]
	s_setprio 0
	s_add_u32 s24, s24, 0x100
	s_addc_u32 s25, s25, 0
	s_add_u32 s58, s58, 0x100
	s_addc_u32 s59, s59, 0
	s_cmp_ge_i32 s60, s44
	s_mov_b32 s26, s60
	s_barrier
	s_cbranch_scc0 .LBB0_757

.LBB0_778:
	v_add_u32_e32 v138, s57, v1
	ds_read_b128 v[148:151], v138
	ds_read_b128 v[152:155], v138 offset:1024
	ds_read_b128 v[158:161], v138 offset:2048
	ds_read_b128 v[162:165], v138 offset:3072
	v_add_u32_e32 v138, s58, v1
	ds_read_b128 v[170:173], v138
	ds_read_b128 v[174:177], v138 offset:1024
	ds_read_b128 v[178:181], v138 offset:2048
	ds_read_b128 v[182:185], v138 offset:3072
	s_add_i32 s66, s28, 2
	s_add_u32 s67, s26, 0x80
	s_addc_u32 s29, s27, 0
	s_cmp_eq_u32 s55, s28
	s_cselect_b32 s28, s2, s67
	s_cselect_b32 s29, s3, s29
	s_cselect_b32 s69, s25, s65
	s_cselect_b32 s68, s24, s64
	v_lshl_add_u64 v[166:167], s[26:27], 0, v[140:141]
	s_add_i32 m0, s43, 0xc000
	ds_read_b128 v[186:189], v157
	ds_read_b128 v[190:193], v157 offset:1024
	ds_read_b128 v[194:197], v157 offset:2048
	ds_read_b128 v[198:201], v157 offset:3072
	ds_read_b128 v[202:205], v157 offset:4096
	ds_read_b128 v[206:209], v157 offset:5120
	ds_read_b128 v[210:213], v157 offset:6144
	ds_read_b128 v[214:217], v157 offset:7168
	global_load_lds_dwordx4 v[166:167], off
	v_lshl_add_u64 v[166:167], s[26:27], 0, v[142:143]
	s_add_i32 m0, s43, 0xe000
	s_nop 0
	global_load_lds_dwordx4 v[166:167], off
	s_waitcnt vmcnt(8)
	s_waitcnt lgkmcnt(0)
	s_barrier
	s_setprio 1
	s_waitcnt lgkmcnt(0)
	v_mfma_i32_16x16x64_i8 v[126:129], v[148:151], v[186:189], v[126:129]
	v_mfma_i32_16x16x64_i8 v[122:125], v[158:161], v[186:189], v[122:125]
	v_mfma_i32_16x16x64_i8 v[118:121], v[148:151], v[194:197], v[118:121]
	v_mfma_i32_16x16x64_i8 v[114:117], v[158:161], v[194:197], v[114:117]
	v_mfma_i32_16x16x64_i8 v[106:109], v[148:151], v[202:205], v[106:109]
	v_mfma_i32_16x16x64_i8 v[98:101], v[158:161], v[202:205], v[98:101]
	v_mfma_i32_16x16x64_i8 v[90:93], v[148:151], v[210:213], v[90:93]
	v_mfma_i32_16x16x64_i8 v[82:85], v[158:161], v[210:213], v[82:85]
	v_mfma_i32_16x16x64_i8 v[126:129], v[152:155], v[190:193], v[126:129]
	v_mfma_i32_16x16x64_i8 v[122:125], v[162:165], v[190:193], v[122:125]
	v_mfma_i32_16x16x64_i8 v[118:121], v[152:155], v[198:201], v[118:121]
	v_mfma_i32_16x16x64_i8 v[114:117], v[162:165], v[198:201], v[114:117]
	v_mfma_i32_16x16x64_i8 v[106:109], v[152:155], v[206:209], v[106:109]
	v_mfma_i32_16x16x64_i8 v[98:101], v[162:165], v[206:209], v[98:101]
	v_mfma_i32_16x16x64_i8 v[90:93], v[152:155], v[214:217], v[90:93]
	v_mfma_i32_16x16x64_i8 v[82:85], v[162:165], v[214:217], v[82:85]
	s_setprio 0
	s_setprio 1
	v_mfma_i32_16x16x64_i8 v[110:113], v[170:173], v[186:189], v[110:113]
	v_mfma_i32_16x16x64_i8 v[102:105], v[178:181], v[186:189], v[102:105]
	v_mfma_i32_16x16x64_i8 v[94:97], v[170:173], v[194:197], v[94:97]
	v_mfma_i32_16x16x64_i8 v[86:89], v[178:181], v[194:197], v[86:89]
	v_mfma_i32_16x16x64_i8 v[78:81], v[170:173], v[202:205], v[78:81]
	v_mfma_i32_16x16x64_i8 v[74:77], v[178:181], v[202:205], v[74:77]
	v_mfma_i32_16x16x64_i8 v[70:73], v[170:173], v[210:213], v[70:73]
	v_mfma_i32_16x16x64_i8 v[66:69], v[178:181], v[210:213], v[66:69]
	v_mfma_i32_16x16x64_i8 v[110:113], v[174:177], v[190:193], v[110:113]
	v_mfma_i32_16x16x64_i8 v[102:105], v[182:185], v[190:193], v[102:105]
	v_mfma_i32_16x16x64_i8 v[94:97], v[174:177], v[198:201], v[94:97]
	v_mfma_i32_16x16x64_i8 v[86:89], v[182:185], v[198:201], v[86:89]
	v_mfma_i32_16x16x64_i8 v[78:81], v[174:177], v[206:209], v[78:81]
	v_mfma_i32_16x16x64_i8 v[74:77], v[182:185], v[206:209], v[74:77]
	v_mfma_i32_16x16x64_i8 v[70:73], v[174:177], v[214:217], v[70:73]
	v_mfma_i32_16x16x64_i8 v[66:69], v[182:185], v[214:217], v[66:69]
	s_setprio 0
	s_barrier
	s_add_i32 s67, s57, s38
	v_lshl_add_u64 v[166:167], s[68:69], 0, v[134:135]
	s_mov_b32 m0, s67
	ds_read_b128 v[186:189], v157 offset:16384
	ds_read_b128 v[190:193], v157 offset:17408
	ds_read_b128 v[194:197], v157 offset:18432
	ds_read_b128 v[198:201], v157 offset:19456
	ds_read_b128 v[202:205], v157 offset:20480
	ds_read_b128 v[206:209], v157 offset:21504
	ds_read_b128 v[210:213], v157 offset:22528
	ds_read_b128 v[214:217], v157 offset:23552
	global_load_lds_dwordx4 v[166:167], off
	s_add_i32 m0, s67, 0x2000
	v_lshl_add_u64 v[218:219], s[68:69], 0, v[130:131]
	s_add_u32 s68, s68, s6
	s_addc_u32 s69, s69, s7
	s_add_i32 s67, s58, s38
	global_load_lds_dwordx4 v[218:219], off
	v_lshl_add_u64 v[220:221], s[68:69], 0, v[134:135]
	s_mov_b32 m0, s67
	v_lshl_add_u64 v[222:223], s[68:69], 0, v[130:131]
	global_load_lds_dwordx4 v[220:221], off
	s_add_i32 m0, s67, 0x2000
	v_lshl_add_u64 v[224:225], s[28:29], 0, v[136:137]
	global_load_lds_dwordx4 v[222:223], off
	s_mov_b32 m0, s43
	v_lshl_add_u64 v[226:227], s[28:29], 0, v[132:133]
	global_load_lds_dwordx4 v[224:225], off
	s_mov_b32 m0, s44
	s_nop 0
	global_load_lds_dwordx4 v[226:227], off
	s_waitcnt vmcnt(8)
	s_waitcnt lgkmcnt(0)
	s_barrier
	s_setprio 1
	s_waitcnt lgkmcnt(0)
	v_mfma_i32_16x16x64_i8 v[62:65], v[148:151], v[186:189], v[62:65]
	v_mfma_i32_16x16x64_i8 v[58:61], v[158:161], v[186:189], v[58:61]
	v_mfma_i32_16x16x64_i8 v[54:57], v[148:151], v[194:197], v[54:57]
	v_mfma_i32_16x16x64_i8 v[50:53], v[158:161], v[194:197], v[50:53]
	v_mfma_i32_16x16x64_i8 v[42:45], v[148:151], v[202:205], v[42:45]
	v_mfma_i32_16x16x64_i8 v[34:37], v[158:161], v[202:205], v[34:37]
	v_mfma_i32_16x16x64_i8 v[26:29], v[148:151], v[210:213], v[26:29]
	v_mfma_i32_16x16x64_i8 v[18:21], v[158:161], v[210:213], v[18:21]
	v_mfma_i32_16x16x64_i8 v[62:65], v[152:155], v[190:193], v[62:65]
	v_mfma_i32_16x16x64_i8 v[58:61], v[162:165], v[190:193], v[58:61]
	v_mfma_i32_16x16x64_i8 v[54:57], v[152:155], v[198:201], v[54:57]
	v_mfma_i32_16x16x64_i8 v[50:53], v[162:165], v[198:201], v[50:53]
	v_mfma_i32_16x16x64_i8 v[42:45], v[152:155], v[206:209], v[42:45]
	v_mfma_i32_16x16x64_i8 v[34:37], v[162:165], v[206:209], v[34:37]
	v_mfma_i32_16x16x64_i8 v[26:29], v[152:155], v[214:217], v[26:29]
	v_mfma_i32_16x16x64_i8 v[18:21], v[162:165], v[214:217], v[18:21]
	s_setprio 0
	s_setprio 1
	v_mfma_i32_16x16x64_i8 v[46:49], v[170:173], v[186:189], v[46:49]
	v_mfma_i32_16x16x64_i8 v[38:41], v[178:181], v[186:189], v[38:41]
	v_mfma_i32_16x16x64_i8 v[30:33], v[170:173], v[194:197], v[30:33]
	v_mfma_i32_16x16x64_i8 v[22:25], v[178:181], v[194:197], v[22:25]
	v_mfma_i32_16x16x64_i8 v[14:17], v[170:173], v[202:205], v[14:17]
	v_mfma_i32_16x16x64_i8 v[10:13], v[178:181], v[202:205], v[10:13]
	v_mfma_i32_16x16x64_i8 v[6:9], v[170:173], v[210:213], v[6:9]
	v_mfma_i32_16x16x64_i8 v[2:5], v[178:181], v[210:213], v[2:5]
	v_mfma_i32_16x16x64_i8 v[46:49], v[174:177], v[190:193], v[46:49]
	v_mfma_i32_16x16x64_i8 v[38:41], v[182:185], v[190:193], v[38:41]
	v_mfma_i32_16x16x64_i8 v[30:33], v[174:177], v[198:201], v[30:33]
	v_mfma_i32_16x16x64_i8 v[22:25], v[182:185], v[198:201], v[22:25]
	v_mfma_i32_16x16x64_i8 v[14:17], v[174:177], v[206:209], v[14:17]
	v_mfma_i32_16x16x64_i8 v[10:13], v[182:185], v[206:209], v[10:13]
	v_mfma_i32_16x16x64_i8 v[6:9], v[174:177], v[214:217], v[6:9]
	v_mfma_i32_16x16x64_i8 v[2:5], v[182:185], v[214:217], v[2:5]
	s_setprio 0
	s_barrier
	s_add_i32 s67, 0, 0x18000
	v_add_u32_e32 v138, s67, v1
	s_add_i32 s68, 0, 0x1c000
	ds_read_b128 v[148:151], v138
	ds_read_b128 v[152:155], v138 offset:1024
	ds_read_b128 v[158:161], v138 offset:2048
	ds_read_b128 v[162:165], v138 offset:3072
	v_add_u32_e32 v138, s68, v1
	ds_read_b128 v[170:173], v138
	ds_read_b128 v[174:177], v138 offset:1024
	ds_read_b128 v[178:181], v138 offset:2048
	ds_read_b128 v[182:185], v138 offset:3072
	s_add_u32 s28, s28, s6
	s_addc_u32 s29, s29, s7
	s_mov_b32 m0, s45
	v_lshl_add_u64 v[228:229], s[28:29], 0, v[136:137]
	ds_read_b128 v[186:189], v157 offset:32768
	ds_read_b128 v[190:193], v157 offset:33792
	ds_read_b128 v[194:197], v157 offset:34816
	ds_read_b128 v[198:201], v157 offset:35840
	ds_read_b128 v[202:205], v157 offset:36864
	ds_read_b128 v[206:209], v157 offset:37888
	ds_read_b128 v[210:213], v157 offset:38912
	ds_read_b128 v[214:217], v157 offset:39936
	global_load_lds_dwordx4 v[228:229], off
	v_lshl_add_u64 v[228:229], s[28:29], 0, v[132:133]
	s_mov_b32 m0, s46
	s_nop 0
	global_load_lds_dwordx4 v[228:229], off
	s_waitcnt vmcnt(8)
	s_waitcnt lgkmcnt(0)
	s_barrier
	s_setprio 1
	s_waitcnt lgkmcnt(0)
	v_mfma_i32_16x16x64_i8 v[126:129], v[148:151], v[186:189], v[126:129]
	v_mfma_i32_16x16x64_i8 v[122:125], v[158:161], v[186:189], v[122:125]
	v_mfma_i32_16x16x64_i8 v[118:121], v[148:151], v[194:197], v[118:121]
	v_mfma_i32_16x16x64_i8 v[114:117], v[158:161], v[194:197], v[114:117]
	v_mfma_i32_16x16x64_i8 v[106:109], v[148:151], v[202:205], v[106:109]
	v_mfma_i32_16x16x64_i8 v[98:101], v[158:161], v[202:205], v[98:101]
	v_mfma_i32_16x16x64_i8 v[90:93], v[148:151], v[210:213], v[90:93]
	v_mfma_i32_16x16x64_i8 v[82:85], v[158:161], v[210:213], v[82:85]
	v_mfma_i32_16x16x64_i8 v[126:129], v[152:155], v[190:193], v[126:129]
	v_mfma_i32_16x16x64_i8 v[122:125], v[162:165], v[190:193], v[122:125]
	v_mfma_i32_16x16x64_i8 v[118:121], v[152:155], v[198:201], v[118:121]
	v_mfma_i32_16x16x64_i8 v[114:117], v[162:165], v[198:201], v[114:117]
	v_mfma_i32_16x16x64_i8 v[106:109], v[152:155], v[206:209], v[106:109]
	v_mfma_i32_16x16x64_i8 v[98:101], v[162:165], v[206:209], v[98:101]
	v_mfma_i32_16x16x64_i8 v[90:93], v[152:155], v[214:217], v[90:93]
	v_mfma_i32_16x16x64_i8 v[82:85], v[162:165], v[214:217], v[82:85]
	s_setprio 0
	s_setprio 1
	v_mfma_i32_16x16x64_i8 v[110:113], v[170:173], v[186:189], v[110:113]
	v_mfma_i32_16x16x64_i8 v[102:105], v[178:181], v[186:189], v[102:105]
	v_mfma_i32_16x16x64_i8 v[94:97], v[170:173], v[194:197], v[94:97]
	v_mfma_i32_16x16x64_i8 v[86:89], v[178:181], v[194:197], v[86:89]
	v_mfma_i32_16x16x64_i8 v[78:81], v[170:173], v[202:205], v[78:81]
	v_mfma_i32_16x16x64_i8 v[74:77], v[178:181], v[202:205], v[74:77]
	v_mfma_i32_16x16x64_i8 v[70:73], v[170:173], v[210:213], v[70:73]
	v_mfma_i32_16x16x64_i8 v[66:69], v[178:181], v[210:213], v[66:69]
	v_mfma_i32_16x16x64_i8 v[110:113], v[174:177], v[190:193], v[110:113]
	v_mfma_i32_16x16x64_i8 v[102:105], v[182:185], v[190:193], v[102:105]
	v_mfma_i32_16x16x64_i8 v[94:97], v[174:177], v[198:201], v[94:97]
	v_mfma_i32_16x16x64_i8 v[86:89], v[182:185], v[198:201], v[86:89]
	v_mfma_i32_16x16x64_i8 v[78:81], v[174:177], v[206:209], v[78:81]
	v_mfma_i32_16x16x64_i8 v[74:77], v[182:185], v[206:209], v[74:77]
	v_mfma_i32_16x16x64_i8 v[70:73], v[174:177], v[214:217], v[70:73]
	v_mfma_i32_16x16x64_i8 v[66:69], v[182:185], v[214:217], v[66:69]
	s_setprio 0
	s_barrier
	s_add_i32 s28, s67, s38
	v_lshl_add_u64 v[166:167], v[166:167], 0, s[16:17]
	s_mov_b32 m0, s28
	ds_read_b128 v[186:189], v157 offset:49152
	ds_read_b128 v[190:193], v157 offset:50176
	ds_read_b128 v[194:197], v157 offset:51200
	ds_read_b128 v[198:201], v157 offset:52224
	ds_read_b128 v[202:205], v157 offset:53248
	ds_read_b128 v[206:209], v157 offset:54272
	ds_read_b128 v[210:213], v157 offset:55296
	ds_read_b128 v[214:217], v157 offset:56320
	global_load_lds_dwordx4 v[166:167], off
	v_lshl_add_u64 v[166:167], v[218:219], 0, s[16:17]
	s_add_i32 m0, s28, 0x2000
	s_add_i32 s28, s68, s38
	global_load_lds_dwordx4 v[166:167], off
	v_lshl_add_u64 v[166:167], v[220:221], 0, s[16:17]
	s_mov_b32 m0, s28
	s_nop 0
	global_load_lds_dwordx4 v[166:167], off
	v_lshl_add_u64 v[166:167], v[222:223], 0, s[16:17]
	s_add_i32 m0, s28, 0x2000
	s_nop 0
	global_load_lds_dwordx4 v[166:167], off
	v_lshl_add_u64 v[166:167], v[224:225], 0, s[16:17]
	s_mov_b32 m0, s53
	s_nop 0
	global_load_lds_dwordx4 v[166:167], off
	v_lshl_add_u64 v[166:167], v[226:227], 0, s[16:17]
	s_mov_b32 m0, s54
	s_nop 0
	global_load_lds_dwordx4 v[166:167], off
	s_waitcnt vmcnt(8)
	s_waitcnt lgkmcnt(0)
	s_barrier
	s_setprio 1
	s_waitcnt lgkmcnt(0)
	v_mfma_i32_16x16x64_i8 v[62:65], v[148:151], v[186:189], v[62:65]
	v_mfma_i32_16x16x64_i8 v[58:61], v[158:161], v[186:189], v[58:61]
	v_mfma_i32_16x16x64_i8 v[54:57], v[148:151], v[194:197], v[54:57]
	v_mfma_i32_16x16x64_i8 v[50:53], v[158:161], v[194:197], v[50:53]
	v_mfma_i32_16x16x64_i8 v[42:45], v[148:151], v[202:205], v[42:45]
	v_mfma_i32_16x16x64_i8 v[34:37], v[158:161], v[202:205], v[34:37]
	v_mfma_i32_16x16x64_i8 v[26:29], v[148:151], v[210:213], v[26:29]
	v_mfma_i32_16x16x64_i8 v[18:21], v[158:161], v[210:213], v[18:21]
	v_mfma_i32_16x16x64_i8 v[62:65], v[152:155], v[190:193], v[62:65]
	v_mfma_i32_16x16x64_i8 v[58:61], v[162:165], v[190:193], v[58:61]
	v_mfma_i32_16x16x64_i8 v[54:57], v[152:155], v[198:201], v[54:57]
	v_mfma_i32_16x16x64_i8 v[50:53], v[162:165], v[198:201], v[50:53]
	v_mfma_i32_16x16x64_i8 v[42:45], v[152:155], v[206:209], v[42:45]
	v_mfma_i32_16x16x64_i8 v[34:37], v[162:165], v[206:209], v[34:37]
	v_mfma_i32_16x16x64_i8 v[26:29], v[152:155], v[214:217], v[26:29]
	v_mfma_i32_16x16x64_i8 v[18:21], v[162:165], v[214:217], v[18:21]
	s_setprio 0
	s_setprio 1
	v_mfma_i32_16x16x64_i8 v[46:49], v[170:173], v[186:189], v[46:49]
	v_mfma_i32_16x16x64_i8 v[38:41], v[178:181], v[186:189], v[38:41]
	v_mfma_i32_16x16x64_i8 v[30:33], v[170:173], v[194:197], v[30:33]
	v_mfma_i32_16x16x64_i8 v[22:25], v[178:181], v[194:197], v[22:25]
	v_mfma_i32_16x16x64_i8 v[14:17], v[170:173], v[202:205], v[14:17]
	v_mfma_i32_16x16x64_i8 v[10:13], v[178:181], v[202:205], v[10:13]
	v_mfma_i32_16x16x64_i8 v[6:9], v[170:173], v[210:213], v[6:9]
	v_mfma_i32_16x16x64_i8 v[2:5], v[178:181], v[210:213], v[2:5]
	v_mfma_i32_16x16x64_i8 v[46:49], v[174:177], v[190:193], v[46:49]
	v_mfma_i32_16x16x64_i8 v[38:41], v[182:185], v[190:193], v[38:41]
	v_mfma_i32_16x16x64_i8 v[30:33], v[174:177], v[198:201], v[30:33]
	v_mfma_i32_16x16x64_i8 v[22:25], v[182:185], v[198:201], v[22:25]
	v_mfma_i32_16x16x64_i8 v[14:17], v[174:177], v[206:209], v[14:17]
	v_mfma_i32_16x16x64_i8 v[10:13], v[182:185], v[206:209], v[10:13]
	v_mfma_i32_16x16x64_i8 v[6:9], v[174:177], v[214:217], v[6:9]
	v_mfma_i32_16x16x64_i8 v[2:5], v[182:185], v[214:217], v[2:5]
	s_setprio 0
	s_add_u32 s26, s26, 0x100
	s_addc_u32 s27, s27, 0
	s_add_u32 s64, s64, 0x100
	s_addc_u32 s65, s65, 0
	s_cmp_ge_i32 s66, s50
	s_mov_b32 s28, s66
	s_barrier
	s_cbranch_scc0 .LBB0_778
	v_cvt_f32_i32_e32 v162, v126
	v_cvt_f32_i32_e32 v163, v127
	v_cvt_f32_i32_e32 v160, v128
	v_cvt_f32_i32_e32 v161, v129
	v_cvt_f32_i32_e32 v164, v122
	v_cvt_f32_i32_e32 v165, v123
	v_cvt_f32_i32_e32 v166, v124
	v_cvt_f32_i32_e32 v167, v125
	v_cvt_f32_i32_e32 v148, v110
	v_cvt_f32_i32_e32 v149, v111
	v_cvt_f32_i32_e32 v150, v112
	v_cvt_f32_i32_e32 v151, v113
	v_cvt_f32_i32_e32 v126, v102
	v_cvt_f32_i32_e32 v127, v103
	v_cvt_f32_i32_e32 v128, v104
	v_cvt_f32_i32_e32 v129, v105
	v_cvt_f32_i32_e32 v122, v118
	v_cvt_f32_i32_e32 v123, v119
	v_cvt_f32_i32_e32 v124, v120
	v_cvt_f32_i32_e32 v125, v121
	v_cvt_f32_i32_e32 v118, v114
	v_cvt_f32_i32_e32 v119, v115
	v_cvt_f32_i32_e32 v120, v116
	v_cvt_f32_i32_e32 v121, v117
	v_cvt_f32_i32_e32 v112, v94
	v_cvt_f32_i32_e32 v113, v95
	v_cvt_f32_i32_e32 v116, v96
	v_cvt_f32_i32_e32 v117, v97
	v_cvt_f32_i32_e32 v110, v86
	v_cvt_f32_i32_e32 v111, v87
	v_cvt_f32_i32_e32 v114, v88
	v_cvt_f32_i32_e32 v115, v89
	v_cvt_f32_i32_e32 v96, v106
	v_cvt_f32_i32_e32 v97, v107
	v_cvt_f32_i32_e32 v102, v108
	v_cvt_f32_i32_e32 v103, v109
	v_cvt_f32_i32_e32 v94, v98
	v_cvt_f32_i32_e32 v95, v99
	v_cvt_f32_i32_e32 v98, v100
	v_cvt_f32_i32_e32 v99, v101
	v_cvt_f32_i32_e32 v104, v78
	v_cvt_f32_i32_e32 v105, v79
	v_cvt_f32_i32_e32 v108, v80
	v_cvt_f32_i32_e32 v109, v81
	v_cvt_f32_i32_e32 v100, v74
	v_cvt_f32_i32_e32 v101, v75
	v_cvt_f32_i32_e32 v106, v76
	v_cvt_f32_i32_e32 v107, v77
	v_cvt_f32_i32_e32 v76, v90
	v_cvt_f32_i32_e32 v77, v91
	v_cvt_f32_i32_e32 v80, v92
	v_cvt_f32_i32_e32 v81, v93
	v_cvt_f32_i32_e32 v74, v82
	v_cvt_f32_i32_e32 v75, v83
	v_cvt_f32_i32_e32 v78, v84
	v_cvt_f32_i32_e32 v79, v85
	v_cvt_f32_i32_e32 v82, v70
	v_cvt_f32_i32_e32 v83, v71
	v_cvt_f32_i32_e32 v88, v72
	v_cvt_f32_i32_e32 v89, v73
	v_cvt_f32_i32_e32 v70, v66
	v_cvt_f32_i32_e32 v71, v67
	v_cvt_f32_i32_e32 v86, v68
	v_cvt_f32_i32_e32 v87, v69
	v_cvt_f32_i32_e32 v66, v62
	v_cvt_f32_i32_e32 v67, v63
	v_cvt_f32_i32_e32 v68, v64
	v_cvt_f32_i32_e32 v69, v65
	v_cvt_f32_i32_e32 v62, v58
	v_cvt_f32_i32_e32 v63, v59
	v_cvt_f32_i32_e32 v64, v60
	v_cvt_f32_i32_e32 v65, v61
	v_cvt_f32_i32_e32 v84, v46
	v_cvt_f32_i32_e32 v85, v47
	v_cvt_f32_i32_e32 v92, v48
	v_cvt_f32_i32_e32 v93, v49
	v_cvt_f32_i32_e32 v72, v38
	v_cvt_f32_i32_e32 v73, v39
	v_cvt_f32_i32_e32 v90, v40
	v_cvt_f32_i32_e32 v91, v41
	v_cvt_f32_i32_e32 v48, v54
	v_cvt_f32_i32_e32 v49, v55
	v_cvt_f32_i32_e32 v54, v56
	v_cvt_f32_i32_e32 v55, v57
	v_cvt_f32_i32_e32 v46, v50
	v_cvt_f32_i32_e32 v47, v51
	v_cvt_f32_i32_e32 v50, v52
	v_cvt_f32_i32_e32 v51, v53
	v_cvt_f32_i32_e32 v56, v30
	v_cvt_f32_i32_e32 v57, v31
	v_cvt_f32_i32_e32 v60, v32
	v_cvt_f32_i32_e32 v61, v33
	v_cvt_f32_i32_e32 v52, v22
	v_cvt_f32_i32_e32 v53, v23
	v_cvt_f32_i32_e32 v58, v24
	v_cvt_f32_i32_e32 v59, v25
	v_cvt_f32_i32_e32 v24, v42
	v_cvt_f32_i32_e32 v25, v43
	v_cvt_f32_i32_e32 v32, v44
	v_cvt_f32_i32_e32 v33, v45
	v_cvt_f32_i32_e32 v22, v34
	v_cvt_f32_i32_e32 v23, v35
	v_cvt_f32_i32_e32 v30, v36
	v_cvt_f32_i32_e32 v31, v37
	v_cvt_f32_i32_e32 v36, v14
	v_cvt_f32_i32_e32 v37, v15
	v_cvt_f32_i32_e32 v40, v16
	v_cvt_f32_i32_e32 v41, v17
	v_cvt_f32_i32_e32 v34, v10
	v_cvt_f32_i32_e32 v35, v11
	v_cvt_f32_i32_e32 v38, v12
	v_cvt_f32_i32_e32 v39, v13
	v_cvt_f32_i32_e32 v12, v26
	v_cvt_f32_i32_e32 v13, v27
	v_cvt_f32_i32_e32 v16, v28
	v_cvt_f32_i32_e32 v17, v29
	v_cvt_f32_i32_e32 v10, v18
	v_cvt_f32_i32_e32 v11, v19
	v_cvt_f32_i32_e32 v14, v20
	v_cvt_f32_i32_e32 v15, v21
	v_cvt_f32_i32_e32 v6, v6
	v_cvt_f32_i32_e32 v7, v7
	v_cvt_f32_i32_e32 v8, v8
	v_cvt_f32_i32_e32 v9, v9
	v_cvt_f32_i32_e32 v2, v2
	v_cvt_f32_i32_e32 v3, v3
	v_cvt_f32_i32_e32 v4, v4
	v_cvt_f32_i32_e32 v5, v5

.LBB0_800:
	v_add_u32_e32 v138, s55, v1
	ds_read_b128 v[148:151], v138
	ds_read_b128 v[152:155], v138 offset:1024
	ds_read_b128 v[158:161], v138 offset:2048
	ds_read_b128 v[162:165], v138 offset:3072
	v_add_u32_e32 v138, s56, v1
	ds_read_b128 v[170:173], v138
	ds_read_b128 v[174:177], v138 offset:1024
	ds_read_b128 v[178:181], v138 offset:2048
	ds_read_b128 v[182:185], v138 offset:3072
	s_add_i32 s63, s28, 2
	s_add_u32 s64, s26, 0x80
	s_addc_u32 s29, s27, 0
	s_cmp_eq_u32 s53, s28
	s_cselect_b32 s28, s2, s64
	s_cselect_b32 s29, s3, s29
	s_cselect_b32 s65, s25, s62
	s_cselect_b32 s64, s24, s61
	v_lshl_add_u64 v[166:167], s[26:27], 0, v[140:141]
	s_add_i32 m0, s39, 0xc000
	ds_read_b128 v[186:189], v157
	ds_read_b128 v[190:193], v157 offset:1024
	ds_read_b128 v[194:197], v157 offset:2048
	ds_read_b128 v[198:201], v157 offset:3072
	ds_read_b128 v[202:205], v157 offset:4096
	ds_read_b128 v[206:209], v157 offset:5120
	ds_read_b128 v[210:213], v157 offset:6144
	ds_read_b128 v[214:217], v157 offset:7168
	global_load_lds_dwordx4 v[166:167], off
	v_lshl_add_u64 v[166:167], s[26:27], 0, v[142:143]
	s_add_i32 m0, s39, 0xe000
	s_nop 0
	global_load_lds_dwordx4 v[166:167], off
	s_waitcnt vmcnt(8)
	s_waitcnt lgkmcnt(0)
	s_barrier
	s_setprio 1
	s_waitcnt lgkmcnt(0)
	v_mfma_i32_16x16x64_i8 v[126:129], v[148:151], v[186:189], v[126:129]
	v_mfma_i32_16x16x64_i8 v[122:125], v[158:161], v[186:189], v[122:125]
	v_mfma_i32_16x16x64_i8 v[118:121], v[148:151], v[194:197], v[118:121]
	v_mfma_i32_16x16x64_i8 v[114:117], v[158:161], v[194:197], v[114:117]
	v_mfma_i32_16x16x64_i8 v[106:109], v[148:151], v[202:205], v[106:109]
	v_mfma_i32_16x16x64_i8 v[98:101], v[158:161], v[202:205], v[98:101]
	v_mfma_i32_16x16x64_i8 v[90:93], v[148:151], v[210:213], v[90:93]
	v_mfma_i32_16x16x64_i8 v[82:85], v[158:161], v[210:213], v[82:85]
	v_mfma_i32_16x16x64_i8 v[126:129], v[152:155], v[190:193], v[126:129]
	v_mfma_i32_16x16x64_i8 v[122:125], v[162:165], v[190:193], v[122:125]
	v_mfma_i32_16x16x64_i8 v[118:121], v[152:155], v[198:201], v[118:121]
	v_mfma_i32_16x16x64_i8 v[114:117], v[162:165], v[198:201], v[114:117]
	v_mfma_i32_16x16x64_i8 v[106:109], v[152:155], v[206:209], v[106:109]
	v_mfma_i32_16x16x64_i8 v[98:101], v[162:165], v[206:209], v[98:101]
	v_mfma_i32_16x16x64_i8 v[90:93], v[152:155], v[214:217], v[90:93]
	v_mfma_i32_16x16x64_i8 v[82:85], v[162:165], v[214:217], v[82:85]
	s_setprio 0
	s_setprio 1
	v_mfma_i32_16x16x64_i8 v[110:113], v[170:173], v[186:189], v[110:113]
	v_mfma_i32_16x16x64_i8 v[102:105], v[178:181], v[186:189], v[102:105]
	v_mfma_i32_16x16x64_i8 v[94:97], v[170:173], v[194:197], v[94:97]
	v_mfma_i32_16x16x64_i8 v[86:89], v[178:181], v[194:197], v[86:89]
	v_mfma_i32_16x16x64_i8 v[78:81], v[170:173], v[202:205], v[78:81]
	v_mfma_i32_16x16x64_i8 v[74:77], v[178:181], v[202:205], v[74:77]
	v_mfma_i32_16x16x64_i8 v[70:73], v[170:173], v[210:213], v[70:73]
	v_mfma_i32_16x16x64_i8 v[66:69], v[178:181], v[210:213], v[66:69]
	v_mfma_i32_16x16x64_i8 v[110:113], v[174:177], v[190:193], v[110:113]
	v_mfma_i32_16x16x64_i8 v[102:105], v[182:185], v[190:193], v[102:105]
	v_mfma_i32_16x16x64_i8 v[94:97], v[174:177], v[198:201], v[94:97]
	v_mfma_i32_16x16x64_i8 v[86:89], v[182:185], v[198:201], v[86:89]
	v_mfma_i32_16x16x64_i8 v[78:81], v[174:177], v[206:209], v[78:81]
	v_mfma_i32_16x16x64_i8 v[74:77], v[182:185], v[206:209], v[74:77]
	v_mfma_i32_16x16x64_i8 v[70:73], v[174:177], v[214:217], v[70:73]
	v_mfma_i32_16x16x64_i8 v[66:69], v[182:185], v[214:217], v[66:69]
	s_setprio 0
	s_barrier
	s_add_i32 s66, s55, s36
	v_lshl_add_u64 v[166:167], s[64:65], 0, v[134:135]
	s_mov_b32 m0, s66
	ds_read_b128 v[186:189], v157 offset:16384
	ds_read_b128 v[190:193], v157 offset:17408
	ds_read_b128 v[194:197], v157 offset:18432
	ds_read_b128 v[198:201], v157 offset:19456
	ds_read_b128 v[202:205], v157 offset:20480
	ds_read_b128 v[206:209], v157 offset:21504
	ds_read_b128 v[210:213], v157 offset:22528
	ds_read_b128 v[214:217], v157 offset:23552
	global_load_lds_dwordx4 v[166:167], off
	s_add_i32 m0, s66, 0x2000
	v_lshl_add_u64 v[218:219], s[64:65], 0, v[130:131]
	s_add_u32 s64, s64, s6
	s_addc_u32 s65, s65, s7
	s_add_i32 s66, s56, s36
	global_load_lds_dwordx4 v[218:219], off
	v_lshl_add_u64 v[220:221], s[64:65], 0, v[134:135]
	s_mov_b32 m0, s66
	v_lshl_add_u64 v[222:223], s[64:65], 0, v[130:131]
	global_load_lds_dwordx4 v[220:221], off
	s_add_i32 m0, s66, 0x2000
	v_lshl_add_u64 v[224:225], s[28:29], 0, v[136:137]
	global_load_lds_dwordx4 v[222:223], off
	s_mov_b32 m0, s39
	v_lshl_add_u64 v[226:227], s[28:29], 0, v[132:133]
	global_load_lds_dwordx4 v[224:225], off
	s_mov_b32 m0, s42
	s_nop 0
	global_load_lds_dwordx4 v[226:227], off
	s_waitcnt vmcnt(8)
	s_waitcnt lgkmcnt(0)
	s_barrier
	s_setprio 1
	s_waitcnt lgkmcnt(0)
	v_mfma_i32_16x16x64_i8 v[62:65], v[148:151], v[186:189], v[62:65]
	v_mfma_i32_16x16x64_i8 v[58:61], v[158:161], v[186:189], v[58:61]
	v_mfma_i32_16x16x64_i8 v[54:57], v[148:151], v[194:197], v[54:57]
	v_mfma_i32_16x16x64_i8 v[50:53], v[158:161], v[194:197], v[50:53]
	v_mfma_i32_16x16x64_i8 v[42:45], v[148:151], v[202:205], v[42:45]
	v_mfma_i32_16x16x64_i8 v[34:37], v[158:161], v[202:205], v[34:37]
	v_mfma_i32_16x16x64_i8 v[26:29], v[148:151], v[210:213], v[26:29]
	v_mfma_i32_16x16x64_i8 v[18:21], v[158:161], v[210:213], v[18:21]
	v_mfma_i32_16x16x64_i8 v[62:65], v[152:155], v[190:193], v[62:65]
	v_mfma_i32_16x16x64_i8 v[58:61], v[162:165], v[190:193], v[58:61]
	v_mfma_i32_16x16x64_i8 v[54:57], v[152:155], v[198:201], v[54:57]
	v_mfma_i32_16x16x64_i8 v[50:53], v[162:165], v[198:201], v[50:53]
	v_mfma_i32_16x16x64_i8 v[42:45], v[152:155], v[206:209], v[42:45]
	v_mfma_i32_16x16x64_i8 v[34:37], v[162:165], v[206:209], v[34:37]
	v_mfma_i32_16x16x64_i8 v[26:29], v[152:155], v[214:217], v[26:29]
	v_mfma_i32_16x16x64_i8 v[18:21], v[162:165], v[214:217], v[18:21]
	s_setprio 0
	s_setprio 1
	v_mfma_i32_16x16x64_i8 v[46:49], v[170:173], v[186:189], v[46:49]
	v_mfma_i32_16x16x64_i8 v[38:41], v[178:181], v[186:189], v[38:41]
	v_mfma_i32_16x16x64_i8 v[30:33], v[170:173], v[194:197], v[30:33]
	v_mfma_i32_16x16x64_i8 v[22:25], v[178:181], v[194:197], v[22:25]
	v_mfma_i32_16x16x64_i8 v[14:17], v[170:173], v[202:205], v[14:17]
	v_mfma_i32_16x16x64_i8 v[10:13], v[178:181], v[202:205], v[10:13]
	v_mfma_i32_16x16x64_i8 v[6:9], v[170:173], v[210:213], v[6:9]
	v_mfma_i32_16x16x64_i8 v[2:5], v[178:181], v[210:213], v[2:5]
	v_mfma_i32_16x16x64_i8 v[46:49], v[174:177], v[190:193], v[46:49]
	v_mfma_i32_16x16x64_i8 v[38:41], v[182:185], v[190:193], v[38:41]
	v_mfma_i32_16x16x64_i8 v[30:33], v[174:177], v[198:201], v[30:33]
	v_mfma_i32_16x16x64_i8 v[22:25], v[182:185], v[198:201], v[22:25]
	v_mfma_i32_16x16x64_i8 v[14:17], v[174:177], v[206:209], v[14:17]
	v_mfma_i32_16x16x64_i8 v[10:13], v[182:185], v[206:209], v[10:13]
	v_mfma_i32_16x16x64_i8 v[6:9], v[174:177], v[214:217], v[6:9]
	v_mfma_i32_16x16x64_i8 v[2:5], v[182:185], v[214:217], v[2:5]
	s_setprio 0
	s_barrier
	s_add_i32 s64, 0, 0x18000
	v_add_u32_e32 v138, s64, v1
	s_add_i32 s65, 0, 0x1c000
	ds_read_b128 v[148:151], v138
	ds_read_b128 v[152:155], v138 offset:1024
	ds_read_b128 v[158:161], v138 offset:2048
	ds_read_b128 v[162:165], v138 offset:3072
	v_add_u32_e32 v138, s65, v1
	ds_read_b128 v[170:173], v138
	ds_read_b128 v[174:177], v138 offset:1024
	ds_read_b128 v[178:181], v138 offset:2048
	ds_read_b128 v[182:185], v138 offset:3072
	s_add_u32 s28, s28, s6
	s_addc_u32 s29, s29, s7
	s_mov_b32 m0, s43
	v_lshl_add_u64 v[228:229], s[28:29], 0, v[136:137]
	ds_read_b128 v[186:189], v157 offset:32768
	ds_read_b128 v[190:193], v157 offset:33792
	ds_read_b128 v[194:197], v157 offset:34816
	ds_read_b128 v[198:201], v157 offset:35840
	ds_read_b128 v[202:205], v157 offset:36864
	ds_read_b128 v[206:209], v157 offset:37888
	ds_read_b128 v[210:213], v157 offset:38912
	ds_read_b128 v[214:217], v157 offset:39936
	global_load_lds_dwordx4 v[228:229], off
	v_lshl_add_u64 v[228:229], s[28:29], 0, v[132:133]
	s_mov_b32 m0, s44
	s_nop 0
	global_load_lds_dwordx4 v[228:229], off
	s_waitcnt vmcnt(8)
	s_waitcnt lgkmcnt(0)
	s_barrier
	s_setprio 1
	s_waitcnt lgkmcnt(0)
	v_mfma_i32_16x16x64_i8 v[126:129], v[148:151], v[186:189], v[126:129]
	v_mfma_i32_16x16x64_i8 v[122:125], v[158:161], v[186:189], v[122:125]
	v_mfma_i32_16x16x64_i8 v[118:121], v[148:151], v[194:197], v[118:121]
	v_mfma_i32_16x16x64_i8 v[114:117], v[158:161], v[194:197], v[114:117]
	v_mfma_i32_16x16x64_i8 v[106:109], v[148:151], v[202:205], v[106:109]
	v_mfma_i32_16x16x64_i8 v[98:101], v[158:161], v[202:205], v[98:101]
	v_mfma_i32_16x16x64_i8 v[90:93], v[148:151], v[210:213], v[90:93]
	v_mfma_i32_16x16x64_i8 v[82:85], v[158:161], v[210:213], v[82:85]
	v_mfma_i32_16x16x64_i8 v[126:129], v[152:155], v[190:193], v[126:129]
	v_mfma_i32_16x16x64_i8 v[122:125], v[162:165], v[190:193], v[122:125]
	v_mfma_i32_16x16x64_i8 v[118:121], v[152:155], v[198:201], v[118:121]
	v_mfma_i32_16x16x64_i8 v[114:117], v[162:165], v[198:201], v[114:117]
	v_mfma_i32_16x16x64_i8 v[106:109], v[152:155], v[206:209], v[106:109]
	v_mfma_i32_16x16x64_i8 v[98:101], v[162:165], v[206:209], v[98:101]
	v_mfma_i32_16x16x64_i8 v[90:93], v[152:155], v[214:217], v[90:93]
	v_mfma_i32_16x16x64_i8 v[82:85], v[162:165], v[214:217], v[82:85]
	s_setprio 0
	s_setprio 1
	v_mfma_i32_16x16x64_i8 v[110:113], v[170:173], v[186:189], v[110:113]
	v_mfma_i32_16x16x64_i8 v[102:105], v[178:181], v[186:189], v[102:105]
	v_mfma_i32_16x16x64_i8 v[94:97], v[170:173], v[194:197], v[94:97]
	v_mfma_i32_16x16x64_i8 v[86:89], v[178:181], v[194:197], v[86:89]
	v_mfma_i32_16x16x64_i8 v[78:81], v[170:173], v[202:205], v[78:81]
	v_mfma_i32_16x16x64_i8 v[74:77], v[178:181], v[202:205], v[74:77]
	v_mfma_i32_16x16x64_i8 v[70:73], v[170:173], v[210:213], v[70:73]
	v_mfma_i32_16x16x64_i8 v[66:69], v[178:181], v[210:213], v[66:69]
	v_mfma_i32_16x16x64_i8 v[110:113], v[174:177], v[190:193], v[110:113]
	v_mfma_i32_16x16x64_i8 v[102:105], v[182:185], v[190:193], v[102:105]
	v_mfma_i32_16x16x64_i8 v[94:97], v[174:177], v[198:201], v[94:97]
	v_mfma_i32_16x16x64_i8 v[86:89], v[182:185], v[198:201], v[86:89]
	v_mfma_i32_16x16x64_i8 v[78:81], v[174:177], v[206:209], v[78:81]
	v_mfma_i32_16x16x64_i8 v[74:77], v[182:185], v[206:209], v[74:77]
	v_mfma_i32_16x16x64_i8 v[70:73], v[174:177], v[214:217], v[70:73]
	v_mfma_i32_16x16x64_i8 v[66:69], v[182:185], v[214:217], v[66:69]
	s_setprio 0
	s_barrier
	s_add_i32 s28, s64, s36
	v_lshl_add_u64 v[166:167], v[166:167], 0, s[16:17]
	s_mov_b32 m0, s28
	ds_read_b128 v[186:189], v157 offset:49152
	ds_read_b128 v[190:193], v157 offset:50176
	ds_read_b128 v[194:197], v157 offset:51200
	ds_read_b128 v[198:201], v157 offset:52224
	ds_read_b128 v[202:205], v157 offset:53248
	ds_read_b128 v[206:209], v157 offset:54272
	ds_read_b128 v[210:213], v157 offset:55296
	ds_read_b128 v[214:217], v157 offset:56320
	global_load_lds_dwordx4 v[166:167], off
	v_lshl_add_u64 v[166:167], v[218:219], 0, s[16:17]
	s_add_i32 m0, s28, 0x2000
	s_add_i32 s28, s65, s36
	global_load_lds_dwordx4 v[166:167], off
	v_lshl_add_u64 v[166:167], v[220:221], 0, s[16:17]
	s_mov_b32 m0, s28
	s_nop 0
	global_load_lds_dwordx4 v[166:167], off
	v_lshl_add_u64 v[166:167], v[222:223], 0, s[16:17]
	s_add_i32 m0, s28, 0x2000
	s_nop 0
	global_load_lds_dwordx4 v[166:167], off
	v_lshl_add_u64 v[166:167], v[224:225], 0, s[16:17]
	s_mov_b32 m0, s51
	s_nop 0
	global_load_lds_dwordx4 v[166:167], off
	v_lshl_add_u64 v[166:167], v[226:227], 0, s[16:17]
	s_mov_b32 m0, s52
	s_nop 0
	global_load_lds_dwordx4 v[166:167], off
	s_waitcnt vmcnt(8)
	s_waitcnt lgkmcnt(0)
	s_barrier
	s_setprio 1
	s_waitcnt lgkmcnt(0)
	v_mfma_i32_16x16x64_i8 v[62:65], v[148:151], v[186:189], v[62:65]
	v_mfma_i32_16x16x64_i8 v[58:61], v[158:161], v[186:189], v[58:61]
	v_mfma_i32_16x16x64_i8 v[54:57], v[148:151], v[194:197], v[54:57]
	v_mfma_i32_16x16x64_i8 v[50:53], v[158:161], v[194:197], v[50:53]
	v_mfma_i32_16x16x64_i8 v[42:45], v[148:151], v[202:205], v[42:45]
	v_mfma_i32_16x16x64_i8 v[34:37], v[158:161], v[202:205], v[34:37]
	v_mfma_i32_16x16x64_i8 v[26:29], v[148:151], v[210:213], v[26:29]
	v_mfma_i32_16x16x64_i8 v[18:21], v[158:161], v[210:213], v[18:21]
	v_mfma_i32_16x16x64_i8 v[62:65], v[152:155], v[190:193], v[62:65]
	v_mfma_i32_16x16x64_i8 v[58:61], v[162:165], v[190:193], v[58:61]
	v_mfma_i32_16x16x64_i8 v[54:57], v[152:155], v[198:201], v[54:57]
	v_mfma_i32_16x16x64_i8 v[50:53], v[162:165], v[198:201], v[50:53]
	v_mfma_i32_16x16x64_i8 v[42:45], v[152:155], v[206:209], v[42:45]
	v_mfma_i32_16x16x64_i8 v[34:37], v[162:165], v[206:209], v[34:37]
	v_mfma_i32_16x16x64_i8 v[26:29], v[152:155], v[214:217], v[26:29]
	v_mfma_i32_16x16x64_i8 v[18:21], v[162:165], v[214:217], v[18:21]
	s_setprio 0
	s_setprio 1
	v_mfma_i32_16x16x64_i8 v[46:49], v[170:173], v[186:189], v[46:49]
	v_mfma_i32_16x16x64_i8 v[38:41], v[178:181], v[186:189], v[38:41]
	v_mfma_i32_16x16x64_i8 v[30:33], v[170:173], v[194:197], v[30:33]
	v_mfma_i32_16x16x64_i8 v[22:25], v[178:181], v[194:197], v[22:25]
	v_mfma_i32_16x16x64_i8 v[14:17], v[170:173], v[202:205], v[14:17]
	v_mfma_i32_16x16x64_i8 v[10:13], v[178:181], v[202:205], v[10:13]
	v_mfma_i32_16x16x64_i8 v[6:9], v[170:173], v[210:213], v[6:9]
	v_mfma_i32_16x16x64_i8 v[2:5], v[178:181], v[210:213], v[2:5]
	v_mfma_i32_16x16x64_i8 v[46:49], v[174:177], v[190:193], v[46:49]
	v_mfma_i32_16x16x64_i8 v[38:41], v[182:185], v[190:193], v[38:41]
	v_mfma_i32_16x16x64_i8 v[30:33], v[174:177], v[198:201], v[30:33]
	v_mfma_i32_16x16x64_i8 v[22:25], v[182:185], v[198:201], v[22:25]
	v_mfma_i32_16x16x64_i8 v[14:17], v[174:177], v[206:209], v[14:17]
	v_mfma_i32_16x16x64_i8 v[10:13], v[182:185], v[206:209], v[10:13]
	v_mfma_i32_16x16x64_i8 v[6:9], v[174:177], v[214:217], v[6:9]
	v_mfma_i32_16x16x64_i8 v[2:5], v[182:185], v[214:217], v[2:5]
	s_setprio 0
	s_add_u32 s26, s26, 0x100
	s_addc_u32 s27, s27, 0
	s_add_u32 s61, s61, 0x100
	s_addc_u32 s62, s62, 0
	s_cmp_ge_i32 s63, s48
	s_mov_b32 s28, s63
	s_barrier
	s_cbranch_scc0 .LBB0_800
	v_cvt_f32_i32_e32 v172, v126
	v_cvt_f32_i32_e32 v173, v127
	v_cvt_f32_i32_e32 v166, v128
	v_cvt_f32_i32_e32 v167, v129
	v_cvt_f32_i32_e32 v174, v122
	v_cvt_f32_i32_e32 v175, v123
	v_cvt_f32_i32_e32 v176, v124
	v_cvt_f32_i32_e32 v177, v125
	v_cvt_f32_i32_e32 v158, v110
	v_cvt_f32_i32_e32 v159, v111
	v_cvt_f32_i32_e32 v160, v112
	v_cvt_f32_i32_e32 v161, v113
	v_cvt_f32_i32_e32 v162, v102
	v_cvt_f32_i32_e32 v163, v103
	v_cvt_f32_i32_e32 v164, v104
	v_cvt_f32_i32_e32 v165, v105
	v_cvt_f32_i32_e32 v148, v118
	v_cvt_f32_i32_e32 v149, v119
	v_cvt_f32_i32_e32 v150, v120
	v_cvt_f32_i32_e32 v151, v121
	v_cvt_f32_i32_e32 v152, v114
	v_cvt_f32_i32_e32 v153, v115
	v_cvt_f32_i32_e32 v154, v116
	v_cvt_f32_i32_e32 v155, v117
	v_cvt_f32_i32_e32 v112, v94
	v_cvt_f32_i32_e32 v113, v95
	v_cvt_f32_i32_e32 v116, v96
	v_cvt_f32_i32_e32 v117, v97
	v_cvt_f32_i32_e32 v110, v86
	v_cvt_f32_i32_e32 v111, v87
	v_cvt_f32_i32_e32 v114, v88
	v_cvt_f32_i32_e32 v115, v89
	v_cvt_f32_i32_e32 v96, v106
	v_cvt_f32_i32_e32 v97, v107
	v_cvt_f32_i32_e32 v102, v108
	v_cvt_f32_i32_e32 v103, v109
	v_cvt_f32_i32_e32 v94, v98
	v_cvt_f32_i32_e32 v95, v99
	v_cvt_f32_i32_e32 v98, v100
	v_cvt_f32_i32_e32 v99, v101
	v_cvt_f32_i32_e32 v104, v78
	v_cvt_f32_i32_e32 v105, v79
	v_cvt_f32_i32_e32 v108, v80
	v_cvt_f32_i32_e32 v109, v81
	v_cvt_f32_i32_e32 v100, v74
	v_cvt_f32_i32_e32 v101, v75
	v_cvt_f32_i32_e32 v106, v76
	v_cvt_f32_i32_e32 v107, v77
	v_cvt_f32_i32_e32 v76, v90
	v_cvt_f32_i32_e32 v77, v91
	v_cvt_f32_i32_e32 v80, v92
	v_cvt_f32_i32_e32 v81, v93
	v_cvt_f32_i32_e32 v74, v82
	v_cvt_f32_i32_e32 v75, v83
	v_cvt_f32_i32_e32 v78, v84
	v_cvt_f32_i32_e32 v79, v85
	v_cvt_f32_i32_e32 v84, v70
	v_cvt_f32_i32_e32 v85, v71
	v_cvt_f32_i32_e32 v92, v72
	v_cvt_f32_i32_e32 v93, v73
	v_cvt_f32_i32_e32 v82, v66
	v_cvt_f32_i32_e32 v83, v67
	v_cvt_f32_i32_e32 v90, v68
	v_cvt_f32_i32_e32 v91, v69
	v_cvt_f32_i32_e32 v66, v62
	v_cvt_f32_i32_e32 v67, v63
	v_cvt_f32_i32_e32 v68, v64
	v_cvt_f32_i32_e32 v69, v65
	v_cvt_f32_i32_e32 v62, v58
	v_cvt_f32_i32_e32 v63, v59
	v_cvt_f32_i32_e32 v64, v60
	v_cvt_f32_i32_e32 v65, v61
	v_cvt_f32_i32_e32 v72, v46
	v_cvt_f32_i32_e32 v73, v47
	v_cvt_f32_i32_e32 v88, v48
	v_cvt_f32_i32_e32 v89, v49
	v_cvt_f32_i32_e32 v70, v38
	v_cvt_f32_i32_e32 v71, v39
	v_cvt_f32_i32_e32 v86, v40
	v_cvt_f32_i32_e32 v87, v41
	v_cvt_f32_i32_e32 v48, v54
	v_cvt_f32_i32_e32 v49, v55
	v_cvt_f32_i32_e32 v54, v56
	v_cvt_f32_i32_e32 v55, v57
	v_cvt_f32_i32_e32 v46, v50
	v_cvt_f32_i32_e32 v47, v51
	v_cvt_f32_i32_e32 v50, v52
	v_cvt_f32_i32_e32 v51, v53
	v_cvt_f32_i32_e32 v56, v30
	v_cvt_f32_i32_e32 v57, v31
	v_cvt_f32_i32_e32 v60, v32
	v_cvt_f32_i32_e32 v61, v33
	v_cvt_f32_i32_e32 v52, v22
	v_cvt_f32_i32_e32 v53, v23
	v_cvt_f32_i32_e32 v58, v24
	v_cvt_f32_i32_e32 v59, v25
	v_cvt_f32_i32_e32 v24, v42
	v_cvt_f32_i32_e32 v25, v43
	v_cvt_f32_i32_e32 v32, v44
	v_cvt_f32_i32_e32 v33, v45
	v_cvt_f32_i32_e32 v22, v34
	v_cvt_f32_i32_e32 v23, v35
	v_cvt_f32_i32_e32 v30, v36
	v_cvt_f32_i32_e32 v31, v37
	v_cvt_f32_i32_e32 v36, v14
	v_cvt_f32_i32_e32 v37, v15
	v_cvt_f32_i32_e32 v40, v16
	v_cvt_f32_i32_e32 v41, v17
	v_cvt_f32_i32_e32 v34, v10
	v_cvt_f32_i32_e32 v35, v11
	v_cvt_f32_i32_e32 v38, v12
	v_cvt_f32_i32_e32 v39, v13
	v_cvt_f32_i32_e32 v12, v26
	v_cvt_f32_i32_e32 v13, v27
	v_cvt_f32_i32_e32 v16, v28
	v_cvt_f32_i32_e32 v17, v29
	v_cvt_f32_i32_e32 v10, v18
	v_cvt_f32_i32_e32 v11, v19
	v_cvt_f32_i32_e32 v14, v20
	v_cvt_f32_i32_e32 v15, v21
	v_cvt_f32_i32_e32 v18, v6
	v_cvt_f32_i32_e32 v19, v7
	v_cvt_f32_i32_e32 v20, v8
	v_cvt_f32_i32_e32 v21, v9
	v_cvt_f32_i32_e32 v6, v2
	v_cvt_f32_i32_e32 v7, v3
	v_cvt_f32_i32_e32 v8, v4
	v_cvt_f32_i32_e32 v9, v5

.LBB0_1297:
	v_add_u32_e32 v138, s77, v1
	ds_read_b128 v[148:151], v138
	ds_read_b128 v[152:155], v138 offset:1024
	ds_read_b128 v[156:159], v138 offset:2048
	ds_read_b128 v[160:163], v138 offset:3072
	v_add_u32_e32 v138, s78, v1
	ds_read_b128 v[164:167], v138
	ds_read_b128 v[170:173], v138 offset:1024
	ds_read_b128 v[174:177], v138 offset:2048
	ds_read_b128 v[178:181], v138 offset:3072
	s_add_i32 s46, s6, 2
	s_add_u32 s47, s4, 0x80
	s_addc_u32 s7, s5, 0
	s_cmp_eq_u32 s55, s6
	s_cselect_b32 s6, s40, s47
	s_cselect_b32 s7, s41, s7
	s_cselect_b32 s51, s43, s45
	s_cselect_b32 s50, s42, s44
	v_lshl_add_u64 v[198:199], s[4:5], 0, v[140:141]
	s_add_i32 m0, s70, 0xc000
	ds_read_b128 v[182:185], v169
	ds_read_b128 v[186:189], v169 offset:1024
	ds_read_b128 v[190:193], v169 offset:2048
	ds_read_b128 v[194:197], v169 offset:3072
	ds_read_b128 v[202:205], v169 offset:4096
	ds_read_b128 v[206:209], v169 offset:5120
	ds_read_b128 v[210:213], v169 offset:6144
	ds_read_b128 v[214:217], v169 offset:7168
	global_load_lds_dwordx4 v[198:199], off
	v_lshl_add_u64 v[198:199], s[4:5], 0, v[142:143]
	s_add_i32 m0, s70, 0xe000
	s_nop 0
	global_load_lds_dwordx4 v[198:199], off
	s_waitcnt vmcnt(8)
	s_waitcnt lgkmcnt(0)
	s_barrier
	s_setprio 1
	s_waitcnt lgkmcnt(0)
	v_mfma_i32_16x16x64_i8 v[126:129], v[148:151], v[182:185], v[126:129]
	v_mfma_i32_16x16x64_i8 v[122:125], v[156:159], v[182:185], v[122:125]
	v_mfma_i32_16x16x64_i8 v[118:121], v[148:151], v[190:193], v[118:121]
	v_mfma_i32_16x16x64_i8 v[114:117], v[156:159], v[190:193], v[114:117]
	v_mfma_i32_16x16x64_i8 v[106:109], v[148:151], v[202:205], v[106:109]
	v_mfma_i32_16x16x64_i8 v[98:101], v[156:159], v[202:205], v[98:101]
	v_mfma_i32_16x16x64_i8 v[90:93], v[148:151], v[210:213], v[90:93]
	v_mfma_i32_16x16x64_i8 v[82:85], v[156:159], v[210:213], v[82:85]
	v_mfma_i32_16x16x64_i8 v[126:129], v[152:155], v[186:189], v[126:129]
	v_mfma_i32_16x16x64_i8 v[122:125], v[160:163], v[186:189], v[122:125]
	v_mfma_i32_16x16x64_i8 v[118:121], v[152:155], v[194:197], v[118:121]
	v_mfma_i32_16x16x64_i8 v[114:117], v[160:163], v[194:197], v[114:117]
	v_mfma_i32_16x16x64_i8 v[106:109], v[152:155], v[206:209], v[106:109]
	v_mfma_i32_16x16x64_i8 v[98:101], v[160:163], v[206:209], v[98:101]
	v_mfma_i32_16x16x64_i8 v[90:93], v[152:155], v[214:217], v[90:93]
	v_mfma_i32_16x16x64_i8 v[82:85], v[160:163], v[214:217], v[82:85]
	s_setprio 0
	s_setprio 1
	v_mfma_i32_16x16x64_i8 v[110:113], v[164:167], v[182:185], v[110:113]
	v_mfma_i32_16x16x64_i8 v[102:105], v[174:177], v[182:185], v[102:105]
	v_mfma_i32_16x16x64_i8 v[94:97], v[164:167], v[190:193], v[94:97]
	v_mfma_i32_16x16x64_i8 v[86:89], v[174:177], v[190:193], v[86:89]
	v_mfma_i32_16x16x64_i8 v[78:81], v[164:167], v[202:205], v[78:81]
	v_mfma_i32_16x16x64_i8 v[74:77], v[174:177], v[202:205], v[74:77]
	v_mfma_i32_16x16x64_i8 v[70:73], v[164:167], v[210:213], v[70:73]
	v_mfma_i32_16x16x64_i8 v[66:69], v[174:177], v[210:213], v[66:69]
	v_mfma_i32_16x16x64_i8 v[110:113], v[170:173], v[186:189], v[110:113]
	v_mfma_i32_16x16x64_i8 v[102:105], v[178:181], v[186:189], v[102:105]
	v_mfma_i32_16x16x64_i8 v[94:97], v[170:173], v[194:197], v[94:97]
	v_mfma_i32_16x16x64_i8 v[86:89], v[178:181], v[194:197], v[86:89]
	v_mfma_i32_16x16x64_i8 v[78:81], v[170:173], v[206:209], v[78:81]
	v_mfma_i32_16x16x64_i8 v[74:77], v[178:181], v[206:209], v[74:77]
	v_mfma_i32_16x16x64_i8 v[70:73], v[170:173], v[214:217], v[70:73]
	v_mfma_i32_16x16x64_i8 v[66:69], v[178:181], v[214:217], v[66:69]
	s_setprio 0
	s_barrier
	s_add_i32 s47, s77, s69
	v_lshl_add_u64 v[198:199], s[50:51], 0, v[132:133]
	s_mov_b32 m0, s47
	ds_read_b128 v[182:185], v169 offset:16384
	ds_read_b128 v[186:189], v169 offset:17408
	ds_read_b128 v[190:193], v169 offset:18432
	ds_read_b128 v[194:197], v169 offset:19456
	ds_read_b128 v[202:205], v169 offset:20480
	ds_read_b128 v[206:209], v169 offset:21504
	ds_read_b128 v[210:213], v169 offset:22528
	ds_read_b128 v[214:217], v169 offset:23552
	global_load_lds_dwordx4 v[198:199], off
	s_add_i32 m0, s47, 0x2000
	v_lshl_add_u64 v[218:219], s[50:51], 0, v[136:137]
	s_add_u32 s50, s50, s22
	s_addc_u32 s51, s51, s23
	s_add_i32 s47, s78, s69
	global_load_lds_dwordx4 v[218:219], off
	v_lshl_add_u64 v[220:221], s[50:51], 0, v[132:133]
	s_mov_b32 m0, s47
	v_lshl_add_u64 v[222:223], s[50:51], 0, v[136:137]
	global_load_lds_dwordx4 v[220:221], off
	s_add_i32 m0, s47, 0x2000
	v_lshl_add_u64 v[224:225], s[6:7], 0, v[130:131]
	global_load_lds_dwordx4 v[222:223], off
	s_mov_b32 m0, s70
	v_lshl_add_u64 v[226:227], s[6:7], 0, v[134:135]
	global_load_lds_dwordx4 v[224:225], off
	s_mov_b32 m0, s71
	s_nop 0
	global_load_lds_dwordx4 v[226:227], off
	s_waitcnt vmcnt(8)
	s_waitcnt lgkmcnt(0)
	s_barrier
	s_setprio 1
	s_waitcnt lgkmcnt(0)
	v_mfma_i32_16x16x64_i8 v[62:65], v[148:151], v[182:185], v[62:65]
	v_mfma_i32_16x16x64_i8 v[58:61], v[156:159], v[182:185], v[58:61]
	v_mfma_i32_16x16x64_i8 v[54:57], v[148:151], v[190:193], v[54:57]
	v_mfma_i32_16x16x64_i8 v[50:53], v[156:159], v[190:193], v[50:53]
	v_mfma_i32_16x16x64_i8 v[42:45], v[148:151], v[202:205], v[42:45]
	v_mfma_i32_16x16x64_i8 v[34:37], v[156:159], v[202:205], v[34:37]
	v_mfma_i32_16x16x64_i8 v[26:29], v[148:151], v[210:213], v[26:29]
	v_mfma_i32_16x16x64_i8 v[18:21], v[156:159], v[210:213], v[18:21]
	v_mfma_i32_16x16x64_i8 v[62:65], v[152:155], v[186:189], v[62:65]
	v_mfma_i32_16x16x64_i8 v[58:61], v[160:163], v[186:189], v[58:61]
	v_mfma_i32_16x16x64_i8 v[54:57], v[152:155], v[194:197], v[54:57]
	v_mfma_i32_16x16x64_i8 v[50:53], v[160:163], v[194:197], v[50:53]
	v_mfma_i32_16x16x64_i8 v[42:45], v[152:155], v[206:209], v[42:45]
	v_mfma_i32_16x16x64_i8 v[34:37], v[160:163], v[206:209], v[34:37]
	v_mfma_i32_16x16x64_i8 v[26:29], v[152:155], v[214:217], v[26:29]
	v_mfma_i32_16x16x64_i8 v[18:21], v[160:163], v[214:217], v[18:21]
	s_setprio 0
	s_setprio 1
	v_mfma_i32_16x16x64_i8 v[46:49], v[164:167], v[182:185], v[46:49]
	v_mfma_i32_16x16x64_i8 v[38:41], v[174:177], v[182:185], v[38:41]
	v_mfma_i32_16x16x64_i8 v[30:33], v[164:167], v[190:193], v[30:33]
	v_mfma_i32_16x16x64_i8 v[22:25], v[174:177], v[190:193], v[22:25]
	v_mfma_i32_16x16x64_i8 v[14:17], v[164:167], v[202:205], v[14:17]
	v_mfma_i32_16x16x64_i8 v[10:13], v[174:177], v[202:205], v[10:13]
	v_mfma_i32_16x16x64_i8 v[6:9], v[164:167], v[210:213], v[6:9]
	v_mfma_i32_16x16x64_i8 v[2:5], v[174:177], v[210:213], v[2:5]
	v_mfma_i32_16x16x64_i8 v[46:49], v[170:173], v[186:189], v[46:49]
	v_mfma_i32_16x16x64_i8 v[38:41], v[178:181], v[186:189], v[38:41]
	v_mfma_i32_16x16x64_i8 v[30:33], v[170:173], v[194:197], v[30:33]
	v_mfma_i32_16x16x64_i8 v[22:25], v[178:181], v[194:197], v[22:25]
	v_mfma_i32_16x16x64_i8 v[14:17], v[170:173], v[206:209], v[14:17]
	v_mfma_i32_16x16x64_i8 v[10:13], v[178:181], v[206:209], v[10:13]
	v_mfma_i32_16x16x64_i8 v[6:9], v[170:173], v[214:217], v[6:9]
	v_mfma_i32_16x16x64_i8 v[2:5], v[178:181], v[214:217], v[2:5]
	s_setprio 0
	s_barrier
	s_add_i32 s47, 0, 0x18000
	v_add_u32_e32 v138, s47, v1
	s_add_i32 s49, 0, 0x1c000
	ds_read_b128 v[148:151], v138
	ds_read_b128 v[152:155], v138 offset:1024
	ds_read_b128 v[156:159], v138 offset:2048
	ds_read_b128 v[160:163], v138 offset:3072
	v_add_u32_e32 v138, s49, v1
	ds_read_b128 v[164:167], v138
	ds_read_b128 v[170:173], v138 offset:1024
	ds_read_b128 v[174:177], v138 offset:2048
	ds_read_b128 v[178:181], v138 offset:3072
	s_add_u32 s6, s6, s22
	s_addc_u32 s7, s7, s23
	s_mov_b32 m0, s72
	v_lshl_add_u64 v[228:229], s[6:7], 0, v[130:131]
	ds_read_b128 v[182:185], v169 offset:32768
	ds_read_b128 v[186:189], v169 offset:33792
	ds_read_b128 v[190:193], v169 offset:34816
	ds_read_b128 v[194:197], v169 offset:35840
	ds_read_b128 v[202:205], v169 offset:36864
	ds_read_b128 v[206:209], v169 offset:37888
	ds_read_b128 v[210:213], v169 offset:38912
	ds_read_b128 v[214:217], v169 offset:39936
	global_load_lds_dwordx4 v[228:229], off
	v_lshl_add_u64 v[228:229], s[6:7], 0, v[134:135]
	s_mov_b32 m0, s73
	s_nop 0
	global_load_lds_dwordx4 v[228:229], off
	s_waitcnt vmcnt(8)
	s_waitcnt lgkmcnt(0)
	s_barrier
	s_setprio 1
	s_waitcnt lgkmcnt(0)
	v_mfma_i32_16x16x64_i8 v[126:129], v[148:151], v[182:185], v[126:129]
	v_mfma_i32_16x16x64_i8 v[122:125], v[156:159], v[182:185], v[122:125]
	v_mfma_i32_16x16x64_i8 v[118:121], v[148:151], v[190:193], v[118:121]
	v_mfma_i32_16x16x64_i8 v[114:117], v[156:159], v[190:193], v[114:117]
	v_mfma_i32_16x16x64_i8 v[106:109], v[148:151], v[202:205], v[106:109]
	v_mfma_i32_16x16x64_i8 v[98:101], v[156:159], v[202:205], v[98:101]
	v_mfma_i32_16x16x64_i8 v[90:93], v[148:151], v[210:213], v[90:93]
	v_mfma_i32_16x16x64_i8 v[82:85], v[156:159], v[210:213], v[82:85]
	v_mfma_i32_16x16x64_i8 v[126:129], v[152:155], v[186:189], v[126:129]
	v_mfma_i32_16x16x64_i8 v[122:125], v[160:163], v[186:189], v[122:125]
	v_mfma_i32_16x16x64_i8 v[118:121], v[152:155], v[194:197], v[118:121]
	v_mfma_i32_16x16x64_i8 v[114:117], v[160:163], v[194:197], v[114:117]
	v_mfma_i32_16x16x64_i8 v[106:109], v[152:155], v[206:209], v[106:109]
	v_mfma_i32_16x16x64_i8 v[98:101], v[160:163], v[206:209], v[98:101]
	v_mfma_i32_16x16x64_i8 v[90:93], v[152:155], v[214:217], v[90:93]
	v_mfma_i32_16x16x64_i8 v[82:85], v[160:163], v[214:217], v[82:85]
	s_setprio 0
	s_setprio 1
	v_mfma_i32_16x16x64_i8 v[110:113], v[164:167], v[182:185], v[110:113]
	v_mfma_i32_16x16x64_i8 v[102:105], v[174:177], v[182:185], v[102:105]
	v_mfma_i32_16x16x64_i8 v[94:97], v[164:167], v[190:193], v[94:97]
	v_mfma_i32_16x16x64_i8 v[86:89], v[174:177], v[190:193], v[86:89]
	v_mfma_i32_16x16x64_i8 v[78:81], v[164:167], v[202:205], v[78:81]
	v_mfma_i32_16x16x64_i8 v[74:77], v[174:177], v[202:205], v[74:77]
	v_mfma_i32_16x16x64_i8 v[70:73], v[164:167], v[210:213], v[70:73]
	v_mfma_i32_16x16x64_i8 v[66:69], v[174:177], v[210:213], v[66:69]
	v_mfma_i32_16x16x64_i8 v[110:113], v[170:173], v[186:189], v[110:113]
	v_mfma_i32_16x16x64_i8 v[102:105], v[178:181], v[186:189], v[102:105]
	v_mfma_i32_16x16x64_i8 v[94:97], v[170:173], v[194:197], v[94:97]
	v_mfma_i32_16x16x64_i8 v[86:89], v[178:181], v[194:197], v[86:89]
	v_mfma_i32_16x16x64_i8 v[78:81], v[170:173], v[206:209], v[78:81]
	v_mfma_i32_16x16x64_i8 v[74:77], v[178:181], v[206:209], v[74:77]
	v_mfma_i32_16x16x64_i8 v[70:73], v[170:173], v[214:217], v[70:73]
	v_mfma_i32_16x16x64_i8 v[66:69], v[178:181], v[214:217], v[66:69]
	s_setprio 0
	s_barrier
	s_add_i32 s6, s47, s69
	v_lshl_add_u64 v[198:199], v[198:199], 0, s[34:35]
	s_mov_b32 m0, s6
	ds_read_b128 v[182:185], v169 offset:49152
	ds_read_b128 v[186:189], v169 offset:50176
	ds_read_b128 v[190:193], v169 offset:51200
	ds_read_b128 v[194:197], v169 offset:52224
	ds_read_b128 v[202:205], v169 offset:53248
	ds_read_b128 v[206:209], v169 offset:54272
	ds_read_b128 v[210:213], v169 offset:55296
	ds_read_b128 v[214:217], v169 offset:56320
	global_load_lds_dwordx4 v[198:199], off
	v_lshl_add_u64 v[198:199], v[218:219], 0, s[34:35]
	s_add_i32 m0, s6, 0x2000
	s_add_i32 s6, s49, s69
	global_load_lds_dwordx4 v[198:199], off
	v_lshl_add_u64 v[198:199], v[220:221], 0, s[34:35]
	s_mov_b32 m0, s6
	s_nop 0
	global_load_lds_dwordx4 v[198:199], off
	v_lshl_add_u64 v[198:199], v[222:223], 0, s[34:35]
	s_add_i32 m0, s6, 0x2000
	s_nop 0
	global_load_lds_dwordx4 v[198:199], off
	v_lshl_add_u64 v[198:199], v[224:225], 0, s[34:35]
	s_mov_b32 m0, s74
	s_nop 0
	global_load_lds_dwordx4 v[198:199], off
	v_lshl_add_u64 v[198:199], v[226:227], 0, s[34:35]
	s_mov_b32 m0, s75
	s_nop 0
	global_load_lds_dwordx4 v[198:199], off
	s_waitcnt vmcnt(8)
	s_waitcnt lgkmcnt(0)
	s_barrier
	s_setprio 1
	s_waitcnt lgkmcnt(0)
	v_mfma_i32_16x16x64_i8 v[62:65], v[148:151], v[182:185], v[62:65]
	v_mfma_i32_16x16x64_i8 v[58:61], v[156:159], v[182:185], v[58:61]
	v_mfma_i32_16x16x64_i8 v[54:57], v[148:151], v[190:193], v[54:57]
	v_mfma_i32_16x16x64_i8 v[50:53], v[156:159], v[190:193], v[50:53]
	v_mfma_i32_16x16x64_i8 v[42:45], v[148:151], v[202:205], v[42:45]
	v_mfma_i32_16x16x64_i8 v[34:37], v[156:159], v[202:205], v[34:37]
	v_mfma_i32_16x16x64_i8 v[26:29], v[148:151], v[210:213], v[26:29]
	v_mfma_i32_16x16x64_i8 v[18:21], v[156:159], v[210:213], v[18:21]
	v_mfma_i32_16x16x64_i8 v[62:65], v[152:155], v[186:189], v[62:65]
	v_mfma_i32_16x16x64_i8 v[58:61], v[160:163], v[186:189], v[58:61]
	v_mfma_i32_16x16x64_i8 v[54:57], v[152:155], v[194:197], v[54:57]
	v_mfma_i32_16x16x64_i8 v[50:53], v[160:163], v[194:197], v[50:53]
	v_mfma_i32_16x16x64_i8 v[42:45], v[152:155], v[206:209], v[42:45]
	v_mfma_i32_16x16x64_i8 v[34:37], v[160:163], v[206:209], v[34:37]
	v_mfma_i32_16x16x64_i8 v[26:29], v[152:155], v[214:217], v[26:29]
	v_mfma_i32_16x16x64_i8 v[18:21], v[160:163], v[214:217], v[18:21]
	s_setprio 0
	s_setprio 1
	v_mfma_i32_16x16x64_i8 v[46:49], v[164:167], v[182:185], v[46:49]
	v_mfma_i32_16x16x64_i8 v[38:41], v[174:177], v[182:185], v[38:41]
	v_mfma_i32_16x16x64_i8 v[30:33], v[164:167], v[190:193], v[30:33]
	v_mfma_i32_16x16x64_i8 v[22:25], v[174:177], v[190:193], v[22:25]
	v_mfma_i32_16x16x64_i8 v[14:17], v[164:167], v[202:205], v[14:17]
	v_mfma_i32_16x16x64_i8 v[10:13], v[174:177], v[202:205], v[10:13]
	v_mfma_i32_16x16x64_i8 v[6:9], v[164:167], v[210:213], v[6:9]
	v_mfma_i32_16x16x64_i8 v[2:5], v[174:177], v[210:213], v[2:5]
	v_mfma_i32_16x16x64_i8 v[46:49], v[170:173], v[186:189], v[46:49]
	v_mfma_i32_16x16x64_i8 v[38:41], v[178:181], v[186:189], v[38:41]
	v_mfma_i32_16x16x64_i8 v[30:33], v[170:173], v[194:197], v[30:33]
	v_mfma_i32_16x16x64_i8 v[22:25], v[178:181], v[194:197], v[22:25]
	v_mfma_i32_16x16x64_i8 v[14:17], v[170:173], v[206:209], v[14:17]
	v_mfma_i32_16x16x64_i8 v[10:13], v[178:181], v[206:209], v[10:13]
	v_mfma_i32_16x16x64_i8 v[6:9], v[170:173], v[214:217], v[6:9]
	v_mfma_i32_16x16x64_i8 v[2:5], v[178:181], v[214:217], v[2:5]
	s_setprio 0
	s_add_u32 s4, s4, 0x100
	s_addc_u32 s5, s5, 0
	s_add_u32 s44, s44, 0x100
	s_addc_u32 s45, s45, 0
	s_cmp_ge_i32 s46, s52
	s_mov_b32 s6, s46
	s_barrier
	s_cbranch_scc0 .LBB0_1297
	v_cvt_f32_i32_e32 v182, v126
	v_cvt_f32_i32_e32 v183, v127
	v_cvt_f32_i32_e32 v180, v128
	v_cvt_f32_i32_e32 v181, v129
	v_cvt_f32_i32_e32 v184, v122
	v_cvt_f32_i32_e32 v185, v123
	v_cvt_f32_i32_e32 v186, v124
	v_cvt_f32_i32_e32 v187, v125
	v_cvt_f32_i32_e32 v170, v110
	v_cvt_f32_i32_e32 v171, v111
	v_cvt_f32_i32_e32 v174, v112
	v_cvt_f32_i32_e32 v175, v113
	v_cvt_f32_i32_e32 v172, v102
	v_cvt_f32_i32_e32 v173, v103
	v_cvt_f32_i32_e32 v166, v104
	v_cvt_f32_i32_e32 v167, v105
	v_cvt_f32_i32_e32 v162, v118
	v_cvt_f32_i32_e32 v163, v119
	v_cvt_f32_i32_e32 v164, v120
	v_cvt_f32_i32_e32 v165, v121
	v_cvt_f32_i32_e32 v158, v114
	v_cvt_f32_i32_e32 v159, v115
	v_cvt_f32_i32_e32 v160, v116
	v_cvt_f32_i32_e32 v161, v117
	v_cvt_f32_i32_e32 v152, v94
	v_cvt_f32_i32_e32 v153, v95
	v_cvt_f32_i32_e32 v154, v96
	v_cvt_f32_i32_e32 v155, v97
	v_cvt_f32_i32_e32 v128, v86
	v_cvt_f32_i32_e32 v129, v87
	v_cvt_f32_i32_e32 v148, v88
	v_cvt_f32_i32_e32 v149, v89
	v_cvt_f32_i32_e32 v124, v106
	v_cvt_f32_i32_e32 v125, v107
	v_cvt_f32_i32_e32 v126, v108
	v_cvt_f32_i32_e32 v127, v109
	v_cvt_f32_i32_e32 v120, v98
	v_cvt_f32_i32_e32 v121, v99
	v_cvt_f32_i32_e32 v122, v100
	v_cvt_f32_i32_e32 v123, v101
	v_cvt_f32_i32_e32 v114, v78
	v_cvt_f32_i32_e32 v115, v79
	v_cvt_f32_i32_e32 v116, v80
	v_cvt_f32_i32_e32 v117, v81
	v_cvt_f32_i32_e32 v110, v74
	v_cvt_f32_i32_e32 v111, v75
	v_cvt_f32_i32_e32 v112, v76
	v_cvt_f32_i32_e32 v113, v77
	v_cvt_f32_i32_e32 v104, v90
	v_cvt_f32_i32_e32 v105, v91
	v_cvt_f32_i32_e32 v106, v92
	v_cvt_f32_i32_e32 v107, v93
	v_cvt_f32_i32_e32 v100, v82
	v_cvt_f32_i32_e32 v101, v83
	v_cvt_f32_i32_e32 v102, v84
	v_cvt_f32_i32_e32 v103, v85
	v_cvt_f32_i32_e32 v96, v70
	v_cvt_f32_i32_e32 v97, v71
	v_cvt_f32_i32_e32 v98, v72
	v_cvt_f32_i32_e32 v99, v73
	v_cvt_f32_i32_e32 v92, v66
	v_cvt_f32_i32_e32 v93, v67
	v_cvt_f32_i32_e32 v94, v68
	v_cvt_f32_i32_e32 v95, v69
	v_cvt_f32_i32_e32 v86, v62
	v_cvt_f32_i32_e32 v87, v63
	v_cvt_f32_i32_e32 v88, v64
	v_cvt_f32_i32_e32 v89, v65
	v_cvt_f32_i32_e32 v82, v58
	v_cvt_f32_i32_e32 v83, v59
	v_cvt_f32_i32_e32 v84, v60
	v_cvt_f32_i32_e32 v85, v61
	v_cvt_f32_i32_e32 v78, v46
	v_cvt_f32_i32_e32 v79, v47
	v_cvt_f32_i32_e32 v80, v48
	v_cvt_f32_i32_e32 v81, v49
	v_cvt_f32_i32_e32 v74, v38
	v_cvt_f32_i32_e32 v75, v39
	v_cvt_f32_i32_e32 v76, v40
	v_cvt_f32_i32_e32 v77, v41
	v_cvt_f32_i32_e32 v68, v54
	v_cvt_f32_i32_e32 v69, v55
	v_cvt_f32_i32_e32 v70, v56
	v_cvt_f32_i32_e32 v71, v57
	v_cvt_f32_i32_e32 v64, v50
	v_cvt_f32_i32_e32 v65, v51
	v_cvt_f32_i32_e32 v66, v52
	v_cvt_f32_i32_e32 v67, v53
	v_cvt_f32_i32_e32 v60, v30
	v_cvt_f32_i32_e32 v61, v31
	v_cvt_f32_i32_e32 v62, v32
	v_cvt_f32_i32_e32 v63, v33
	v_cvt_f32_i32_e32 v56, v22
	v_cvt_f32_i32_e32 v57, v23
	v_cvt_f32_i32_e32 v58, v24
	v_cvt_f32_i32_e32 v59, v25
	v_cvt_f32_i32_e32 v50, v42
	v_cvt_f32_i32_e32 v51, v43
	v_cvt_f32_i32_e32 v52, v44
	v_cvt_f32_i32_e32 v53, v45
	v_cvt_f32_i32_e32 v46, v34
	v_cvt_f32_i32_e32 v47, v35
	v_cvt_f32_i32_e32 v48, v36
	v_cvt_f32_i32_e32 v49, v37
	v_cvt_f32_i32_e32 v34, v14
	v_cvt_f32_i32_e32 v35, v15
	v_cvt_f32_i32_e32 v36, v16
	v_cvt_f32_i32_e32 v37, v17
	v_cvt_f32_i32_e32 v30, v10
	v_cvt_f32_i32_e32 v31, v11
	v_cvt_f32_i32_e32 v32, v12
	v_cvt_f32_i32_e32 v33, v13
	v_cvt_f32_i32_e32 v22, v26
	v_cvt_f32_i32_e32 v23, v27
	v_cvt_f32_i32_e32 v24, v28
	v_cvt_f32_i32_e32 v25, v29
	v_cvt_f32_i32_e32 v18, v18
	v_cvt_f32_i32_e32 v19, v19
	v_cvt_f32_i32_e32 v20, v20
	v_cvt_f32_i32_e32 v21, v21
	v_cvt_f32_i32_e32 v14, v6
	v_cvt_f32_i32_e32 v15, v7
	v_cvt_f32_i32_e32 v16, v8
	v_cvt_f32_i32_e32 v17, v9
	v_cvt_f32_i32_e32 v10, v2
	v_cvt_f32_i32_e32 v11, v3
	v_cvt_f32_i32_e32 v12, v4
	v_cvt_f32_i32_e32 v13, v5

.LBB0_1513:
	v_add_u32_e32 v138, s55, v1
	ds_read_b128 v[148:151], v138
	ds_read_b128 v[152:155], v138 offset:1024
	ds_read_b128 v[156:159], v138 offset:2048
	ds_read_b128 v[160:163], v138 offset:3072
	v_add_u32_e32 v138, s76, v1
	ds_read_b128 v[164:167], v138
	ds_read_b128 v[170:173], v138 offset:1024
	ds_read_b128 v[174:177], v138 offset:2048
	ds_read_b128 v[178:181], v138 offset:3072
	s_add_i32 s46, s6, 2
	s_add_u32 s47, s4, 0x80
	s_addc_u32 s7, s5, 0
	s_cmp_eq_u32 s53, s6
	s_cselect_b32 s6, s40, s47
	s_cselect_b32 s7, s41, s7
	s_cselect_b32 s51, s43, s45
	s_cselect_b32 s50, s42, s44
	v_lshl_add_u64 v[198:199], s[4:5], 0, v[140:141]
	s_add_i32 m0, s68, 0xc000
	ds_read_b128 v[182:185], v169
	ds_read_b128 v[186:189], v169 offset:1024
	ds_read_b128 v[190:193], v169 offset:2048
	ds_read_b128 v[194:197], v169 offset:3072
	ds_read_b128 v[202:205], v169 offset:4096
	ds_read_b128 v[206:209], v169 offset:5120
	ds_read_b128 v[210:213], v169 offset:6144
	ds_read_b128 v[214:217], v169 offset:7168
	global_load_lds_dwordx4 v[198:199], off
	v_lshl_add_u64 v[198:199], s[4:5], 0, v[142:143]
	s_add_i32 m0, s68, 0xe000
	s_nop 0
	global_load_lds_dwordx4 v[198:199], off
	s_waitcnt vmcnt(8)
	s_waitcnt lgkmcnt(0)
	s_barrier
	s_setprio 1
	s_waitcnt lgkmcnt(0)
	v_mfma_i32_16x16x64_i8 v[126:129], v[148:151], v[182:185], v[126:129]
	v_mfma_i32_16x16x64_i8 v[122:125], v[156:159], v[182:185], v[122:125]
	v_mfma_i32_16x16x64_i8 v[118:121], v[148:151], v[190:193], v[118:121]
	v_mfma_i32_16x16x64_i8 v[114:117], v[156:159], v[190:193], v[114:117]
	v_mfma_i32_16x16x64_i8 v[106:109], v[148:151], v[202:205], v[106:109]
	v_mfma_i32_16x16x64_i8 v[98:101], v[156:159], v[202:205], v[98:101]
	v_mfma_i32_16x16x64_i8 v[90:93], v[148:151], v[210:213], v[90:93]
	v_mfma_i32_16x16x64_i8 v[82:85], v[156:159], v[210:213], v[82:85]
	v_mfma_i32_16x16x64_i8 v[126:129], v[152:155], v[186:189], v[126:129]
	v_mfma_i32_16x16x64_i8 v[122:125], v[160:163], v[186:189], v[122:125]
	v_mfma_i32_16x16x64_i8 v[118:121], v[152:155], v[194:197], v[118:121]
	v_mfma_i32_16x16x64_i8 v[114:117], v[160:163], v[194:197], v[114:117]
	v_mfma_i32_16x16x64_i8 v[106:109], v[152:155], v[206:209], v[106:109]
	v_mfma_i32_16x16x64_i8 v[98:101], v[160:163], v[206:209], v[98:101]
	v_mfma_i32_16x16x64_i8 v[90:93], v[152:155], v[214:217], v[90:93]
	v_mfma_i32_16x16x64_i8 v[82:85], v[160:163], v[214:217], v[82:85]
	s_setprio 0
	s_setprio 1
	v_mfma_i32_16x16x64_i8 v[110:113], v[164:167], v[182:185], v[110:113]
	v_mfma_i32_16x16x64_i8 v[102:105], v[174:177], v[182:185], v[102:105]
	v_mfma_i32_16x16x64_i8 v[94:97], v[164:167], v[190:193], v[94:97]
	v_mfma_i32_16x16x64_i8 v[86:89], v[174:177], v[190:193], v[86:89]
	v_mfma_i32_16x16x64_i8 v[78:81], v[164:167], v[202:205], v[78:81]
	v_mfma_i32_16x16x64_i8 v[74:77], v[174:177], v[202:205], v[74:77]
	v_mfma_i32_16x16x64_i8 v[70:73], v[164:167], v[210:213], v[70:73]
	v_mfma_i32_16x16x64_i8 v[66:69], v[174:177], v[210:213], v[66:69]
	v_mfma_i32_16x16x64_i8 v[110:113], v[170:173], v[186:189], v[110:113]
	v_mfma_i32_16x16x64_i8 v[102:105], v[178:181], v[186:189], v[102:105]
	v_mfma_i32_16x16x64_i8 v[94:97], v[170:173], v[194:197], v[94:97]
	v_mfma_i32_16x16x64_i8 v[86:89], v[178:181], v[194:197], v[86:89]
	v_mfma_i32_16x16x64_i8 v[78:81], v[170:173], v[206:209], v[78:81]
	v_mfma_i32_16x16x64_i8 v[74:77], v[178:181], v[206:209], v[74:77]
	v_mfma_i32_16x16x64_i8 v[70:73], v[170:173], v[214:217], v[70:73]
	v_mfma_i32_16x16x64_i8 v[66:69], v[178:181], v[214:217], v[66:69]
	s_setprio 0
	s_barrier
	s_add_i32 s47, s55, s67
	v_lshl_add_u64 v[198:199], s[50:51], 0, v[132:133]
	s_mov_b32 m0, s47
	ds_read_b128 v[182:185], v169 offset:16384
	ds_read_b128 v[186:189], v169 offset:17408
	ds_read_b128 v[190:193], v169 offset:18432
	ds_read_b128 v[194:197], v169 offset:19456
	ds_read_b128 v[202:205], v169 offset:20480
	ds_read_b128 v[206:209], v169 offset:21504
	ds_read_b128 v[210:213], v169 offset:22528
	ds_read_b128 v[214:217], v169 offset:23552
	global_load_lds_dwordx4 v[198:199], off
	s_add_i32 m0, s47, 0x2000
	v_lshl_add_u64 v[218:219], s[50:51], 0, v[136:137]
	s_add_u32 s50, s50, s22
	s_addc_u32 s51, s51, s23
	s_add_i32 s47, s76, s67
	global_load_lds_dwordx4 v[218:219], off
	v_lshl_add_u64 v[220:221], s[50:51], 0, v[132:133]
	s_mov_b32 m0, s47
	v_lshl_add_u64 v[222:223], s[50:51], 0, v[136:137]
	global_load_lds_dwordx4 v[220:221], off
	s_add_i32 m0, s47, 0x2000
	v_lshl_add_u64 v[224:225], s[6:7], 0, v[130:131]
	global_load_lds_dwordx4 v[222:223], off
	s_mov_b32 m0, s68
	v_lshl_add_u64 v[226:227], s[6:7], 0, v[134:135]
	global_load_lds_dwordx4 v[224:225], off
	s_mov_b32 m0, s69
	s_nop 0
	global_load_lds_dwordx4 v[226:227], off
	s_waitcnt vmcnt(8)
	s_waitcnt lgkmcnt(0)
	s_barrier
	s_setprio 1
	s_waitcnt lgkmcnt(0)
	v_mfma_i32_16x16x64_i8 v[62:65], v[148:151], v[182:185], v[62:65]
	v_mfma_i32_16x16x64_i8 v[58:61], v[156:159], v[182:185], v[58:61]
	v_mfma_i32_16x16x64_i8 v[54:57], v[148:151], v[190:193], v[54:57]
	v_mfma_i32_16x16x64_i8 v[50:53], v[156:159], v[190:193], v[50:53]
	v_mfma_i32_16x16x64_i8 v[42:45], v[148:151], v[202:205], v[42:45]
	v_mfma_i32_16x16x64_i8 v[34:37], v[156:159], v[202:205], v[34:37]
	v_mfma_i32_16x16x64_i8 v[26:29], v[148:151], v[210:213], v[26:29]
	v_mfma_i32_16x16x64_i8 v[18:21], v[156:159], v[210:213], v[18:21]
	v_mfma_i32_16x16x64_i8 v[62:65], v[152:155], v[186:189], v[62:65]
	v_mfma_i32_16x16x64_i8 v[58:61], v[160:163], v[186:189], v[58:61]
	v_mfma_i32_16x16x64_i8 v[54:57], v[152:155], v[194:197], v[54:57]
	v_mfma_i32_16x16x64_i8 v[50:53], v[160:163], v[194:197], v[50:53]
	v_mfma_i32_16x16x64_i8 v[42:45], v[152:155], v[206:209], v[42:45]
	v_mfma_i32_16x16x64_i8 v[34:37], v[160:163], v[206:209], v[34:37]
	v_mfma_i32_16x16x64_i8 v[26:29], v[152:155], v[214:217], v[26:29]
	v_mfma_i32_16x16x64_i8 v[18:21], v[160:163], v[214:217], v[18:21]
	s_setprio 0
	s_setprio 1
	v_mfma_i32_16x16x64_i8 v[46:49], v[164:167], v[182:185], v[46:49]
	v_mfma_i32_16x16x64_i8 v[38:41], v[174:177], v[182:185], v[38:41]
	v_mfma_i32_16x16x64_i8 v[30:33], v[164:167], v[190:193], v[30:33]
	v_mfma_i32_16x16x64_i8 v[22:25], v[174:177], v[190:193], v[22:25]
	v_mfma_i32_16x16x64_i8 v[14:17], v[164:167], v[202:205], v[14:17]
	v_mfma_i32_16x16x64_i8 v[10:13], v[174:177], v[202:205], v[10:13]
	v_mfma_i32_16x16x64_i8 v[6:9], v[164:167], v[210:213], v[6:9]
	v_mfma_i32_16x16x64_i8 v[2:5], v[174:177], v[210:213], v[2:5]
	v_mfma_i32_16x16x64_i8 v[46:49], v[170:173], v[186:189], v[46:49]
	v_mfma_i32_16x16x64_i8 v[38:41], v[178:181], v[186:189], v[38:41]
	v_mfma_i32_16x16x64_i8 v[30:33], v[170:173], v[194:197], v[30:33]
	v_mfma_i32_16x16x64_i8 v[22:25], v[178:181], v[194:197], v[22:25]
	v_mfma_i32_16x16x64_i8 v[14:17], v[170:173], v[206:209], v[14:17]
	v_mfma_i32_16x16x64_i8 v[10:13], v[178:181], v[206:209], v[10:13]
	v_mfma_i32_16x16x64_i8 v[6:9], v[170:173], v[214:217], v[6:9]
	v_mfma_i32_16x16x64_i8 v[2:5], v[178:181], v[214:217], v[2:5]
	s_setprio 0
	s_barrier
	s_add_i32 s47, 0, 0x18000
	v_add_u32_e32 v138, s47, v1
	s_add_i32 s49, 0, 0x1c000
	ds_read_b128 v[148:151], v138
	ds_read_b128 v[152:155], v138 offset:1024
	ds_read_b128 v[156:159], v138 offset:2048
	ds_read_b128 v[160:163], v138 offset:3072
	v_add_u32_e32 v138, s49, v1
	ds_read_b128 v[164:167], v138
	ds_read_b128 v[170:173], v138 offset:1024
	ds_read_b128 v[174:177], v138 offset:2048
	ds_read_b128 v[178:181], v138 offset:3072
	s_add_u32 s6, s6, s22
	s_addc_u32 s7, s7, s23
	s_mov_b32 m0, s70
	v_lshl_add_u64 v[228:229], s[6:7], 0, v[130:131]
	ds_read_b128 v[182:185], v169 offset:32768
	ds_read_b128 v[186:189], v169 offset:33792
	ds_read_b128 v[190:193], v169 offset:34816
	ds_read_b128 v[194:197], v169 offset:35840
	ds_read_b128 v[202:205], v169 offset:36864
	ds_read_b128 v[206:209], v169 offset:37888
	ds_read_b128 v[210:213], v169 offset:38912
	ds_read_b128 v[214:217], v169 offset:39936
	global_load_lds_dwordx4 v[228:229], off
	v_lshl_add_u64 v[228:229], s[6:7], 0, v[134:135]
	s_mov_b32 m0, s71
	s_nop 0
	global_load_lds_dwordx4 v[228:229], off
	s_waitcnt vmcnt(8)
	s_waitcnt lgkmcnt(0)
	s_barrier
	s_setprio 1
	s_waitcnt lgkmcnt(0)
	v_mfma_i32_16x16x64_i8 v[126:129], v[148:151], v[182:185], v[126:129]
	v_mfma_i32_16x16x64_i8 v[122:125], v[156:159], v[182:185], v[122:125]
	v_mfma_i32_16x16x64_i8 v[118:121], v[148:151], v[190:193], v[118:121]
	v_mfma_i32_16x16x64_i8 v[114:117], v[156:159], v[190:193], v[114:117]
	v_mfma_i32_16x16x64_i8 v[106:109], v[148:151], v[202:205], v[106:109]
	v_mfma_i32_16x16x64_i8 v[98:101], v[156:159], v[202:205], v[98:101]
	v_mfma_i32_16x16x64_i8 v[90:93], v[148:151], v[210:213], v[90:93]
	v_mfma_i32_16x16x64_i8 v[82:85], v[156:159], v[210:213], v[82:85]
	v_mfma_i32_16x16x64_i8 v[126:129], v[152:155], v[186:189], v[126:129]
	v_mfma_i32_16x16x64_i8 v[122:125], v[160:163], v[186:189], v[122:125]
	v_mfma_i32_16x16x64_i8 v[118:121], v[152:155], v[194:197], v[118:121]
	v_mfma_i32_16x16x64_i8 v[114:117], v[160:163], v[194:197], v[114:117]
	v_mfma_i32_16x16x64_i8 v[106:109], v[152:155], v[206:209], v[106:109]
	v_mfma_i32_16x16x64_i8 v[98:101], v[160:163], v[206:209], v[98:101]
	v_mfma_i32_16x16x64_i8 v[90:93], v[152:155], v[214:217], v[90:93]
	v_mfma_i32_16x16x64_i8 v[82:85], v[160:163], v[214:217], v[82:85]
	s_setprio 0
	s_setprio 1
	v_mfma_i32_16x16x64_i8 v[110:113], v[164:167], v[182:185], v[110:113]
	v_mfma_i32_16x16x64_i8 v[102:105], v[174:177], v[182:185], v[102:105]
	v_mfma_i32_16x16x64_i8 v[94:97], v[164:167], v[190:193], v[94:97]
	v_mfma_i32_16x16x64_i8 v[86:89], v[174:177], v[190:193], v[86:89]
	v_mfma_i32_16x16x64_i8 v[78:81], v[164:167], v[202:205], v[78:81]
	v_mfma_i32_16x16x64_i8 v[74:77], v[174:177], v[202:205], v[74:77]
	v_mfma_i32_16x16x64_i8 v[70:73], v[164:167], v[210:213], v[70:73]
	v_mfma_i32_16x16x64_i8 v[66:69], v[174:177], v[210:213], v[66:69]
	v_mfma_i32_16x16x64_i8 v[110:113], v[170:173], v[186:189], v[110:113]
	v_mfma_i32_16x16x64_i8 v[102:105], v[178:181], v[186:189], v[102:105]
	v_mfma_i32_16x16x64_i8 v[94:97], v[170:173], v[194:197], v[94:97]
	v_mfma_i32_16x16x64_i8 v[86:89], v[178:181], v[194:197], v[86:89]
	v_mfma_i32_16x16x64_i8 v[78:81], v[170:173], v[206:209], v[78:81]
	v_mfma_i32_16x16x64_i8 v[74:77], v[178:181], v[206:209], v[74:77]
	v_mfma_i32_16x16x64_i8 v[70:73], v[170:173], v[214:217], v[70:73]
	v_mfma_i32_16x16x64_i8 v[66:69], v[178:181], v[214:217], v[66:69]
	s_setprio 0
	s_barrier
	s_add_i32 s6, s47, s67
	v_lshl_add_u64 v[198:199], v[198:199], 0, s[34:35]
	s_mov_b32 m0, s6
	ds_read_b128 v[182:185], v169 offset:49152
	ds_read_b128 v[186:189], v169 offset:50176
	ds_read_b128 v[190:193], v169 offset:51200
	ds_read_b128 v[194:197], v169 offset:52224
	ds_read_b128 v[202:205], v169 offset:53248
	ds_read_b128 v[206:209], v169 offset:54272
	ds_read_b128 v[210:213], v169 offset:55296
	ds_read_b128 v[214:217], v169 offset:56320
	global_load_lds_dwordx4 v[198:199], off
	v_lshl_add_u64 v[198:199], v[218:219], 0, s[34:35]
	s_add_i32 m0, s6, 0x2000
	s_add_i32 s6, s49, s67
	global_load_lds_dwordx4 v[198:199], off
	v_lshl_add_u64 v[198:199], v[220:221], 0, s[34:35]
	s_mov_b32 m0, s6
	s_nop 0
	global_load_lds_dwordx4 v[198:199], off
	v_lshl_add_u64 v[198:199], v[222:223], 0, s[34:35]
	s_add_i32 m0, s6, 0x2000
	s_nop 0
	global_load_lds_dwordx4 v[198:199], off
	v_lshl_add_u64 v[198:199], v[224:225], 0, s[34:35]
	s_mov_b32 m0, s72
	s_nop 0
	global_load_lds_dwordx4 v[198:199], off
	v_lshl_add_u64 v[198:199], v[226:227], 0, s[34:35]
	s_mov_b32 m0, s73
	s_nop 0
	global_load_lds_dwordx4 v[198:199], off
	s_waitcnt vmcnt(8)
	s_waitcnt lgkmcnt(0)
	s_barrier
	s_setprio 1
	s_waitcnt lgkmcnt(0)
	v_mfma_i32_16x16x64_i8 v[62:65], v[148:151], v[182:185], v[62:65]
	v_mfma_i32_16x16x64_i8 v[58:61], v[156:159], v[182:185], v[58:61]
	v_mfma_i32_16x16x64_i8 v[54:57], v[148:151], v[190:193], v[54:57]
	v_mfma_i32_16x16x64_i8 v[50:53], v[156:159], v[190:193], v[50:53]
	v_mfma_i32_16x16x64_i8 v[42:45], v[148:151], v[202:205], v[42:45]
	v_mfma_i32_16x16x64_i8 v[34:37], v[156:159], v[202:205], v[34:37]
	v_mfma_i32_16x16x64_i8 v[26:29], v[148:151], v[210:213], v[26:29]
	v_mfma_i32_16x16x64_i8 v[18:21], v[156:159], v[210:213], v[18:21]
	v_mfma_i32_16x16x64_i8 v[62:65], v[152:155], v[186:189], v[62:65]
	v_mfma_i32_16x16x64_i8 v[58:61], v[160:163], v[186:189], v[58:61]
	v_mfma_i32_16x16x64_i8 v[54:57], v[152:155], v[194:197], v[54:57]
	v_mfma_i32_16x16x64_i8 v[50:53], v[160:163], v[194:197], v[50:53]
	v_mfma_i32_16x16x64_i8 v[42:45], v[152:155], v[206:209], v[42:45]
	v_mfma_i32_16x16x64_i8 v[34:37], v[160:163], v[206:209], v[34:37]
	v_mfma_i32_16x16x64_i8 v[26:29], v[152:155], v[214:217], v[26:29]
	v_mfma_i32_16x16x64_i8 v[18:21], v[160:163], v[214:217], v[18:21]
	s_setprio 0
	s_setprio 1
	v_mfma_i32_16x16x64_i8 v[46:49], v[164:167], v[182:185], v[46:49]
	v_mfma_i32_16x16x64_i8 v[38:41], v[174:177], v[182:185], v[38:41]
	v_mfma_i32_16x16x64_i8 v[30:33], v[164:167], v[190:193], v[30:33]
	v_mfma_i32_16x16x64_i8 v[22:25], v[174:177], v[190:193], v[22:25]
	v_mfma_i32_16x16x64_i8 v[14:17], v[164:167], v[202:205], v[14:17]
	v_mfma_i32_16x16x64_i8 v[10:13], v[174:177], v[202:205], v[10:13]
	v_mfma_i32_16x16x64_i8 v[6:9], v[164:167], v[210:213], v[6:9]
	v_mfma_i32_16x16x64_i8 v[2:5], v[174:177], v[210:213], v[2:5]
	v_mfma_i32_16x16x64_i8 v[46:49], v[170:173], v[186:189], v[46:49]
	v_mfma_i32_16x16x64_i8 v[38:41], v[178:181], v[186:189], v[38:41]
	v_mfma_i32_16x16x64_i8 v[30:33], v[170:173], v[194:197], v[30:33]
	v_mfma_i32_16x16x64_i8 v[22:25], v[178:181], v[194:197], v[22:25]
	v_mfma_i32_16x16x64_i8 v[14:17], v[170:173], v[206:209], v[14:17]
	v_mfma_i32_16x16x64_i8 v[10:13], v[178:181], v[206:209], v[10:13]
	v_mfma_i32_16x16x64_i8 v[6:9], v[170:173], v[214:217], v[6:9]
	v_mfma_i32_16x16x64_i8 v[2:5], v[178:181], v[214:217], v[2:5]
	s_setprio 0
	s_add_u32 s4, s4, 0x100
	s_addc_u32 s5, s5, 0
	s_add_u32 s44, s44, 0x100
	s_addc_u32 s45, s45, 0
	s_cmp_lt_i32 s46, s74
	s_mov_b32 s6, s46
	s_barrier
	s_cbranch_scc1 .LBB0_1513
	v_cvt_f32_i32_e32 v182, v126
	v_cvt_f32_i32_e32 v183, v127
	v_cvt_f32_i32_e32 v180, v128
	v_cvt_f32_i32_e32 v181, v129
	v_cvt_f32_i32_e32 v184, v122
	v_cvt_f32_i32_e32 v185, v123
	v_cvt_f32_i32_e32 v186, v124
	v_cvt_f32_i32_e32 v187, v125
	v_cvt_f32_i32_e32 v170, v110
	v_cvt_f32_i32_e32 v171, v111
	v_cvt_f32_i32_e32 v174, v112
	v_cvt_f32_i32_e32 v175, v113
	v_cvt_f32_i32_e32 v172, v102
	v_cvt_f32_i32_e32 v173, v103
	v_cvt_f32_i32_e32 v166, v104
	v_cvt_f32_i32_e32 v167, v105
	v_cvt_f32_i32_e32 v162, v118
	v_cvt_f32_i32_e32 v163, v119
	v_cvt_f32_i32_e32 v164, v120
	v_cvt_f32_i32_e32 v165, v121
	v_cvt_f32_i32_e32 v158, v114
	v_cvt_f32_i32_e32 v159, v115
	v_cvt_f32_i32_e32 v160, v116
	v_cvt_f32_i32_e32 v161, v117
	v_cvt_f32_i32_e32 v150, v94
	v_cvt_f32_i32_e32 v151, v95
	v_cvt_f32_i32_e32 v154, v96
	v_cvt_f32_i32_e32 v155, v97
	v_cvt_f32_i32_e32 v128, v86
	v_cvt_f32_i32_e32 v129, v87
	v_cvt_f32_i32_e32 v148, v88
	v_cvt_f32_i32_e32 v149, v89
	v_cvt_f32_i32_e32 v124, v106
	v_cvt_f32_i32_e32 v125, v107
	v_cvt_f32_i32_e32 v126, v108
	v_cvt_f32_i32_e32 v127, v109
	v_cvt_f32_i32_e32 v120, v98
	v_cvt_f32_i32_e32 v121, v99
	v_cvt_f32_i32_e32 v122, v100
	v_cvt_f32_i32_e32 v123, v101
	v_cvt_f32_i32_e32 v114, v78
	v_cvt_f32_i32_e32 v115, v79
	v_cvt_f32_i32_e32 v116, v80
	v_cvt_f32_i32_e32 v117, v81
	v_cvt_f32_i32_e32 v110, v74
	v_cvt_f32_i32_e32 v111, v75
	v_cvt_f32_i32_e32 v112, v76
	v_cvt_f32_i32_e32 v113, v77
	v_cvt_f32_i32_e32 v104, v90
	v_cvt_f32_i32_e32 v105, v91
	v_cvt_f32_i32_e32 v106, v92
	v_cvt_f32_i32_e32 v107, v93
	v_cvt_f32_i32_e32 v100, v82
	v_cvt_f32_i32_e32 v101, v83
	v_cvt_f32_i32_e32 v102, v84
	v_cvt_f32_i32_e32 v103, v85
	v_cvt_f32_i32_e32 v96, v70
	v_cvt_f32_i32_e32 v97, v71
	v_cvt_f32_i32_e32 v98, v72
	v_cvt_f32_i32_e32 v99, v73
	v_cvt_f32_i32_e32 v92, v66
	v_cvt_f32_i32_e32 v93, v67
	v_cvt_f32_i32_e32 v94, v68
	v_cvt_f32_i32_e32 v95, v69
	v_cvt_f32_i32_e32 v86, v62
	v_cvt_f32_i32_e32 v87, v63
	v_cvt_f32_i32_e32 v88, v64
	v_cvt_f32_i32_e32 v89, v65
	v_cvt_f32_i32_e32 v82, v58
	v_cvt_f32_i32_e32 v83, v59
	v_cvt_f32_i32_e32 v84, v60
	v_cvt_f32_i32_e32 v85, v61
	v_cvt_f32_i32_e32 v78, v46
	v_cvt_f32_i32_e32 v79, v47
	v_cvt_f32_i32_e32 v80, v48
	v_cvt_f32_i32_e32 v81, v49
	v_cvt_f32_i32_e32 v74, v38
	v_cvt_f32_i32_e32 v75, v39
	v_cvt_f32_i32_e32 v76, v40
	v_cvt_f32_i32_e32 v77, v41
	v_cvt_f32_i32_e32 v68, v54
	v_cvt_f32_i32_e32 v69, v55
	v_cvt_f32_i32_e32 v70, v56
	v_cvt_f32_i32_e32 v71, v57
	v_cvt_f32_i32_e32 v64, v50
	v_cvt_f32_i32_e32 v65, v51
	v_cvt_f32_i32_e32 v66, v52
	v_cvt_f32_i32_e32 v67, v53
	v_cvt_f32_i32_e32 v60, v30
	v_cvt_f32_i32_e32 v61, v31
	v_cvt_f32_i32_e32 v62, v32
	v_cvt_f32_i32_e32 v63, v33
	v_cvt_f32_i32_e32 v56, v22
	v_cvt_f32_i32_e32 v57, v23
	v_cvt_f32_i32_e32 v58, v24
	v_cvt_f32_i32_e32 v59, v25
	v_cvt_f32_i32_e32 v50, v42
	v_cvt_f32_i32_e32 v51, v43
	v_cvt_f32_i32_e32 v52, v44
	v_cvt_f32_i32_e32 v53, v45
	v_cvt_f32_i32_e32 v46, v34
	v_cvt_f32_i32_e32 v47, v35
	v_cvt_f32_i32_e32 v48, v36
	v_cvt_f32_i32_e32 v49, v37
	v_cvt_f32_i32_e32 v34, v14
	v_cvt_f32_i32_e32 v35, v15
	v_cvt_f32_i32_e32 v36, v16
	v_cvt_f32_i32_e32 v37, v17
	v_cvt_f32_i32_e32 v30, v10
	v_cvt_f32_i32_e32 v31, v11
	v_cvt_f32_i32_e32 v32, v12
	v_cvt_f32_i32_e32 v33, v13
	v_cvt_f32_i32_e32 v22, v26
	v_cvt_f32_i32_e32 v23, v27
	v_cvt_f32_i32_e32 v24, v28
	v_cvt_f32_i32_e32 v25, v29
	v_cvt_f32_i32_e32 v18, v18
	v_cvt_f32_i32_e32 v19, v19
	v_cvt_f32_i32_e32 v20, v20
	v_cvt_f32_i32_e32 v21, v21
	v_cvt_f32_i32_e32 v14, v6
	v_cvt_f32_i32_e32 v15, v7
	v_cvt_f32_i32_e32 v16, v8
	v_cvt_f32_i32_e32 v17, v9
	v_cvt_f32_i32_e32 v10, v2
	v_cvt_f32_i32_e32 v11, v3
	v_cvt_f32_i32_e32 v12, v4
	v_cvt_f32_i32_e32 v13, v5

.LBB0_1727:
	v_add_u32_e32 v150, s52, v1
	ds_read_b128 v[146:149], v150
	ds_read_b128 v[154:157], v150 offset:1024
	ds_read_b128 v[158:161], v150 offset:2048
	ds_read_b128 v[162:165], v150 offset:3072
	v_add_u32_e32 v150, s53, v1
	ds_read_b128 v[170:173], v150
	ds_read_b128 v[174:177], v150 offset:1024
	ds_read_b128 v[178:181], v150 offset:2048
	ds_read_b128 v[182:185], v150 offset:3072
	s_add_i32 s77, s48, 2
	s_add_u32 s78, s46, 0x80
	s_addc_u32 s49, s47, 0
	s_cmp_eq_u32 s72, s48
	s_cselect_b32 s48, s4, s78
	s_cselect_b32 s49, s5, s49
	s_cselect_b32 s79, s45, s76
	s_cselect_b32 s78, s44, s75
	v_lshl_add_u64 v[150:151], s[46:47], 0, v[138:139]
	s_add_i32 m0, s58, 0xc000
	ds_read_b128 v[186:189], v153
	ds_read_b128 v[190:193], v153 offset:1024
	ds_read_b128 v[194:197], v153 offset:2048
	ds_read_b128 v[198:201], v153 offset:3072
	ds_read_b128 v[202:205], v153 offset:4096
	ds_read_b128 v[206:209], v153 offset:5120
	ds_read_b128 v[210:213], v153 offset:6144
	ds_read_b128 v[214:217], v153 offset:7168
	global_load_lds_dwordx4 v[150:151], off
	v_lshl_add_u64 v[150:151], s[46:47], 0, v[140:141]
	s_add_i32 m0, s58, 0xe000
	s_nop 0
	global_load_lds_dwordx4 v[150:151], off
	s_waitcnt vmcnt(8)
	s_waitcnt lgkmcnt(0)
	s_barrier
	s_setprio 1
	s_waitcnt lgkmcnt(0)
	v_mfma_i32_16x16x64_i8 v[126:129], v[146:149], v[186:189], v[126:129]
	v_mfma_i32_16x16x64_i8 v[122:125], v[158:161], v[186:189], v[122:125]
	v_mfma_i32_16x16x64_i8 v[118:121], v[146:149], v[194:197], v[118:121]
	v_mfma_i32_16x16x64_i8 v[114:117], v[158:161], v[194:197], v[114:117]
	v_mfma_i32_16x16x64_i8 v[106:109], v[146:149], v[202:205], v[106:109]
	v_mfma_i32_16x16x64_i8 v[98:101], v[158:161], v[202:205], v[98:101]
	v_mfma_i32_16x16x64_i8 v[90:93], v[146:149], v[210:213], v[90:93]
	v_mfma_i32_16x16x64_i8 v[82:85], v[158:161], v[210:213], v[82:85]
	v_mfma_i32_16x16x64_i8 v[126:129], v[154:157], v[190:193], v[126:129]
	v_mfma_i32_16x16x64_i8 v[122:125], v[162:165], v[190:193], v[122:125]
	v_mfma_i32_16x16x64_i8 v[118:121], v[154:157], v[198:201], v[118:121]
	v_mfma_i32_16x16x64_i8 v[114:117], v[162:165], v[198:201], v[114:117]
	v_mfma_i32_16x16x64_i8 v[106:109], v[154:157], v[206:209], v[106:109]
	v_mfma_i32_16x16x64_i8 v[98:101], v[162:165], v[206:209], v[98:101]
	v_mfma_i32_16x16x64_i8 v[90:93], v[154:157], v[214:217], v[90:93]
	v_mfma_i32_16x16x64_i8 v[82:85], v[162:165], v[214:217], v[82:85]
	s_setprio 0
	s_setprio 1
	v_mfma_i32_16x16x64_i8 v[110:113], v[170:173], v[186:189], v[110:113]
	v_mfma_i32_16x16x64_i8 v[102:105], v[178:181], v[186:189], v[102:105]
	v_mfma_i32_16x16x64_i8 v[94:97], v[170:173], v[194:197], v[94:97]
	v_mfma_i32_16x16x64_i8 v[86:89], v[178:181], v[194:197], v[86:89]
	v_mfma_i32_16x16x64_i8 v[78:81], v[170:173], v[202:205], v[78:81]
	v_mfma_i32_16x16x64_i8 v[74:77], v[178:181], v[202:205], v[74:77]
	v_mfma_i32_16x16x64_i8 v[70:73], v[170:173], v[210:213], v[70:73]
	v_mfma_i32_16x16x64_i8 v[66:69], v[178:181], v[210:213], v[66:69]
	v_mfma_i32_16x16x64_i8 v[110:113], v[174:177], v[190:193], v[110:113]
	v_mfma_i32_16x16x64_i8 v[102:105], v[182:185], v[190:193], v[102:105]
	v_mfma_i32_16x16x64_i8 v[94:97], v[174:177], v[198:201], v[94:97]
	v_mfma_i32_16x16x64_i8 v[86:89], v[182:185], v[198:201], v[86:89]
	v_mfma_i32_16x16x64_i8 v[78:81], v[174:177], v[206:209], v[78:81]
	v_mfma_i32_16x16x64_i8 v[74:77], v[182:185], v[206:209], v[74:77]
	v_mfma_i32_16x16x64_i8 v[70:73], v[174:177], v[214:217], v[70:73]
	v_mfma_i32_16x16x64_i8 v[66:69], v[182:185], v[214:217], v[66:69]
	s_setprio 0
	s_barrier
	s_add_i32 s80, s52, s51
	v_lshl_add_u64 v[150:151], s[78:79], 0, v[134:135]
	s_mov_b32 m0, s80
	ds_read_b128 v[186:189], v153 offset:16384
	ds_read_b128 v[190:193], v153 offset:17408
	ds_read_b128 v[194:197], v153 offset:18432
	ds_read_b128 v[198:201], v153 offset:19456
	ds_read_b128 v[202:205], v153 offset:20480
	ds_read_b128 v[206:209], v153 offset:21504
	ds_read_b128 v[210:213], v153 offset:22528
	ds_read_b128 v[214:217], v153 offset:23552
	global_load_lds_dwordx4 v[150:151], off
	s_add_i32 m0, s80, 0x2000
	v_lshl_add_u64 v[166:167], s[78:79], 0, v[130:131]
	s_add_u32 s78, s78, s14
	s_addc_u32 s79, s79, s15
	s_add_i32 s80, s53, s51
	global_load_lds_dwordx4 v[166:167], off
	v_lshl_add_u64 v[218:219], s[78:79], 0, v[134:135]
	s_mov_b32 m0, s80
	v_lshl_add_u64 v[220:221], s[78:79], 0, v[130:131]
	global_load_lds_dwordx4 v[218:219], off
	s_add_i32 m0, s80, 0x2000
	v_lshl_add_u64 v[222:223], s[48:49], 0, v[136:137]
	global_load_lds_dwordx4 v[220:221], off
	s_mov_b32 m0, s58
	v_lshl_add_u64 v[224:225], s[48:49], 0, v[132:133]
	global_load_lds_dwordx4 v[222:223], off
	s_mov_b32 m0, s59
	s_nop 0
	global_load_lds_dwordx4 v[224:225], off
	s_waitcnt vmcnt(8)
	s_waitcnt lgkmcnt(0)
	s_barrier
	s_setprio 1
	s_waitcnt lgkmcnt(0)
	v_mfma_i32_16x16x64_i8 v[62:65], v[146:149], v[186:189], v[62:65]
	v_mfma_i32_16x16x64_i8 v[58:61], v[158:161], v[186:189], v[58:61]
	v_mfma_i32_16x16x64_i8 v[54:57], v[146:149], v[194:197], v[54:57]
	v_mfma_i32_16x16x64_i8 v[50:53], v[158:161], v[194:197], v[50:53]
	v_mfma_i32_16x16x64_i8 v[42:45], v[146:149], v[202:205], v[42:45]
	v_mfma_i32_16x16x64_i8 v[34:37], v[158:161], v[202:205], v[34:37]
	v_mfma_i32_16x16x64_i8 v[26:29], v[146:149], v[210:213], v[26:29]
	v_mfma_i32_16x16x64_i8 v[18:21], v[158:161], v[210:213], v[18:21]
	v_mfma_i32_16x16x64_i8 v[62:65], v[154:157], v[190:193], v[62:65]
	v_mfma_i32_16x16x64_i8 v[58:61], v[162:165], v[190:193], v[58:61]
	v_mfma_i32_16x16x64_i8 v[54:57], v[154:157], v[198:201], v[54:57]
	v_mfma_i32_16x16x64_i8 v[50:53], v[162:165], v[198:201], v[50:53]
	v_mfma_i32_16x16x64_i8 v[42:45], v[154:157], v[206:209], v[42:45]
	v_mfma_i32_16x16x64_i8 v[34:37], v[162:165], v[206:209], v[34:37]
	v_mfma_i32_16x16x64_i8 v[26:29], v[154:157], v[214:217], v[26:29]
	v_mfma_i32_16x16x64_i8 v[18:21], v[162:165], v[214:217], v[18:21]
	s_setprio 0
	s_setprio 1
	v_mfma_i32_16x16x64_i8 v[46:49], v[170:173], v[186:189], v[46:49]
	v_mfma_i32_16x16x64_i8 v[38:41], v[178:181], v[186:189], v[38:41]
	v_mfma_i32_16x16x64_i8 v[30:33], v[170:173], v[194:197], v[30:33]
	v_mfma_i32_16x16x64_i8 v[22:25], v[178:181], v[194:197], v[22:25]
	v_mfma_i32_16x16x64_i8 v[14:17], v[170:173], v[202:205], v[14:17]
	v_mfma_i32_16x16x64_i8 v[10:13], v[178:181], v[202:205], v[10:13]
	v_mfma_i32_16x16x64_i8 v[6:9], v[170:173], v[210:213], v[6:9]
	v_mfma_i32_16x16x64_i8 v[2:5], v[178:181], v[210:213], v[2:5]
	v_mfma_i32_16x16x64_i8 v[46:49], v[174:177], v[190:193], v[46:49]
	v_mfma_i32_16x16x64_i8 v[38:41], v[182:185], v[190:193], v[38:41]
	v_mfma_i32_16x16x64_i8 v[30:33], v[174:177], v[198:201], v[30:33]
	v_mfma_i32_16x16x64_i8 v[22:25], v[182:185], v[198:201], v[22:25]
	v_mfma_i32_16x16x64_i8 v[14:17], v[174:177], v[206:209], v[14:17]
	v_mfma_i32_16x16x64_i8 v[10:13], v[182:185], v[206:209], v[10:13]
	v_mfma_i32_16x16x64_i8 v[6:9], v[174:177], v[214:217], v[6:9]
	v_mfma_i32_16x16x64_i8 v[2:5], v[182:185], v[214:217], v[2:5]
	s_setprio 0
	s_barrier
	s_add_i32 s78, 0, 0x18000
	v_add_u32_e32 v152, s78, v1
	s_add_i32 s79, 0, 0x1c000
	ds_read_b128 v[146:149], v152
	ds_read_b128 v[154:157], v152 offset:1024
	ds_read_b128 v[158:161], v152 offset:2048
	ds_read_b128 v[162:165], v152 offset:3072
	v_add_u32_e32 v152, s79, v1
	ds_read_b128 v[170:173], v152
	ds_read_b128 v[174:177], v152 offset:1024
	ds_read_b128 v[178:181], v152 offset:2048
	ds_read_b128 v[182:185], v152 offset:3072
	s_add_u32 s48, s48, s14
	s_addc_u32 s49, s49, s15
	s_mov_b32 m0, s62
	v_lshl_add_u64 v[226:227], s[48:49], 0, v[136:137]
	ds_read_b128 v[186:189], v153 offset:32768
	ds_read_b128 v[190:193], v153 offset:33792
	ds_read_b128 v[194:197], v153 offset:34816
	ds_read_b128 v[198:201], v153 offset:35840
	ds_read_b128 v[202:205], v153 offset:36864
	ds_read_b128 v[206:209], v153 offset:37888
	ds_read_b128 v[210:213], v153 offset:38912
	ds_read_b128 v[214:217], v153 offset:39936
	global_load_lds_dwordx4 v[226:227], off
	v_lshl_add_u64 v[226:227], s[48:49], 0, v[132:133]
	s_mov_b32 m0, s63
	s_nop 0
	global_load_lds_dwordx4 v[226:227], off
	s_waitcnt vmcnt(8)
	s_waitcnt lgkmcnt(0)
	s_barrier
	s_setprio 1
	s_waitcnt lgkmcnt(0)
	v_mfma_i32_16x16x64_i8 v[126:129], v[146:149], v[186:189], v[126:129]
	v_mfma_i32_16x16x64_i8 v[122:125], v[158:161], v[186:189], v[122:125]
	v_mfma_i32_16x16x64_i8 v[118:121], v[146:149], v[194:197], v[118:121]
	v_mfma_i32_16x16x64_i8 v[114:117], v[158:161], v[194:197], v[114:117]
	v_mfma_i32_16x16x64_i8 v[106:109], v[146:149], v[202:205], v[106:109]
	v_mfma_i32_16x16x64_i8 v[98:101], v[158:161], v[202:205], v[98:101]
	v_mfma_i32_16x16x64_i8 v[90:93], v[146:149], v[210:213], v[90:93]
	v_mfma_i32_16x16x64_i8 v[82:85], v[158:161], v[210:213], v[82:85]
	v_mfma_i32_16x16x64_i8 v[126:129], v[154:157], v[190:193], v[126:129]
	v_mfma_i32_16x16x64_i8 v[122:125], v[162:165], v[190:193], v[122:125]
	v_mfma_i32_16x16x64_i8 v[118:121], v[154:157], v[198:201], v[118:121]
	v_mfma_i32_16x16x64_i8 v[114:117], v[162:165], v[198:201], v[114:117]
	v_mfma_i32_16x16x64_i8 v[106:109], v[154:157], v[206:209], v[106:109]
	v_mfma_i32_16x16x64_i8 v[98:101], v[162:165], v[206:209], v[98:101]
	v_mfma_i32_16x16x64_i8 v[90:93], v[154:157], v[214:217], v[90:93]
	v_mfma_i32_16x16x64_i8 v[82:85], v[162:165], v[214:217], v[82:85]
	s_setprio 0
	s_setprio 1
	v_mfma_i32_16x16x64_i8 v[110:113], v[170:173], v[186:189], v[110:113]
	v_mfma_i32_16x16x64_i8 v[102:105], v[178:181], v[186:189], v[102:105]
	v_mfma_i32_16x16x64_i8 v[94:97], v[170:173], v[194:197], v[94:97]
	v_mfma_i32_16x16x64_i8 v[86:89], v[178:181], v[194:197], v[86:89]
	v_mfma_i32_16x16x64_i8 v[78:81], v[170:173], v[202:205], v[78:81]
	v_mfma_i32_16x16x64_i8 v[74:77], v[178:181], v[202:205], v[74:77]
	v_mfma_i32_16x16x64_i8 v[70:73], v[170:173], v[210:213], v[70:73]
	v_mfma_i32_16x16x64_i8 v[66:69], v[178:181], v[210:213], v[66:69]
	v_mfma_i32_16x16x64_i8 v[110:113], v[174:177], v[190:193], v[110:113]
	v_mfma_i32_16x16x64_i8 v[102:105], v[182:185], v[190:193], v[102:105]
	v_mfma_i32_16x16x64_i8 v[94:97], v[174:177], v[198:201], v[94:97]
	v_mfma_i32_16x16x64_i8 v[86:89], v[182:185], v[198:201], v[86:89]
	v_mfma_i32_16x16x64_i8 v[78:81], v[174:177], v[206:209], v[78:81]
	v_mfma_i32_16x16x64_i8 v[74:77], v[182:185], v[206:209], v[74:77]
	v_mfma_i32_16x16x64_i8 v[70:73], v[174:177], v[214:217], v[70:73]
	v_mfma_i32_16x16x64_i8 v[66:69], v[182:185], v[214:217], v[66:69]
	s_setprio 0
	s_barrier
	s_add_i32 s48, s78, s51
	v_lshl_add_u64 v[150:151], v[150:151], 0, s[24:25]
	s_mov_b32 m0, s48
	ds_read_b128 v[186:189], v153 offset:49152
	ds_read_b128 v[190:193], v153 offset:50176
	ds_read_b128 v[194:197], v153 offset:51200
	ds_read_b128 v[198:201], v153 offset:52224
	ds_read_b128 v[202:205], v153 offset:53248
	ds_read_b128 v[206:209], v153 offset:54272
	ds_read_b128 v[210:213], v153 offset:55296
	ds_read_b128 v[214:217], v153 offset:56320
	global_load_lds_dwordx4 v[150:151], off
	v_lshl_add_u64 v[150:151], v[166:167], 0, s[24:25]
	s_add_i32 m0, s48, 0x2000
	s_add_i32 s48, s79, s51
	global_load_lds_dwordx4 v[150:151], off
	v_lshl_add_u64 v[150:151], v[218:219], 0, s[24:25]
	s_mov_b32 m0, s48
	s_nop 0
	global_load_lds_dwordx4 v[150:151], off
	v_lshl_add_u64 v[150:151], v[220:221], 0, s[24:25]
	s_add_i32 m0, s48, 0x2000
	s_nop 0
	global_load_lds_dwordx4 v[150:151], off
	v_lshl_add_u64 v[150:151], v[222:223], 0, s[24:25]
	s_mov_b32 m0, s67
	s_nop 0
	global_load_lds_dwordx4 v[150:151], off
	v_lshl_add_u64 v[150:151], v[224:225], 0, s[24:25]
	s_mov_b32 m0, s68
	s_nop 0
	global_load_lds_dwordx4 v[150:151], off
	s_waitcnt vmcnt(8)
	s_waitcnt lgkmcnt(0)
	s_barrier
	s_setprio 1
	s_waitcnt lgkmcnt(0)
	v_mfma_i32_16x16x64_i8 v[62:65], v[146:149], v[186:189], v[62:65]
	v_mfma_i32_16x16x64_i8 v[58:61], v[158:161], v[186:189], v[58:61]
	v_mfma_i32_16x16x64_i8 v[54:57], v[146:149], v[194:197], v[54:57]
	v_mfma_i32_16x16x64_i8 v[50:53], v[158:161], v[194:197], v[50:53]
	v_mfma_i32_16x16x64_i8 v[42:45], v[146:149], v[202:205], v[42:45]
	v_mfma_i32_16x16x64_i8 v[34:37], v[158:161], v[202:205], v[34:37]
	v_mfma_i32_16x16x64_i8 v[26:29], v[146:149], v[210:213], v[26:29]
	v_mfma_i32_16x16x64_i8 v[18:21], v[158:161], v[210:213], v[18:21]
	v_mfma_i32_16x16x64_i8 v[62:65], v[154:157], v[190:193], v[62:65]
	v_mfma_i32_16x16x64_i8 v[58:61], v[162:165], v[190:193], v[58:61]
	v_mfma_i32_16x16x64_i8 v[54:57], v[154:157], v[198:201], v[54:57]
	v_mfma_i32_16x16x64_i8 v[50:53], v[162:165], v[198:201], v[50:53]
	v_mfma_i32_16x16x64_i8 v[42:45], v[154:157], v[206:209], v[42:45]
	v_mfma_i32_16x16x64_i8 v[34:37], v[162:165], v[206:209], v[34:37]
	v_mfma_i32_16x16x64_i8 v[26:29], v[154:157], v[214:217], v[26:29]
	v_mfma_i32_16x16x64_i8 v[18:21], v[162:165], v[214:217], v[18:21]
	s_setprio 0
	s_setprio 1
	v_mfma_i32_16x16x64_i8 v[46:49], v[170:173], v[186:189], v[46:49]
	v_mfma_i32_16x16x64_i8 v[38:41], v[178:181], v[186:189], v[38:41]
	v_mfma_i32_16x16x64_i8 v[30:33], v[170:173], v[194:197], v[30:33]
	v_mfma_i32_16x16x64_i8 v[22:25], v[178:181], v[194:197], v[22:25]
	v_mfma_i32_16x16x64_i8 v[14:17], v[170:173], v[202:205], v[14:17]
	v_mfma_i32_16x16x64_i8 v[10:13], v[178:181], v[202:205], v[10:13]
	v_mfma_i32_16x16x64_i8 v[6:9], v[170:173], v[210:213], v[6:9]
	v_mfma_i32_16x16x64_i8 v[2:5], v[178:181], v[210:213], v[2:5]
	v_mfma_i32_16x16x64_i8 v[46:49], v[174:177], v[190:193], v[46:49]
	v_mfma_i32_16x16x64_i8 v[38:41], v[182:185], v[190:193], v[38:41]
	v_mfma_i32_16x16x64_i8 v[30:33], v[174:177], v[198:201], v[30:33]
	v_mfma_i32_16x16x64_i8 v[22:25], v[182:185], v[198:201], v[22:25]
	v_mfma_i32_16x16x64_i8 v[14:17], v[174:177], v[206:209], v[14:17]
	v_mfma_i32_16x16x64_i8 v[10:13], v[182:185], v[206:209], v[10:13]
	v_mfma_i32_16x16x64_i8 v[6:9], v[174:177], v[214:217], v[6:9]
	v_mfma_i32_16x16x64_i8 v[2:5], v[182:185], v[214:217], v[2:5]
	s_setprio 0
	s_add_u32 s46, s46, 0x100
	s_addc_u32 s47, s47, 0
	s_add_u32 s75, s75, 0x100
	s_addc_u32 s76, s76, 0
	s_cmp_ge_i32 s77, s69
	s_mov_b32 s48, s77
	s_barrier
	s_cbranch_scc0 .LBB0_1727
	v_cvt_f32_i32_e32 v180, v126
	v_cvt_f32_i32_e32 v181, v127
	v_cvt_f32_i32_e32 v178, v128
	v_cvt_f32_i32_e32 v179, v129
	v_cvt_f32_i32_e32 v182, v122
	v_cvt_f32_i32_e32 v183, v123
	v_cvt_f32_i32_e32 v184, v124
	v_cvt_f32_i32_e32 v185, v125
	v_cvt_f32_i32_e32 v164, v110
	v_cvt_f32_i32_e32 v165, v111
	v_cvt_f32_i32_e32 v166, v112
	v_cvt_f32_i32_e32 v167, v113
	v_cvt_f32_i32_e32 v170, v102
	v_cvt_f32_i32_e32 v171, v103
	v_cvt_f32_i32_e32 v172, v104
	v_cvt_f32_i32_e32 v173, v105
	v_cvt_f32_i32_e32 v156, v118
	v_cvt_f32_i32_e32 v157, v119
	v_cvt_f32_i32_e32 v158, v120
	v_cvt_f32_i32_e32 v159, v121
	v_cvt_f32_i32_e32 v160, v114
	v_cvt_f32_i32_e32 v161, v115
	v_cvt_f32_i32_e32 v162, v116
	v_cvt_f32_i32_e32 v163, v117
	v_cvt_f32_i32_e32 v126, v94
	v_cvt_f32_i32_e32 v127, v95
	v_cvt_f32_i32_e32 v128, v96
	v_cvt_f32_i32_e32 v129, v97
	v_cvt_f32_i32_e32 v146, v86
	v_cvt_f32_i32_e32 v147, v87
	v_cvt_f32_i32_e32 v148, v88
	v_cvt_f32_i32_e32 v149, v89
	v_cvt_f32_i32_e32 v118, v106
	v_cvt_f32_i32_e32 v119, v107
	v_cvt_f32_i32_e32 v120, v108
	v_cvt_f32_i32_e32 v121, v109
	v_cvt_f32_i32_e32 v122, v98
	v_cvt_f32_i32_e32 v123, v99
	v_cvt_f32_i32_e32 v124, v100
	v_cvt_f32_i32_e32 v125, v101
	v_cvt_f32_i32_e32 v108, v78
	v_cvt_f32_i32_e32 v109, v79
	v_cvt_f32_i32_e32 v110, v80
	v_cvt_f32_i32_e32 v111, v81
	v_cvt_f32_i32_e32 v112, v74
	v_cvt_f32_i32_e32 v113, v75
	v_cvt_f32_i32_e32 v114, v76
	v_cvt_f32_i32_e32 v115, v77
	v_cvt_f32_i32_e32 v100, v90
	v_cvt_f32_i32_e32 v101, v91
	v_cvt_f32_i32_e32 v102, v92
	v_cvt_f32_i32_e32 v103, v93
	v_cvt_f32_i32_e32 v104, v82
	v_cvt_f32_i32_e32 v105, v83
	v_cvt_f32_i32_e32 v106, v84
	v_cvt_f32_i32_e32 v107, v85
	v_cvt_f32_i32_e32 v90, v70
	v_cvt_f32_i32_e32 v91, v71
	v_cvt_f32_i32_e32 v92, v72
	v_cvt_f32_i32_e32 v93, v73
	v_cvt_f32_i32_e32 v94, v66
	v_cvt_f32_i32_e32 v95, v67
	v_cvt_f32_i32_e32 v96, v68
	v_cvt_f32_i32_e32 v97, v69
	v_cvt_f32_i32_e32 v82, v62
	v_cvt_f32_i32_e32 v83, v63
	v_cvt_f32_i32_e32 v84, v64
	v_cvt_f32_i32_e32 v85, v65
	v_cvt_f32_i32_e32 v86, v58
	v_cvt_f32_i32_e32 v87, v59
	v_cvt_f32_i32_e32 v88, v60
	v_cvt_f32_i32_e32 v89, v61
	v_cvt_f32_i32_e32 v72, v46
	v_cvt_f32_i32_e32 v73, v47
	v_cvt_f32_i32_e32 v74, v48
	v_cvt_f32_i32_e32 v75, v49
	v_cvt_f32_i32_e32 v76, v38
	v_cvt_f32_i32_e32 v77, v39
	v_cvt_f32_i32_e32 v78, v40
	v_cvt_f32_i32_e32 v79, v41
	v_cvt_f32_i32_e32 v64, v54
	v_cvt_f32_i32_e32 v65, v55
	v_cvt_f32_i32_e32 v66, v56
	v_cvt_f32_i32_e32 v67, v57
	v_cvt_f32_i32_e32 v68, v50
	v_cvt_f32_i32_e32 v69, v51
	v_cvt_f32_i32_e32 v70, v52
	v_cvt_f32_i32_e32 v71, v53
	v_cvt_f32_i32_e32 v54, v30
	v_cvt_f32_i32_e32 v55, v31
	v_cvt_f32_i32_e32 v56, v32
	v_cvt_f32_i32_e32 v57, v33
	v_cvt_f32_i32_e32 v58, v22
	v_cvt_f32_i32_e32 v59, v23
	v_cvt_f32_i32_e32 v60, v24
	v_cvt_f32_i32_e32 v61, v25
	v_cvt_f32_i32_e32 v46, v42
	v_cvt_f32_i32_e32 v47, v43
	v_cvt_f32_i32_e32 v48, v44
	v_cvt_f32_i32_e32 v49, v45
	v_cvt_f32_i32_e32 v50, v34
	v_cvt_f32_i32_e32 v51, v35
	v_cvt_f32_i32_e32 v52, v36
	v_cvt_f32_i32_e32 v53, v37
	v_cvt_f32_i32_e32 v34, v14
	v_cvt_f32_i32_e32 v35, v15
	v_cvt_f32_i32_e32 v36, v16
	v_cvt_f32_i32_e32 v37, v17
	v_cvt_f32_i32_e32 v38, v10
	v_cvt_f32_i32_e32 v39, v11
	v_cvt_f32_i32_e32 v40, v12
	v_cvt_f32_i32_e32 v41, v13
	v_cvt_f32_i32_e32 v26, v26
	v_cvt_f32_i32_e32 v27, v27
	v_cvt_f32_i32_e32 v28, v28
	v_cvt_f32_i32_e32 v29, v29
	v_cvt_f32_i32_e32 v30, v18
	v_cvt_f32_i32_e32 v31, v19
	v_cvt_f32_i32_e32 v32, v20
	v_cvt_f32_i32_e32 v33, v21
	v_cvt_f32_i32_e32 v18, v6
	v_cvt_f32_i32_e32 v19, v7
	v_cvt_f32_i32_e32 v20, v8
	v_cvt_f32_i32_e32 v21, v9
	v_cvt_f32_i32_e32 v22, v2
	v_cvt_f32_i32_e32 v23, v3
	v_cvt_f32_i32_e32 v24, v4
	v_cvt_f32_i32_e32 v25, v5
	v_readlane_b32 s77, v237, 59

.LBB0_1751:
	v_add_u32_e32 v158, s58, v1
	ds_read_b128 v[146:149], v158
	ds_read_b128 v[150:153], v158 offset:1024
	ds_read_b128 v[154:157], v158 offset:2048
	ds_read_b128 v[162:165], v158 offset:3072
	v_add_u32_e32 v158, s59, v1
	ds_read_b128 v[170:173], v158
	ds_read_b128 v[174:177], v158 offset:1024
	ds_read_b128 v[178:181], v158 offset:2048
	ds_read_b128 v[182:185], v158 offset:3072
	s_add_i32 s68, s38, 2
	s_add_u32 s69, s36, 0x80
	s_addc_u32 s39, s37, 0
	s_cmp_eq_u32 s55, s38
	s_cselect_b32 s38, s2, s69
	s_cselect_b32 s39, s3, s39
	s_cselect_b32 s71, s35, s67
	s_cselect_b32 s70, s34, s66
	v_lshl_add_u64 v[158:159], s[36:37], 0, v[138:139]
	s_add_i32 m0, s43, 0xc000
	ds_read_b128 v[186:189], v161
	ds_read_b128 v[190:193], v161 offset:1024
	ds_read_b128 v[194:197], v161 offset:2048
	ds_read_b128 v[198:201], v161 offset:3072
	ds_read_b128 v[202:205], v161 offset:4096
	ds_read_b128 v[206:209], v161 offset:5120
	ds_read_b128 v[210:213], v161 offset:6144
	ds_read_b128 v[214:217], v161 offset:7168
	global_load_lds_dwordx4 v[158:159], off
	v_lshl_add_u64 v[158:159], s[36:37], 0, v[140:141]
	s_add_i32 m0, s43, 0xe000
	s_nop 0
	global_load_lds_dwordx4 v[158:159], off
	s_waitcnt vmcnt(8)
	s_waitcnt lgkmcnt(0)
	s_barrier
	s_setprio 1
	s_waitcnt lgkmcnt(0)
	v_mfma_i32_16x16x64_i8 v[126:129], v[146:149], v[186:189], v[126:129]
	v_mfma_i32_16x16x64_i8 v[122:125], v[154:157], v[186:189], v[122:125]
	v_mfma_i32_16x16x64_i8 v[118:121], v[146:149], v[194:197], v[118:121]
	v_mfma_i32_16x16x64_i8 v[114:117], v[154:157], v[194:197], v[114:117]
	v_mfma_i32_16x16x64_i8 v[106:109], v[146:149], v[202:205], v[106:109]
	v_mfma_i32_16x16x64_i8 v[98:101], v[154:157], v[202:205], v[98:101]
	v_mfma_i32_16x16x64_i8 v[90:93], v[146:149], v[210:213], v[90:93]
	v_mfma_i32_16x16x64_i8 v[82:85], v[154:157], v[210:213], v[82:85]
	v_mfma_i32_16x16x64_i8 v[126:129], v[150:153], v[190:193], v[126:129]
	v_mfma_i32_16x16x64_i8 v[122:125], v[162:165], v[190:193], v[122:125]
	v_mfma_i32_16x16x64_i8 v[118:121], v[150:153], v[198:201], v[118:121]
	v_mfma_i32_16x16x64_i8 v[114:117], v[162:165], v[198:201], v[114:117]
	v_mfma_i32_16x16x64_i8 v[106:109], v[150:153], v[206:209], v[106:109]
	v_mfma_i32_16x16x64_i8 v[98:101], v[162:165], v[206:209], v[98:101]
	v_mfma_i32_16x16x64_i8 v[90:93], v[150:153], v[214:217], v[90:93]
	v_mfma_i32_16x16x64_i8 v[82:85], v[162:165], v[214:217], v[82:85]
	s_setprio 0
	s_setprio 1
	v_mfma_i32_16x16x64_i8 v[110:113], v[170:173], v[186:189], v[110:113]
	v_mfma_i32_16x16x64_i8 v[102:105], v[178:181], v[186:189], v[102:105]
	v_mfma_i32_16x16x64_i8 v[94:97], v[170:173], v[194:197], v[94:97]
	v_mfma_i32_16x16x64_i8 v[86:89], v[178:181], v[194:197], v[86:89]
	v_mfma_i32_16x16x64_i8 v[78:81], v[170:173], v[202:205], v[78:81]
	v_mfma_i32_16x16x64_i8 v[74:77], v[178:181], v[202:205], v[74:77]
	v_mfma_i32_16x16x64_i8 v[70:73], v[170:173], v[210:213], v[70:73]
	v_mfma_i32_16x16x64_i8 v[66:69], v[178:181], v[210:213], v[66:69]
	v_mfma_i32_16x16x64_i8 v[110:113], v[174:177], v[190:193], v[110:113]
	v_mfma_i32_16x16x64_i8 v[102:105], v[182:185], v[190:193], v[102:105]
	v_mfma_i32_16x16x64_i8 v[94:97], v[174:177], v[198:201], v[94:97]
	v_mfma_i32_16x16x64_i8 v[86:89], v[182:185], v[198:201], v[86:89]
	v_mfma_i32_16x16x64_i8 v[78:81], v[174:177], v[206:209], v[78:81]
	v_mfma_i32_16x16x64_i8 v[74:77], v[182:185], v[206:209], v[74:77]
	v_mfma_i32_16x16x64_i8 v[70:73], v[174:177], v[214:217], v[70:73]
	v_mfma_i32_16x16x64_i8 v[66:69], v[182:185], v[214:217], v[66:69]
	s_setprio 0
	s_barrier
	s_add_i32 s69, s58, s42
	v_lshl_add_u64 v[158:159], s[70:71], 0, v[132:133]
	s_mov_b32 m0, s69
	ds_read_b128 v[186:189], v161 offset:16384
	ds_read_b128 v[190:193], v161 offset:17408
	ds_read_b128 v[194:197], v161 offset:18432
	ds_read_b128 v[198:201], v161 offset:19456
	ds_read_b128 v[202:205], v161 offset:20480
	ds_read_b128 v[206:209], v161 offset:21504
	ds_read_b128 v[210:213], v161 offset:22528
	ds_read_b128 v[214:217], v161 offset:23552
	global_load_lds_dwordx4 v[158:159], off
	s_add_i32 m0, s69, 0x2000
	v_lshl_add_u64 v[166:167], s[70:71], 0, v[136:137]
	s_add_u32 s70, s70, s4
	s_addc_u32 s71, s71, s5
	s_add_i32 s69, s59, s42
	global_load_lds_dwordx4 v[166:167], off
	v_lshl_add_u64 v[218:219], s[70:71], 0, v[132:133]
	s_mov_b32 m0, s69
	v_lshl_add_u64 v[220:221], s[70:71], 0, v[136:137]
	global_load_lds_dwordx4 v[218:219], off
	s_add_i32 m0, s69, 0x2000
	v_lshl_add_u64 v[222:223], s[38:39], 0, v[130:131]
	global_load_lds_dwordx4 v[220:221], off
	s_mov_b32 m0, s43
	v_lshl_add_u64 v[224:225], s[38:39], 0, v[134:135]
	global_load_lds_dwordx4 v[222:223], off
	s_mov_b32 m0, s44
	s_nop 0
	global_load_lds_dwordx4 v[224:225], off
	s_waitcnt vmcnt(8)
	s_waitcnt lgkmcnt(0)
	s_barrier
	s_setprio 1
	s_waitcnt lgkmcnt(0)
	v_mfma_i32_16x16x64_i8 v[62:65], v[146:149], v[186:189], v[62:65]
	v_mfma_i32_16x16x64_i8 v[58:61], v[154:157], v[186:189], v[58:61]
	v_mfma_i32_16x16x64_i8 v[54:57], v[146:149], v[194:197], v[54:57]
	v_mfma_i32_16x16x64_i8 v[50:53], v[154:157], v[194:197], v[50:53]
	v_mfma_i32_16x16x64_i8 v[42:45], v[146:149], v[202:205], v[42:45]
	v_mfma_i32_16x16x64_i8 v[34:37], v[154:157], v[202:205], v[34:37]
	v_mfma_i32_16x16x64_i8 v[26:29], v[146:149], v[210:213], v[26:29]
	v_mfma_i32_16x16x64_i8 v[18:21], v[154:157], v[210:213], v[18:21]
	v_mfma_i32_16x16x64_i8 v[62:65], v[150:153], v[190:193], v[62:65]
	v_mfma_i32_16x16x64_i8 v[58:61], v[162:165], v[190:193], v[58:61]
	v_mfma_i32_16x16x64_i8 v[54:57], v[150:153], v[198:201], v[54:57]
	v_mfma_i32_16x16x64_i8 v[50:53], v[162:165], v[198:201], v[50:53]
	v_mfma_i32_16x16x64_i8 v[42:45], v[150:153], v[206:209], v[42:45]
	v_mfma_i32_16x16x64_i8 v[34:37], v[162:165], v[206:209], v[34:37]
	v_mfma_i32_16x16x64_i8 v[26:29], v[150:153], v[214:217], v[26:29]
	v_mfma_i32_16x16x64_i8 v[18:21], v[162:165], v[214:217], v[18:21]
	s_setprio 0
	s_setprio 1
	v_mfma_i32_16x16x64_i8 v[46:49], v[170:173], v[186:189], v[46:49]
	v_mfma_i32_16x16x64_i8 v[38:41], v[178:181], v[186:189], v[38:41]
	v_mfma_i32_16x16x64_i8 v[30:33], v[170:173], v[194:197], v[30:33]
	v_mfma_i32_16x16x64_i8 v[22:25], v[178:181], v[194:197], v[22:25]
	v_mfma_i32_16x16x64_i8 v[14:17], v[170:173], v[202:205], v[14:17]
	v_mfma_i32_16x16x64_i8 v[10:13], v[178:181], v[202:205], v[10:13]
	v_mfma_i32_16x16x64_i8 v[6:9], v[170:173], v[210:213], v[6:9]
	v_mfma_i32_16x16x64_i8 v[2:5], v[178:181], v[210:213], v[2:5]
	v_mfma_i32_16x16x64_i8 v[46:49], v[174:177], v[190:193], v[46:49]
	v_mfma_i32_16x16x64_i8 v[38:41], v[182:185], v[190:193], v[38:41]
	v_mfma_i32_16x16x64_i8 v[30:33], v[174:177], v[198:201], v[30:33]
	v_mfma_i32_16x16x64_i8 v[22:25], v[182:185], v[198:201], v[22:25]
	v_mfma_i32_16x16x64_i8 v[14:17], v[174:177], v[206:209], v[14:17]
	v_mfma_i32_16x16x64_i8 v[10:13], v[182:185], v[206:209], v[10:13]
	v_mfma_i32_16x16x64_i8 v[6:9], v[174:177], v[214:217], v[6:9]
	v_mfma_i32_16x16x64_i8 v[2:5], v[182:185], v[214:217], v[2:5]
	s_setprio 0
	s_barrier
	s_add_i32 s69, 0, 0x18000
	v_add_u32_e32 v160, s69, v1
	s_add_i32 s70, 0, 0x1c000
	ds_read_b128 v[146:149], v160
	ds_read_b128 v[150:153], v160 offset:1024
	ds_read_b128 v[154:157], v160 offset:2048
	ds_read_b128 v[162:165], v160 offset:3072
	v_add_u32_e32 v160, s70, v1
	ds_read_b128 v[170:173], v160
	ds_read_b128 v[174:177], v160 offset:1024
	ds_read_b128 v[178:181], v160 offset:2048
	ds_read_b128 v[182:185], v160 offset:3072
	s_add_u32 s38, s38, s4
	s_addc_u32 s39, s39, s5
	s_mov_b32 m0, s45
	v_lshl_add_u64 v[226:227], s[38:39], 0, v[130:131]
	ds_read_b128 v[186:189], v161 offset:32768
	ds_read_b128 v[190:193], v161 offset:33792
	ds_read_b128 v[194:197], v161 offset:34816
	ds_read_b128 v[198:201], v161 offset:35840
	ds_read_b128 v[202:205], v161 offset:36864
	ds_read_b128 v[206:209], v161 offset:37888
	ds_read_b128 v[210:213], v161 offset:38912
	ds_read_b128 v[214:217], v161 offset:39936
	global_load_lds_dwordx4 v[226:227], off
	v_lshl_add_u64 v[226:227], s[38:39], 0, v[134:135]
	s_mov_b32 m0, s46
	s_nop 0
	global_load_lds_dwordx4 v[226:227], off
	s_waitcnt vmcnt(8)
	s_waitcnt lgkmcnt(0)
	s_barrier
	s_setprio 1
	s_waitcnt lgkmcnt(0)
	v_mfma_i32_16x16x64_i8 v[126:129], v[146:149], v[186:189], v[126:129]
	v_mfma_i32_16x16x64_i8 v[122:125], v[154:157], v[186:189], v[122:125]
	v_mfma_i32_16x16x64_i8 v[118:121], v[146:149], v[194:197], v[118:121]
	v_mfma_i32_16x16x64_i8 v[114:117], v[154:157], v[194:197], v[114:117]
	v_mfma_i32_16x16x64_i8 v[106:109], v[146:149], v[202:205], v[106:109]
	v_mfma_i32_16x16x64_i8 v[98:101], v[154:157], v[202:205], v[98:101]
	v_mfma_i32_16x16x64_i8 v[90:93], v[146:149], v[210:213], v[90:93]
	v_mfma_i32_16x16x64_i8 v[82:85], v[154:157], v[210:213], v[82:85]
	v_mfma_i32_16x16x64_i8 v[126:129], v[150:153], v[190:193], v[126:129]
	v_mfma_i32_16x16x64_i8 v[122:125], v[162:165], v[190:193], v[122:125]
	v_mfma_i32_16x16x64_i8 v[118:121], v[150:153], v[198:201], v[118:121]
	v_mfma_i32_16x16x64_i8 v[114:117], v[162:165], v[198:201], v[114:117]
	v_mfma_i32_16x16x64_i8 v[106:109], v[150:153], v[206:209], v[106:109]
	v_mfma_i32_16x16x64_i8 v[98:101], v[162:165], v[206:209], v[98:101]
	v_mfma_i32_16x16x64_i8 v[90:93], v[150:153], v[214:217], v[90:93]
	v_mfma_i32_16x16x64_i8 v[82:85], v[162:165], v[214:217], v[82:85]
	s_setprio 0
	s_setprio 1
	v_mfma_i32_16x16x64_i8 v[110:113], v[170:173], v[186:189], v[110:113]
	v_mfma_i32_16x16x64_i8 v[102:105], v[178:181], v[186:189], v[102:105]
	v_mfma_i32_16x16x64_i8 v[94:97], v[170:173], v[194:197], v[94:97]
	v_mfma_i32_16x16x64_i8 v[86:89], v[178:181], v[194:197], v[86:89]
	v_mfma_i32_16x16x64_i8 v[78:81], v[170:173], v[202:205], v[78:81]
	v_mfma_i32_16x16x64_i8 v[74:77], v[178:181], v[202:205], v[74:77]
	v_mfma_i32_16x16x64_i8 v[70:73], v[170:173], v[210:213], v[70:73]
	v_mfma_i32_16x16x64_i8 v[66:69], v[178:181], v[210:213], v[66:69]
	v_mfma_i32_16x16x64_i8 v[110:113], v[174:177], v[190:193], v[110:113]
	v_mfma_i32_16x16x64_i8 v[102:105], v[182:185], v[190:193], v[102:105]
	v_mfma_i32_16x16x64_i8 v[94:97], v[174:177], v[198:201], v[94:97]
	v_mfma_i32_16x16x64_i8 v[86:89], v[182:185], v[198:201], v[86:89]
	v_mfma_i32_16x16x64_i8 v[78:81], v[174:177], v[206:209], v[78:81]
	v_mfma_i32_16x16x64_i8 v[74:77], v[182:185], v[206:209], v[74:77]
	v_mfma_i32_16x16x64_i8 v[70:73], v[174:177], v[214:217], v[70:73]
	v_mfma_i32_16x16x64_i8 v[66:69], v[182:185], v[214:217], v[66:69]
	s_setprio 0
	s_barrier
	s_add_i32 s38, s69, s42
	v_lshl_add_u64 v[158:159], v[158:159], 0, s[24:25]
	s_mov_b32 m0, s38
	ds_read_b128 v[186:189], v161 offset:49152
	ds_read_b128 v[190:193], v161 offset:50176
	ds_read_b128 v[194:197], v161 offset:51200
	ds_read_b128 v[198:201], v161 offset:52224
	ds_read_b128 v[202:205], v161 offset:53248
	ds_read_b128 v[206:209], v161 offset:54272
	ds_read_b128 v[210:213], v161 offset:55296
	ds_read_b128 v[214:217], v161 offset:56320
	global_load_lds_dwordx4 v[158:159], off
	v_lshl_add_u64 v[158:159], v[166:167], 0, s[24:25]
	s_add_i32 m0, s38, 0x2000
	s_add_i32 s38, s70, s42
	global_load_lds_dwordx4 v[158:159], off
	v_lshl_add_u64 v[158:159], v[218:219], 0, s[24:25]
	s_mov_b32 m0, s38
	s_nop 0
	global_load_lds_dwordx4 v[158:159], off
	v_lshl_add_u64 v[158:159], v[220:221], 0, s[24:25]
	s_add_i32 m0, s38, 0x2000
	s_nop 0
	global_load_lds_dwordx4 v[158:159], off
	v_lshl_add_u64 v[158:159], v[222:223], 0, s[24:25]
	s_mov_b32 m0, s50
	s_nop 0
	global_load_lds_dwordx4 v[158:159], off
	v_lshl_add_u64 v[158:159], v[224:225], 0, s[24:25]
	s_mov_b32 m0, s51
	s_nop 0
	global_load_lds_dwordx4 v[158:159], off
	s_waitcnt vmcnt(8)
	s_waitcnt lgkmcnt(0)
	s_barrier
	s_setprio 1
	s_waitcnt lgkmcnt(0)
	v_mfma_i32_16x16x64_i8 v[62:65], v[146:149], v[186:189], v[62:65]
	v_mfma_i32_16x16x64_i8 v[58:61], v[154:157], v[186:189], v[58:61]
	v_mfma_i32_16x16x64_i8 v[54:57], v[146:149], v[194:197], v[54:57]
	v_mfma_i32_16x16x64_i8 v[50:53], v[154:157], v[194:197], v[50:53]
	v_mfma_i32_16x16x64_i8 v[42:45], v[146:149], v[202:205], v[42:45]
	v_mfma_i32_16x16x64_i8 v[34:37], v[154:157], v[202:205], v[34:37]
	v_mfma_i32_16x16x64_i8 v[26:29], v[146:149], v[210:213], v[26:29]
	v_mfma_i32_16x16x64_i8 v[18:21], v[154:157], v[210:213], v[18:21]
	v_mfma_i32_16x16x64_i8 v[62:65], v[150:153], v[190:193], v[62:65]
	v_mfma_i32_16x16x64_i8 v[58:61], v[162:165], v[190:193], v[58:61]
	v_mfma_i32_16x16x64_i8 v[54:57], v[150:153], v[198:201], v[54:57]
	v_mfma_i32_16x16x64_i8 v[50:53], v[162:165], v[198:201], v[50:53]
	v_mfma_i32_16x16x64_i8 v[42:45], v[150:153], v[206:209], v[42:45]
	v_mfma_i32_16x16x64_i8 v[34:37], v[162:165], v[206:209], v[34:37]
	v_mfma_i32_16x16x64_i8 v[26:29], v[150:153], v[214:217], v[26:29]
	v_mfma_i32_16x16x64_i8 v[18:21], v[162:165], v[214:217], v[18:21]
	s_setprio 0
	s_setprio 1
	v_mfma_i32_16x16x64_i8 v[46:49], v[170:173], v[186:189], v[46:49]
	v_mfma_i32_16x16x64_i8 v[38:41], v[178:181], v[186:189], v[38:41]
	v_mfma_i32_16x16x64_i8 v[30:33], v[170:173], v[194:197], v[30:33]
	v_mfma_i32_16x16x64_i8 v[22:25], v[178:181], v[194:197], v[22:25]
	v_mfma_i32_16x16x64_i8 v[14:17], v[170:173], v[202:205], v[14:17]
	v_mfma_i32_16x16x64_i8 v[10:13], v[178:181], v[202:205], v[10:13]
	v_mfma_i32_16x16x64_i8 v[6:9], v[170:173], v[210:213], v[6:9]
	v_mfma_i32_16x16x64_i8 v[2:5], v[178:181], v[210:213], v[2:5]
	v_mfma_i32_16x16x64_i8 v[46:49], v[174:177], v[190:193], v[46:49]
	v_mfma_i32_16x16x64_i8 v[38:41], v[182:185], v[190:193], v[38:41]
	v_mfma_i32_16x16x64_i8 v[30:33], v[174:177], v[198:201], v[30:33]
	v_mfma_i32_16x16x64_i8 v[22:25], v[182:185], v[198:201], v[22:25]
	v_mfma_i32_16x16x64_i8 v[14:17], v[174:177], v[206:209], v[14:17]
	v_mfma_i32_16x16x64_i8 v[10:13], v[182:185], v[206:209], v[10:13]
	v_mfma_i32_16x16x64_i8 v[6:9], v[174:177], v[214:217], v[6:9]
	v_mfma_i32_16x16x64_i8 v[2:5], v[182:185], v[214:217], v[2:5]
	s_setprio 0
	s_add_u32 s36, s36, 0x100
	s_addc_u32 s37, s37, 0
	s_add_u32 s66, s66, 0x100
	s_addc_u32 s67, s67, 0
	s_cmp_ge_i32 s68, s52
	s_mov_b32 s38, s68
	s_barrier
	s_cbranch_scc0 .LBB0_1751
	v_cvt_f32_i32_e32 v176, v126
	v_cvt_f32_i32_e32 v177, v127
	v_cvt_f32_i32_e32 v174, v128
	v_cvt_f32_i32_e32 v175, v129
	v_cvt_f32_i32_e32 v178, v122
	v_cvt_f32_i32_e32 v179, v123
	v_cvt_f32_i32_e32 v180, v124
	v_cvt_f32_i32_e32 v181, v125
	v_cvt_f32_i32_e32 v162, v110
	v_cvt_f32_i32_e32 v163, v111
	v_cvt_f32_i32_e32 v164, v112
	v_cvt_f32_i32_e32 v165, v113
	v_cvt_f32_i32_e32 v166, v102
	v_cvt_f32_i32_e32 v167, v103
	v_cvt_f32_i32_e32 v170, v104
	v_cvt_f32_i32_e32 v171, v105
	v_cvt_f32_i32_e32 v152, v118
	v_cvt_f32_i32_e32 v153, v119
	v_cvt_f32_i32_e32 v154, v120
	v_cvt_f32_i32_e32 v155, v121
	v_cvt_f32_i32_e32 v156, v114
	v_cvt_f32_i32_e32 v157, v115
	v_cvt_f32_i32_e32 v158, v116
	v_cvt_f32_i32_e32 v159, v117
	v_cvt_f32_i32_e32 v126, v94
	v_cvt_f32_i32_e32 v127, v95
	v_cvt_f32_i32_e32 v128, v96
	v_cvt_f32_i32_e32 v129, v97
	v_cvt_f32_i32_e32 v146, v86
	v_cvt_f32_i32_e32 v147, v87
	v_cvt_f32_i32_e32 v148, v88
	v_cvt_f32_i32_e32 v149, v89
	v_cvt_f32_i32_e32 v118, v106
	v_cvt_f32_i32_e32 v119, v107
	v_cvt_f32_i32_e32 v120, v108
	v_cvt_f32_i32_e32 v121, v109
	v_cvt_f32_i32_e32 v122, v98
	v_cvt_f32_i32_e32 v123, v99
	v_cvt_f32_i32_e32 v124, v100
	v_cvt_f32_i32_e32 v125, v101
	v_cvt_f32_i32_e32 v108, v78
	v_cvt_f32_i32_e32 v109, v79
	v_cvt_f32_i32_e32 v110, v80
	v_cvt_f32_i32_e32 v111, v81
	v_cvt_f32_i32_e32 v112, v74
	v_cvt_f32_i32_e32 v113, v75
	v_cvt_f32_i32_e32 v114, v76
	v_cvt_f32_i32_e32 v115, v77
	v_cvt_f32_i32_e32 v100, v90
	v_cvt_f32_i32_e32 v101, v91
	v_cvt_f32_i32_e32 v102, v92
	v_cvt_f32_i32_e32 v103, v93
	v_cvt_f32_i32_e32 v104, v82
	v_cvt_f32_i32_e32 v105, v83
	v_cvt_f32_i32_e32 v106, v84
	v_cvt_f32_i32_e32 v107, v85
	v_cvt_f32_i32_e32 v90, v70
	v_cvt_f32_i32_e32 v91, v71
	v_cvt_f32_i32_e32 v92, v72
	v_cvt_f32_i32_e32 v93, v73
	v_cvt_f32_i32_e32 v94, v66
	v_cvt_f32_i32_e32 v95, v67
	v_cvt_f32_i32_e32 v96, v68
	v_cvt_f32_i32_e32 v97, v69
	v_cvt_f32_i32_e32 v82, v62
	v_cvt_f32_i32_e32 v83, v63
	v_cvt_f32_i32_e32 v84, v64
	v_cvt_f32_i32_e32 v85, v65
	v_cvt_f32_i32_e32 v86, v58
	v_cvt_f32_i32_e32 v87, v59
	v_cvt_f32_i32_e32 v88, v60
	v_cvt_f32_i32_e32 v89, v61
	v_cvt_f32_i32_e32 v74, v46
	v_cvt_f32_i32_e32 v75, v47
	v_cvt_f32_i32_e32 v76, v48
	v_cvt_f32_i32_e32 v77, v49
	v_cvt_f32_i32_e32 v78, v38
	v_cvt_f32_i32_e32 v79, v39
	v_cvt_f32_i32_e32 v80, v40
	v_cvt_f32_i32_e32 v81, v41
	v_cvt_f32_i32_e32 v54, v54
	v_cvt_f32_i32_e32 v55, v55
	v_cvt_f32_i32_e32 v56, v56
	v_cvt_f32_i32_e32 v57, v57
	v_cvt_f32_i32_e32 v58, v50
	v_cvt_f32_i32_e32 v59, v51
	v_cvt_f32_i32_e32 v60, v52
	v_cvt_f32_i32_e32 v61, v53
	v_cvt_f32_i32_e32 v46, v30
	v_cvt_f32_i32_e32 v47, v31
	v_cvt_f32_i32_e32 v48, v32
	v_cvt_f32_i32_e32 v49, v33
	v_cvt_f32_i32_e32 v50, v22
	v_cvt_f32_i32_e32 v51, v23
	v_cvt_f32_i32_e32 v52, v24
	v_cvt_f32_i32_e32 v53, v25
	v_cvt_f32_i32_e32 v38, v42
	v_cvt_f32_i32_e32 v39, v43
	v_cvt_f32_i32_e32 v40, v44
	v_cvt_f32_i32_e32 v41, v45
	v_cvt_f32_i32_e32 v34, v34
	v_cvt_f32_i32_e32 v35, v35
	v_cvt_f32_i32_e32 v36, v36
	v_cvt_f32_i32_e32 v37, v37
	v_cvt_f32_i32_e32 v22, v14
	v_cvt_f32_i32_e32 v23, v15
	v_cvt_f32_i32_e32 v24, v16
	v_cvt_f32_i32_e32 v25, v17
	v_cvt_f32_i32_e32 v30, v10
	v_cvt_f32_i32_e32 v31, v11
	v_cvt_f32_i32_e32 v32, v12
	v_cvt_f32_i32_e32 v33, v13
	v_cvt_f32_i32_e32 v10, v26
	v_cvt_f32_i32_e32 v11, v27
	v_cvt_f32_i32_e32 v12, v28
	v_cvt_f32_i32_e32 v13, v29
	v_cvt_f32_i32_e32 v14, v18
	v_cvt_f32_i32_e32 v15, v19
	v_cvt_f32_i32_e32 v16, v20
	v_cvt_f32_i32_e32 v17, v21
	v_cvt_f32_i32_e32 v6, v6
	v_cvt_f32_i32_e32 v7, v7
	v_cvt_f32_i32_e32 v8, v8
	v_cvt_f32_i32_e32 v9, v9
	v_cvt_f32_i32_e32 v2, v2
	v_cvt_f32_i32_e32 v3, v3
	v_cvt_f32_i32_e32 v4, v4
	v_cvt_f32_i32_e32 v5, v5

.LBB0_1896:
	v_add_u32_e32 v150, s67, v1
	ds_read_b128 v[146:149], v150
	ds_read_b128 v[152:155], v150 offset:1024
	ds_read_b128 v[156:159], v150 offset:2048
	ds_read_b128 v[160:163], v150 offset:3072
	v_add_u32_e32 v150, s68, v1
	ds_read_b128 v[164:167], v150
	ds_read_b128 v[170:173], v150 offset:1024
	ds_read_b128 v[174:177], v150 offset:2048
	ds_read_b128 v[178:181], v150 offset:3072
	s_add_i32 s73, s38, 2
	s_add_u32 s74, s36, 0x80
	s_addc_u32 s39, s37, 0
	s_cmp_eq_u32 s63, s38
	s_cselect_b32 s38, s2, s74
	s_cselect_b32 s39, s3, s39
	s_cselect_b32 s75, s35, s72
	s_cselect_b32 s74, s34, s71
	v_lshl_add_u64 v[214:215], s[36:37], 0, v[138:139]
	s_add_i32 m0, s90, 0xc000
	ds_read_b128 v[182:185], v151
	ds_read_b128 v[186:189], v151 offset:1024
	ds_read_b128 v[190:193], v151 offset:2048
	ds_read_b128 v[194:197], v151 offset:3072
	ds_read_b128 v[198:201], v151 offset:4096
	ds_read_b128 v[202:205], v151 offset:5120
	ds_read_b128 v[206:209], v151 offset:6144
	ds_read_b128 v[210:213], v151 offset:7168
	global_load_lds_dwordx4 v[214:215], off
	v_lshl_add_u64 v[214:215], s[36:37], 0, v[140:141]
	s_add_i32 m0, s90, 0xe000
	s_nop 0
	global_load_lds_dwordx4 v[214:215], off
	s_waitcnt vmcnt(8)
	s_waitcnt lgkmcnt(0)
	s_barrier
	s_setprio 1
	s_waitcnt lgkmcnt(0)
	v_mfma_i32_16x16x64_i8 v[126:129], v[146:149], v[182:185], v[126:129]
	v_mfma_i32_16x16x64_i8 v[122:125], v[156:159], v[182:185], v[122:125]
	v_mfma_i32_16x16x64_i8 v[118:121], v[146:149], v[190:193], v[118:121]
	v_mfma_i32_16x16x64_i8 v[114:117], v[156:159], v[190:193], v[114:117]
	v_mfma_i32_16x16x64_i8 v[106:109], v[146:149], v[198:201], v[106:109]
	v_mfma_i32_16x16x64_i8 v[98:101], v[156:159], v[198:201], v[98:101]
	v_mfma_i32_16x16x64_i8 v[90:93], v[146:149], v[206:209], v[90:93]
	v_mfma_i32_16x16x64_i8 v[82:85], v[156:159], v[206:209], v[82:85]
	v_mfma_i32_16x16x64_i8 v[126:129], v[152:155], v[186:189], v[126:129]
	v_mfma_i32_16x16x64_i8 v[122:125], v[160:163], v[186:189], v[122:125]
	v_mfma_i32_16x16x64_i8 v[118:121], v[152:155], v[194:197], v[118:121]
	v_mfma_i32_16x16x64_i8 v[114:117], v[160:163], v[194:197], v[114:117]
	v_mfma_i32_16x16x64_i8 v[106:109], v[152:155], v[202:205], v[106:109]
	v_mfma_i32_16x16x64_i8 v[98:101], v[160:163], v[202:205], v[98:101]
	v_mfma_i32_16x16x64_i8 v[90:93], v[152:155], v[210:213], v[90:93]
	v_mfma_i32_16x16x64_i8 v[82:85], v[160:163], v[210:213], v[82:85]
	s_setprio 0
	s_setprio 1
	v_mfma_i32_16x16x64_i8 v[110:113], v[164:167], v[182:185], v[110:113]
	v_mfma_i32_16x16x64_i8 v[102:105], v[174:177], v[182:185], v[102:105]
	v_mfma_i32_16x16x64_i8 v[94:97], v[164:167], v[190:193], v[94:97]
	v_mfma_i32_16x16x64_i8 v[86:89], v[174:177], v[190:193], v[86:89]
	v_mfma_i32_16x16x64_i8 v[78:81], v[164:167], v[198:201], v[78:81]
	v_mfma_i32_16x16x64_i8 v[74:77], v[174:177], v[198:201], v[74:77]
	v_mfma_i32_16x16x64_i8 v[70:73], v[164:167], v[206:209], v[70:73]
	v_mfma_i32_16x16x64_i8 v[66:69], v[174:177], v[206:209], v[66:69]
	v_mfma_i32_16x16x64_i8 v[110:113], v[170:173], v[186:189], v[110:113]
	v_mfma_i32_16x16x64_i8 v[102:105], v[178:181], v[186:189], v[102:105]
	v_mfma_i32_16x16x64_i8 v[94:97], v[170:173], v[194:197], v[94:97]
	v_mfma_i32_16x16x64_i8 v[86:89], v[178:181], v[194:197], v[86:89]
	v_mfma_i32_16x16x64_i8 v[78:81], v[170:173], v[202:205], v[78:81]
	v_mfma_i32_16x16x64_i8 v[74:77], v[178:181], v[202:205], v[74:77]
	v_mfma_i32_16x16x64_i8 v[70:73], v[170:173], v[210:213], v[70:73]
	v_mfma_i32_16x16x64_i8 v[66:69], v[178:181], v[210:213], v[66:69]
	s_setprio 0
	s_barrier
	s_add_i32 s76, s67, s85
	v_lshl_add_u64 v[214:215], s[74:75], 0, v[134:135]
	s_mov_b32 m0, s76
	ds_read_b128 v[182:185], v151 offset:16384
	ds_read_b128 v[186:189], v151 offset:17408
	ds_read_b128 v[190:193], v151 offset:18432
	ds_read_b128 v[194:197], v151 offset:19456
	ds_read_b128 v[198:201], v151 offset:20480
	ds_read_b128 v[202:205], v151 offset:21504
	ds_read_b128 v[206:209], v151 offset:22528
	ds_read_b128 v[210:213], v151 offset:23552
	global_load_lds_dwordx4 v[214:215], off
	s_add_i32 m0, s76, 0x2000
	v_lshl_add_u64 v[216:217], s[74:75], 0, v[130:131]
	s_add_u32 s74, s74, s6
	s_addc_u32 s75, s75, s7
	s_add_i32 s76, s68, s85
	global_load_lds_dwordx4 v[216:217], off
	v_lshl_add_u64 v[218:219], s[74:75], 0, v[134:135]
	s_mov_b32 m0, s76
	v_lshl_add_u64 v[220:221], s[74:75], 0, v[130:131]
	global_load_lds_dwordx4 v[218:219], off
	s_add_i32 m0, s76, 0x2000
	v_lshl_add_u64 v[222:223], s[38:39], 0, v[136:137]
	global_load_lds_dwordx4 v[220:221], off
	s_mov_b32 m0, s90
	v_lshl_add_u64 v[224:225], s[38:39], 0, v[132:133]
	global_load_lds_dwordx4 v[222:223], off
	s_mov_b32 m0, s91
	s_nop 0
	global_load_lds_dwordx4 v[224:225], off
	s_waitcnt vmcnt(8)
	s_waitcnt lgkmcnt(0)
	s_barrier
	s_setprio 1
	s_waitcnt lgkmcnt(0)
	v_mfma_i32_16x16x64_i8 v[62:65], v[146:149], v[182:185], v[62:65]
	v_mfma_i32_16x16x64_i8 v[58:61], v[156:159], v[182:185], v[58:61]
	v_mfma_i32_16x16x64_i8 v[54:57], v[146:149], v[190:193], v[54:57]
	v_mfma_i32_16x16x64_i8 v[50:53], v[156:159], v[190:193], v[50:53]
	v_mfma_i32_16x16x64_i8 v[42:45], v[146:149], v[198:201], v[42:45]
	v_mfma_i32_16x16x64_i8 v[34:37], v[156:159], v[198:201], v[34:37]
	v_mfma_i32_16x16x64_i8 v[26:29], v[146:149], v[206:209], v[26:29]
	v_mfma_i32_16x16x64_i8 v[18:21], v[156:159], v[206:209], v[18:21]
	v_mfma_i32_16x16x64_i8 v[62:65], v[152:155], v[186:189], v[62:65]
	v_mfma_i32_16x16x64_i8 v[58:61], v[160:163], v[186:189], v[58:61]
	v_mfma_i32_16x16x64_i8 v[54:57], v[152:155], v[194:197], v[54:57]
	v_mfma_i32_16x16x64_i8 v[50:53], v[160:163], v[194:197], v[50:53]
	v_mfma_i32_16x16x64_i8 v[42:45], v[152:155], v[202:205], v[42:45]
	v_mfma_i32_16x16x64_i8 v[34:37], v[160:163], v[202:205], v[34:37]
	v_mfma_i32_16x16x64_i8 v[26:29], v[152:155], v[210:213], v[26:29]
	v_mfma_i32_16x16x64_i8 v[18:21], v[160:163], v[210:213], v[18:21]
	s_setprio 0
	s_setprio 1
	v_mfma_i32_16x16x64_i8 v[46:49], v[164:167], v[182:185], v[46:49]
	v_mfma_i32_16x16x64_i8 v[38:41], v[174:177], v[182:185], v[38:41]
	v_mfma_i32_16x16x64_i8 v[30:33], v[164:167], v[190:193], v[30:33]
	v_mfma_i32_16x16x64_i8 v[22:25], v[174:177], v[190:193], v[22:25]
	v_mfma_i32_16x16x64_i8 v[14:17], v[164:167], v[198:201], v[14:17]
	v_mfma_i32_16x16x64_i8 v[10:13], v[174:177], v[198:201], v[10:13]
	v_mfma_i32_16x16x64_i8 v[6:9], v[164:167], v[206:209], v[6:9]
	v_mfma_i32_16x16x64_i8 v[2:5], v[174:177], v[206:209], v[2:5]
	v_mfma_i32_16x16x64_i8 v[46:49], v[170:173], v[186:189], v[46:49]
	v_mfma_i32_16x16x64_i8 v[38:41], v[178:181], v[186:189], v[38:41]
	v_mfma_i32_16x16x64_i8 v[30:33], v[170:173], v[194:197], v[30:33]
	v_mfma_i32_16x16x64_i8 v[22:25], v[178:181], v[194:197], v[22:25]
	v_mfma_i32_16x16x64_i8 v[14:17], v[170:173], v[202:205], v[14:17]
	v_mfma_i32_16x16x64_i8 v[10:13], v[178:181], v[202:205], v[10:13]
	v_mfma_i32_16x16x64_i8 v[6:9], v[170:173], v[210:213], v[6:9]
	v_mfma_i32_16x16x64_i8 v[2:5], v[178:181], v[210:213], v[2:5]
	s_setprio 0
	s_barrier
	s_add_i32 s74, 0, 0x18000
	v_add_u32_e32 v150, s74, v1
	s_add_i32 s75, 0, 0x1c000
	ds_read_b128 v[146:149], v150
	ds_read_b128 v[152:155], v150 offset:1024
	ds_read_b128 v[156:159], v150 offset:2048
	ds_read_b128 v[160:163], v150 offset:3072
	v_add_u32_e32 v150, s75, v1
	ds_read_b128 v[164:167], v150
	ds_read_b128 v[170:173], v150 offset:1024
	ds_read_b128 v[174:177], v150 offset:2048
	ds_read_b128 v[178:181], v150 offset:3072
	s_add_u32 s38, s38, s6
	s_addc_u32 s39, s39, s7
	s_mov_b32 m0, s96
	v_lshl_add_u64 v[226:227], s[38:39], 0, v[136:137]
	ds_read_b128 v[182:185], v151 offset:32768
	ds_read_b128 v[186:189], v151 offset:33792
	ds_read_b128 v[190:193], v151 offset:34816
	ds_read_b128 v[194:197], v151 offset:35840
	ds_read_b128 v[198:201], v151 offset:36864
	ds_read_b128 v[202:205], v151 offset:37888
	ds_read_b128 v[206:209], v151 offset:38912
	ds_read_b128 v[210:213], v151 offset:39936
	global_load_lds_dwordx4 v[226:227], off
	v_lshl_add_u64 v[226:227], s[38:39], 0, v[132:133]
	s_mov_b32 m0, s52
	s_nop 0
	global_load_lds_dwordx4 v[226:227], off
	s_waitcnt vmcnt(8)
	s_waitcnt lgkmcnt(0)
	s_barrier
	s_setprio 1
	s_waitcnt lgkmcnt(0)
	v_mfma_i32_16x16x64_i8 v[126:129], v[146:149], v[182:185], v[126:129]
	v_mfma_i32_16x16x64_i8 v[122:125], v[156:159], v[182:185], v[122:125]
	v_mfma_i32_16x16x64_i8 v[118:121], v[146:149], v[190:193], v[118:121]
	v_mfma_i32_16x16x64_i8 v[114:117], v[156:159], v[190:193], v[114:117]
	v_mfma_i32_16x16x64_i8 v[106:109], v[146:149], v[198:201], v[106:109]
	v_mfma_i32_16x16x64_i8 v[98:101], v[156:159], v[198:201], v[98:101]
	v_mfma_i32_16x16x64_i8 v[90:93], v[146:149], v[206:209], v[90:93]
	v_mfma_i32_16x16x64_i8 v[82:85], v[156:159], v[206:209], v[82:85]
	v_mfma_i32_16x16x64_i8 v[126:129], v[152:155], v[186:189], v[126:129]
	v_mfma_i32_16x16x64_i8 v[122:125], v[160:163], v[186:189], v[122:125]
	v_mfma_i32_16x16x64_i8 v[118:121], v[152:155], v[194:197], v[118:121]
	v_mfma_i32_16x16x64_i8 v[114:117], v[160:163], v[194:197], v[114:117]
	v_mfma_i32_16x16x64_i8 v[106:109], v[152:155], v[202:205], v[106:109]
	v_mfma_i32_16x16x64_i8 v[98:101], v[160:163], v[202:205], v[98:101]
	v_mfma_i32_16x16x64_i8 v[90:93], v[152:155], v[210:213], v[90:93]
	v_mfma_i32_16x16x64_i8 v[82:85], v[160:163], v[210:213], v[82:85]
	s_setprio 0
	s_setprio 1
	v_mfma_i32_16x16x64_i8 v[110:113], v[164:167], v[182:185], v[110:113]
	v_mfma_i32_16x16x64_i8 v[102:105], v[174:177], v[182:185], v[102:105]
	v_mfma_i32_16x16x64_i8 v[94:97], v[164:167], v[190:193], v[94:97]
	v_mfma_i32_16x16x64_i8 v[86:89], v[174:177], v[190:193], v[86:89]
	v_mfma_i32_16x16x64_i8 v[78:81], v[164:167], v[198:201], v[78:81]
	v_mfma_i32_16x16x64_i8 v[74:77], v[174:177], v[198:201], v[74:77]
	v_mfma_i32_16x16x64_i8 v[70:73], v[164:167], v[206:209], v[70:73]
	v_mfma_i32_16x16x64_i8 v[66:69], v[174:177], v[206:209], v[66:69]
	v_mfma_i32_16x16x64_i8 v[110:113], v[170:173], v[186:189], v[110:113]
	v_mfma_i32_16x16x64_i8 v[102:105], v[178:181], v[186:189], v[102:105]
	v_mfma_i32_16x16x64_i8 v[94:97], v[170:173], v[194:197], v[94:97]
	v_mfma_i32_16x16x64_i8 v[86:89], v[178:181], v[194:197], v[86:89]
	v_mfma_i32_16x16x64_i8 v[78:81], v[170:173], v[202:205], v[78:81]
	v_mfma_i32_16x16x64_i8 v[74:77], v[178:181], v[202:205], v[74:77]
	v_mfma_i32_16x16x64_i8 v[70:73], v[170:173], v[210:213], v[70:73]
	v_mfma_i32_16x16x64_i8 v[66:69], v[178:181], v[210:213], v[66:69]
	s_setprio 0
	s_barrier
	s_add_i32 s38, s74, s85
	v_lshl_add_u64 v[214:215], v[214:215], 0, s[16:17]
	s_mov_b32 m0, s38
	ds_read_b128 v[182:185], v151 offset:49152
	ds_read_b128 v[186:189], v151 offset:50176
	ds_read_b128 v[190:193], v151 offset:51200
	ds_read_b128 v[194:197], v151 offset:52224
	ds_read_b128 v[198:201], v151 offset:53248
	ds_read_b128 v[202:205], v151 offset:54272
	ds_read_b128 v[206:209], v151 offset:55296
	ds_read_b128 v[210:213], v151 offset:56320
	global_load_lds_dwordx4 v[214:215], off
	v_lshl_add_u64 v[214:215], v[216:217], 0, s[16:17]
	s_add_i32 m0, s38, 0x2000
	s_add_i32 s38, s75, s85
	global_load_lds_dwordx4 v[214:215], off
	v_lshl_add_u64 v[214:215], v[218:219], 0, s[16:17]
	s_mov_b32 m0, s38
	s_nop 0
	global_load_lds_dwordx4 v[214:215], off
	v_lshl_add_u64 v[214:215], v[220:221], 0, s[16:17]
	s_add_i32 m0, s38, 0x2000
	s_nop 0
	global_load_lds_dwordx4 v[214:215], off
	v_lshl_add_u64 v[214:215], v[222:223], 0, s[16:17]
	s_mov_b32 m0, s57
	s_nop 0
	global_load_lds_dwordx4 v[214:215], off
	v_lshl_add_u64 v[214:215], v[224:225], 0, s[16:17]
	s_mov_b32 m0, s58
	s_nop 0
	global_load_lds_dwordx4 v[214:215], off
	s_waitcnt vmcnt(8)
	s_waitcnt lgkmcnt(0)
	s_barrier
	s_setprio 1
	s_waitcnt lgkmcnt(0)
	v_mfma_i32_16x16x64_i8 v[62:65], v[146:149], v[182:185], v[62:65]
	v_mfma_i32_16x16x64_i8 v[58:61], v[156:159], v[182:185], v[58:61]
	v_mfma_i32_16x16x64_i8 v[54:57], v[146:149], v[190:193], v[54:57]
	v_mfma_i32_16x16x64_i8 v[50:53], v[156:159], v[190:193], v[50:53]
	v_mfma_i32_16x16x64_i8 v[42:45], v[146:149], v[198:201], v[42:45]
	v_mfma_i32_16x16x64_i8 v[34:37], v[156:159], v[198:201], v[34:37]
	v_mfma_i32_16x16x64_i8 v[26:29], v[146:149], v[206:209], v[26:29]
	v_mfma_i32_16x16x64_i8 v[18:21], v[156:159], v[206:209], v[18:21]
	v_mfma_i32_16x16x64_i8 v[62:65], v[152:155], v[186:189], v[62:65]
	v_mfma_i32_16x16x64_i8 v[58:61], v[160:163], v[186:189], v[58:61]
	v_mfma_i32_16x16x64_i8 v[54:57], v[152:155], v[194:197], v[54:57]
	v_mfma_i32_16x16x64_i8 v[50:53], v[160:163], v[194:197], v[50:53]
	v_mfma_i32_16x16x64_i8 v[42:45], v[152:155], v[202:205], v[42:45]
	v_mfma_i32_16x16x64_i8 v[34:37], v[160:163], v[202:205], v[34:37]
	v_mfma_i32_16x16x64_i8 v[26:29], v[152:155], v[210:213], v[26:29]
	v_mfma_i32_16x16x64_i8 v[18:21], v[160:163], v[210:213], v[18:21]
	s_setprio 0
	s_setprio 1
	v_mfma_i32_16x16x64_i8 v[46:49], v[164:167], v[182:185], v[46:49]
	v_mfma_i32_16x16x64_i8 v[38:41], v[174:177], v[182:185], v[38:41]
	v_mfma_i32_16x16x64_i8 v[30:33], v[164:167], v[190:193], v[30:33]
	v_mfma_i32_16x16x64_i8 v[22:25], v[174:177], v[190:193], v[22:25]
	v_mfma_i32_16x16x64_i8 v[14:17], v[164:167], v[198:201], v[14:17]
	v_mfma_i32_16x16x64_i8 v[10:13], v[174:177], v[198:201], v[10:13]
	v_mfma_i32_16x16x64_i8 v[6:9], v[164:167], v[206:209], v[6:9]
	v_mfma_i32_16x16x64_i8 v[2:5], v[174:177], v[206:209], v[2:5]
	v_mfma_i32_16x16x64_i8 v[46:49], v[170:173], v[186:189], v[46:49]
	v_mfma_i32_16x16x64_i8 v[38:41], v[178:181], v[186:189], v[38:41]
	v_mfma_i32_16x16x64_i8 v[30:33], v[170:173], v[194:197], v[30:33]
	v_mfma_i32_16x16x64_i8 v[22:25], v[178:181], v[194:197], v[22:25]
	v_mfma_i32_16x16x64_i8 v[14:17], v[170:173], v[202:205], v[14:17]
	v_mfma_i32_16x16x64_i8 v[10:13], v[178:181], v[202:205], v[10:13]
	v_mfma_i32_16x16x64_i8 v[6:9], v[170:173], v[210:213], v[6:9]
	v_mfma_i32_16x16x64_i8 v[2:5], v[178:181], v[210:213], v[2:5]
	s_setprio 0
	s_add_u32 s36, s36, 0x100
	s_addc_u32 s37, s37, 0
	s_add_u32 s71, s71, 0x100
	s_addc_u32 s72, s72, 0
	s_cmp_ge_i32 s73, s59
	s_mov_b32 s38, s73
	s_barrier
	s_cbranch_scc0 .LBB0_1896
	v_cvt_f32_i32_e32 v154, v126
	v_cvt_f32_i32_e32 v155, v127
	v_cvt_f32_i32_e32 v152, v128
	v_cvt_f32_i32_e32 v153, v129
	v_cvt_f32_i32_e32 v158, v122
	v_cvt_f32_i32_e32 v159, v123
	v_cvt_f32_i32_e32 v156, v124
	v_cvt_f32_i32_e32 v157, v125
	v_cvt_f32_i32_e32 v128, v110
	v_cvt_f32_i32_e32 v129, v111
	v_cvt_f32_i32_e32 v126, v112
	v_cvt_f32_i32_e32 v127, v113
	v_cvt_f32_i32_e32 v148, v102
	v_cvt_f32_i32_e32 v149, v103
	v_cvt_f32_i32_e32 v146, v104
	v_cvt_f32_i32_e32 v147, v105
	v_cvt_f32_i32_e32 v122, v118
	v_cvt_f32_i32_e32 v123, v119
	v_cvt_f32_i32_e32 v118, v120
	v_cvt_f32_i32_e32 v119, v121
	v_cvt_f32_i32_e32 v124, v114
	v_cvt_f32_i32_e32 v125, v115
	v_cvt_f32_i32_e32 v120, v116
	v_cvt_f32_i32_e32 v121, v117
	v_cvt_f32_i32_e32 v112, v94
	v_cvt_f32_i32_e32 v113, v95
	v_cvt_f32_i32_e32 v110, v96
	v_cvt_f32_i32_e32 v111, v97
	v_cvt_f32_i32_e32 v116, v86
	v_cvt_f32_i32_e32 v117, v87
	v_cvt_f32_i32_e32 v114, v88
	v_cvt_f32_i32_e32 v115, v89
	v_cvt_f32_i32_e32 v104, v106
	v_cvt_f32_i32_e32 v105, v107
	v_cvt_f32_i32_e32 v102, v108
	v_cvt_f32_i32_e32 v103, v109
	v_cvt_f32_i32_e32 v108, v98
	v_cvt_f32_i32_e32 v109, v99
	v_cvt_f32_i32_e32 v106, v100
	v_cvt_f32_i32_e32 v107, v101
	v_cvt_f32_i32_e32 v96, v78
	v_cvt_f32_i32_e32 v97, v79
	v_cvt_f32_i32_e32 v94, v80
	v_cvt_f32_i32_e32 v95, v81
	v_cvt_f32_i32_e32 v100, v74
	v_cvt_f32_i32_e32 v101, v75
	v_cvt_f32_i32_e32 v98, v76
	v_cvt_f32_i32_e32 v99, v77
	v_cvt_f32_i32_e32 v88, v90
	v_cvt_f32_i32_e32 v89, v91
	v_cvt_f32_i32_e32 v86, v92
	v_cvt_f32_i32_e32 v87, v93
	v_cvt_f32_i32_e32 v92, v82
	v_cvt_f32_i32_e32 v93, v83
	v_cvt_f32_i32_e32 v90, v84
	v_cvt_f32_i32_e32 v91, v85
	v_cvt_f32_i32_e32 v80, v70
	v_cvt_f32_i32_e32 v81, v71
	v_cvt_f32_i32_e32 v78, v72
	v_cvt_f32_i32_e32 v79, v73
	v_cvt_f32_i32_e32 v84, v66
	v_cvt_f32_i32_e32 v85, v67
	v_cvt_f32_i32_e32 v82, v68
	v_cvt_f32_i32_e32 v83, v69
	v_cvt_f32_i32_e32 v72, v62
	v_cvt_f32_i32_e32 v73, v63
	v_cvt_f32_i32_e32 v70, v64
	v_cvt_f32_i32_e32 v71, v65
	v_cvt_f32_i32_e32 v76, v58
	v_cvt_f32_i32_e32 v77, v59
	v_cvt_f32_i32_e32 v74, v60
	v_cvt_f32_i32_e32 v75, v61
	v_cvt_f32_i32_e32 v64, v46
	v_cvt_f32_i32_e32 v65, v47
	v_cvt_f32_i32_e32 v62, v48
	v_cvt_f32_i32_e32 v63, v49
	v_cvt_f32_i32_e32 v68, v38
	v_cvt_f32_i32_e32 v69, v39
	v_cvt_f32_i32_e32 v66, v40
	v_cvt_f32_i32_e32 v67, v41
	v_cvt_f32_i32_e32 v58, v54
	v_cvt_f32_i32_e32 v59, v55
	v_cvt_f32_i32_e32 v54, v56
	v_cvt_f32_i32_e32 v55, v57
	v_cvt_f32_i32_e32 v60, v50
	v_cvt_f32_i32_e32 v61, v51
	v_cvt_f32_i32_e32 v56, v52
	v_cvt_f32_i32_e32 v57, v53
	v_cvt_f32_i32_e32 v48, v30
	v_cvt_f32_i32_e32 v49, v31
	v_cvt_f32_i32_e32 v46, v32
	v_cvt_f32_i32_e32 v47, v33
	v_cvt_f32_i32_e32 v52, v22
	v_cvt_f32_i32_e32 v53, v23
	v_cvt_f32_i32_e32 v50, v24
	v_cvt_f32_i32_e32 v51, v25
	v_cvt_f32_i32_e32 v40, v42
	v_cvt_f32_i32_e32 v41, v43
	v_cvt_f32_i32_e32 v38, v44
	v_cvt_f32_i32_e32 v39, v45
	v_cvt_f32_i32_e32 v42, v34
	v_cvt_f32_i32_e32 v43, v35
	v_cvt_f32_i32_e32 v34, v36
	v_cvt_f32_i32_e32 v35, v37
	v_cvt_f32_i32_e32 v24, v14
	v_cvt_f32_i32_e32 v25, v15
	v_cvt_f32_i32_e32 v22, v16
	v_cvt_f32_i32_e32 v23, v17
	v_cvt_f32_i32_e32 v32, v10
	v_cvt_f32_i32_e32 v33, v11
	v_cvt_f32_i32_e32 v30, v12
	v_cvt_f32_i32_e32 v31, v13
	v_cvt_f32_i32_e32 v14, v26
	v_cvt_f32_i32_e32 v15, v27
	v_cvt_f32_i32_e32 v12, v28
	v_cvt_f32_i32_e32 v13, v29
	v_cvt_f32_i32_e32 v18, v18
	v_cvt_f32_i32_e32 v19, v19
	v_cvt_f32_i32_e32 v16, v20
	v_cvt_f32_i32_e32 v17, v21
	v_cvt_f32_i32_e32 v10, v6
	v_cvt_f32_i32_e32 v11, v7
	v_cvt_f32_i32_e32 v6, v8
	v_cvt_f32_i32_e32 v7, v9
	v_cvt_f32_i32_e32 v8, v2
	v_cvt_f32_i32_e32 v9, v3
	v_cvt_f32_i32_e32 v2, v4
	v_cvt_f32_i32_e32 v3, v5

.LBB0_2025:
	v_add_u32_e32 v138, s56, v1
	ds_read_b128 v[148:151], v138
	ds_read_b128 v[156:159], v138 offset:1024
	ds_read_b128 v[160:163], v138 offset:2048
	ds_read_b128 v[164:167], v138 offset:3072
	v_add_u32_e32 v138, s57, v1
	ds_read_b128 v[168:171], v138
	ds_read_b128 v[172:175], v138 offset:1024
	ds_read_b128 v[176:179], v138 offset:2048
	ds_read_b128 v[180:183], v138 offset:3072
	s_add_i32 s65, s30, 2
	s_add_u32 s66, s28, 0x80
	s_addc_u32 s31, s29, 0
	s_cmp_eq_u32 s54, s30
	s_cselect_b32 s30, s2, s66
	s_cselect_b32 s31, s3, s31
	s_cselect_b32 s67, s27, s64
	s_cselect_b32 s66, s26, s63
	v_lshl_add_u64 v[152:153], s[28:29], 0, v[140:141]
	s_add_i32 m0, s41, 0xc000
	ds_read_b128 v[184:187], v155
	ds_read_b128 v[188:191], v155 offset:1024
	ds_read_b128 v[192:195], v155 offset:2048
	ds_read_b128 v[196:199], v155 offset:3072
	ds_read_b128 v[200:203], v155 offset:4096
	ds_read_b128 v[204:207], v155 offset:5120
	ds_read_b128 v[208:211], v155 offset:6144
	ds_read_b128 v[212:215], v155 offset:7168
	global_load_lds_dwordx4 v[152:153], off
	v_lshl_add_u64 v[152:153], s[28:29], 0, v[142:143]
	s_add_i32 m0, s41, 0xe000
	s_nop 0
	global_load_lds_dwordx4 v[152:153], off
	s_waitcnt vmcnt(8)
	s_waitcnt lgkmcnt(0)
	s_barrier
	s_setprio 1
	s_waitcnt lgkmcnt(0)
	v_mfma_i32_16x16x64_i8 v[126:129], v[148:151], v[184:187], v[126:129]
	v_mfma_i32_16x16x64_i8 v[122:125], v[160:163], v[184:187], v[122:125]
	v_mfma_i32_16x16x64_i8 v[118:121], v[148:151], v[192:195], v[118:121]
	v_mfma_i32_16x16x64_i8 v[114:117], v[160:163], v[192:195], v[114:117]
	v_mfma_i32_16x16x64_i8 v[106:109], v[148:151], v[200:203], v[106:109]
	v_mfma_i32_16x16x64_i8 v[98:101], v[160:163], v[200:203], v[98:101]
	v_mfma_i32_16x16x64_i8 v[90:93], v[148:151], v[208:211], v[90:93]
	v_mfma_i32_16x16x64_i8 v[82:85], v[160:163], v[208:211], v[82:85]
	v_mfma_i32_16x16x64_i8 v[126:129], v[156:159], v[188:191], v[126:129]
	v_mfma_i32_16x16x64_i8 v[122:125], v[164:167], v[188:191], v[122:125]
	v_mfma_i32_16x16x64_i8 v[118:121], v[156:159], v[196:199], v[118:121]
	v_mfma_i32_16x16x64_i8 v[114:117], v[164:167], v[196:199], v[114:117]
	v_mfma_i32_16x16x64_i8 v[106:109], v[156:159], v[204:207], v[106:109]
	v_mfma_i32_16x16x64_i8 v[98:101], v[164:167], v[204:207], v[98:101]
	v_mfma_i32_16x16x64_i8 v[90:93], v[156:159], v[212:215], v[90:93]
	v_mfma_i32_16x16x64_i8 v[82:85], v[164:167], v[212:215], v[82:85]
	s_setprio 0
	s_setprio 1
	v_mfma_i32_16x16x64_i8 v[110:113], v[168:171], v[184:187], v[110:113]
	v_mfma_i32_16x16x64_i8 v[102:105], v[176:179], v[184:187], v[102:105]
	v_mfma_i32_16x16x64_i8 v[94:97], v[168:171], v[192:195], v[94:97]
	v_mfma_i32_16x16x64_i8 v[86:89], v[176:179], v[192:195], v[86:89]
	v_mfma_i32_16x16x64_i8 v[78:81], v[168:171], v[200:203], v[78:81]
	v_mfma_i32_16x16x64_i8 v[74:77], v[176:179], v[200:203], v[74:77]
	v_mfma_i32_16x16x64_i8 v[70:73], v[168:171], v[208:211], v[70:73]
	v_mfma_i32_16x16x64_i8 v[66:69], v[176:179], v[208:211], v[66:69]
	v_mfma_i32_16x16x64_i8 v[110:113], v[172:175], v[188:191], v[110:113]
	v_mfma_i32_16x16x64_i8 v[102:105], v[180:183], v[188:191], v[102:105]
	v_mfma_i32_16x16x64_i8 v[94:97], v[172:175], v[196:199], v[94:97]
	v_mfma_i32_16x16x64_i8 v[86:89], v[180:183], v[196:199], v[86:89]
	v_mfma_i32_16x16x64_i8 v[78:81], v[172:175], v[204:207], v[78:81]
	v_mfma_i32_16x16x64_i8 v[74:77], v[180:183], v[204:207], v[74:77]
	v_mfma_i32_16x16x64_i8 v[70:73], v[172:175], v[212:215], v[70:73]
	v_mfma_i32_16x16x64_i8 v[66:69], v[180:183], v[212:215], v[66:69]
	s_setprio 0
	s_barrier
	s_add_i32 s68, s56, s38
	v_lshl_add_u64 v[152:153], s[66:67], 0, v[134:135]
	s_mov_b32 m0, s68
	ds_read_b128 v[184:187], v155 offset:16384
	ds_read_b128 v[188:191], v155 offset:17408
	ds_read_b128 v[192:195], v155 offset:18432
	ds_read_b128 v[196:199], v155 offset:19456
	ds_read_b128 v[200:203], v155 offset:20480
	ds_read_b128 v[204:207], v155 offset:21504
	ds_read_b128 v[208:211], v155 offset:22528
	ds_read_b128 v[212:215], v155 offset:23552
	global_load_lds_dwordx4 v[152:153], off
	s_add_i32 m0, s68, 0x2000
	v_lshl_add_u64 v[216:217], s[66:67], 0, v[130:131]
	s_add_u32 s66, s66, s6
	s_addc_u32 s67, s67, s7
	s_add_i32 s68, s57, s38
	global_load_lds_dwordx4 v[216:217], off
	v_lshl_add_u64 v[218:219], s[66:67], 0, v[134:135]
	s_mov_b32 m0, s68
	v_lshl_add_u64 v[220:221], s[66:67], 0, v[130:131]
	global_load_lds_dwordx4 v[218:219], off
	s_add_i32 m0, s68, 0x2000
	v_lshl_add_u64 v[222:223], s[30:31], 0, v[136:137]
	global_load_lds_dwordx4 v[220:221], off
	s_mov_b32 m0, s41
	v_lshl_add_u64 v[224:225], s[30:31], 0, v[132:133]
	global_load_lds_dwordx4 v[222:223], off
	s_mov_b32 m0, s42
	s_nop 0
	global_load_lds_dwordx4 v[224:225], off
	s_waitcnt vmcnt(8)
	s_waitcnt lgkmcnt(0)
	s_barrier
	s_setprio 1
	s_waitcnt lgkmcnt(0)
	v_mfma_i32_16x16x64_i8 v[62:65], v[148:151], v[184:187], v[62:65]
	v_mfma_i32_16x16x64_i8 v[58:61], v[160:163], v[184:187], v[58:61]
	v_mfma_i32_16x16x64_i8 v[54:57], v[148:151], v[192:195], v[54:57]
	v_mfma_i32_16x16x64_i8 v[50:53], v[160:163], v[192:195], v[50:53]
	v_mfma_i32_16x16x64_i8 v[42:45], v[148:151], v[200:203], v[42:45]
	v_mfma_i32_16x16x64_i8 v[34:37], v[160:163], v[200:203], v[34:37]
	v_mfma_i32_16x16x64_i8 v[26:29], v[148:151], v[208:211], v[26:29]
	v_mfma_i32_16x16x64_i8 v[18:21], v[160:163], v[208:211], v[18:21]
	v_mfma_i32_16x16x64_i8 v[62:65], v[156:159], v[188:191], v[62:65]
	v_mfma_i32_16x16x64_i8 v[58:61], v[164:167], v[188:191], v[58:61]
	v_mfma_i32_16x16x64_i8 v[54:57], v[156:159], v[196:199], v[54:57]
	v_mfma_i32_16x16x64_i8 v[50:53], v[164:167], v[196:199], v[50:53]
	v_mfma_i32_16x16x64_i8 v[42:45], v[156:159], v[204:207], v[42:45]
	v_mfma_i32_16x16x64_i8 v[34:37], v[164:167], v[204:207], v[34:37]
	v_mfma_i32_16x16x64_i8 v[26:29], v[156:159], v[212:215], v[26:29]
	v_mfma_i32_16x16x64_i8 v[18:21], v[164:167], v[212:215], v[18:21]
	s_setprio 0
	s_setprio 1
	v_mfma_i32_16x16x64_i8 v[46:49], v[168:171], v[184:187], v[46:49]
	v_mfma_i32_16x16x64_i8 v[38:41], v[176:179], v[184:187], v[38:41]
	v_mfma_i32_16x16x64_i8 v[30:33], v[168:171], v[192:195], v[30:33]
	v_mfma_i32_16x16x64_i8 v[22:25], v[176:179], v[192:195], v[22:25]
	v_mfma_i32_16x16x64_i8 v[14:17], v[168:171], v[200:203], v[14:17]
	v_mfma_i32_16x16x64_i8 v[10:13], v[176:179], v[200:203], v[10:13]
	v_mfma_i32_16x16x64_i8 v[6:9], v[168:171], v[208:211], v[6:9]
	v_mfma_i32_16x16x64_i8 v[2:5], v[176:179], v[208:211], v[2:5]
	v_mfma_i32_16x16x64_i8 v[46:49], v[172:175], v[188:191], v[46:49]
	v_mfma_i32_16x16x64_i8 v[38:41], v[180:183], v[188:191], v[38:41]
	v_mfma_i32_16x16x64_i8 v[30:33], v[172:175], v[196:199], v[30:33]
	v_mfma_i32_16x16x64_i8 v[22:25], v[180:183], v[196:199], v[22:25]
	v_mfma_i32_16x16x64_i8 v[14:17], v[172:175], v[204:207], v[14:17]
	v_mfma_i32_16x16x64_i8 v[10:13], v[180:183], v[204:207], v[10:13]
	v_mfma_i32_16x16x64_i8 v[6:9], v[172:175], v[212:215], v[6:9]
	v_mfma_i32_16x16x64_i8 v[2:5], v[180:183], v[212:215], v[2:5]
	s_setprio 0
	s_barrier
	s_add_i32 s66, 0, 0x18000
	v_add_u32_e32 v138, s66, v1
	s_add_i32 s67, 0, 0x1c000
	ds_read_b128 v[148:151], v138
	ds_read_b128 v[156:159], v138 offset:1024
	ds_read_b128 v[160:163], v138 offset:2048
	ds_read_b128 v[164:167], v138 offset:3072
	v_add_u32_e32 v138, s67, v1
	ds_read_b128 v[168:171], v138
	ds_read_b128 v[172:175], v138 offset:1024
	ds_read_b128 v[176:179], v138 offset:2048
	ds_read_b128 v[180:183], v138 offset:3072
	s_add_u32 s30, s30, s6
	s_addc_u32 s31, s31, s7
	s_mov_b32 m0, s43
	v_lshl_add_u64 v[226:227], s[30:31], 0, v[136:137]
	ds_read_b128 v[184:187], v155 offset:32768
	ds_read_b128 v[188:191], v155 offset:33792
	ds_read_b128 v[192:195], v155 offset:34816
	ds_read_b128 v[196:199], v155 offset:35840
	ds_read_b128 v[200:203], v155 offset:36864
	ds_read_b128 v[204:207], v155 offset:37888
	ds_read_b128 v[208:211], v155 offset:38912
	ds_read_b128 v[212:215], v155 offset:39936
	global_load_lds_dwordx4 v[226:227], off
	v_lshl_add_u64 v[226:227], s[30:31], 0, v[132:133]
	s_mov_b32 m0, s44
	s_nop 0
	global_load_lds_dwordx4 v[226:227], off
	s_waitcnt vmcnt(8)
	s_waitcnt lgkmcnt(0)
	s_barrier
	s_setprio 1
	s_waitcnt lgkmcnt(0)
	v_mfma_i32_16x16x64_i8 v[126:129], v[148:151], v[184:187], v[126:129]
	v_mfma_i32_16x16x64_i8 v[122:125], v[160:163], v[184:187], v[122:125]
	v_mfma_i32_16x16x64_i8 v[118:121], v[148:151], v[192:195], v[118:121]
	v_mfma_i32_16x16x64_i8 v[114:117], v[160:163], v[192:195], v[114:117]
	v_mfma_i32_16x16x64_i8 v[106:109], v[148:151], v[200:203], v[106:109]
	v_mfma_i32_16x16x64_i8 v[98:101], v[160:163], v[200:203], v[98:101]
	v_mfma_i32_16x16x64_i8 v[90:93], v[148:151], v[208:211], v[90:93]
	v_mfma_i32_16x16x64_i8 v[82:85], v[160:163], v[208:211], v[82:85]
	v_mfma_i32_16x16x64_i8 v[126:129], v[156:159], v[188:191], v[126:129]
	v_mfma_i32_16x16x64_i8 v[122:125], v[164:167], v[188:191], v[122:125]
	v_mfma_i32_16x16x64_i8 v[118:121], v[156:159], v[196:199], v[118:121]
	v_mfma_i32_16x16x64_i8 v[114:117], v[164:167], v[196:199], v[114:117]
	v_mfma_i32_16x16x64_i8 v[106:109], v[156:159], v[204:207], v[106:109]
	v_mfma_i32_16x16x64_i8 v[98:101], v[164:167], v[204:207], v[98:101]
	v_mfma_i32_16x16x64_i8 v[90:93], v[156:159], v[212:215], v[90:93]
	v_mfma_i32_16x16x64_i8 v[82:85], v[164:167], v[212:215], v[82:85]
	s_setprio 0
	s_setprio 1
	v_mfma_i32_16x16x64_i8 v[110:113], v[168:171], v[184:187], v[110:113]
	v_mfma_i32_16x16x64_i8 v[102:105], v[176:179], v[184:187], v[102:105]
	v_mfma_i32_16x16x64_i8 v[94:97], v[168:171], v[192:195], v[94:97]
	v_mfma_i32_16x16x64_i8 v[86:89], v[176:179], v[192:195], v[86:89]
	v_mfma_i32_16x16x64_i8 v[78:81], v[168:171], v[200:203], v[78:81]
	v_mfma_i32_16x16x64_i8 v[74:77], v[176:179], v[200:203], v[74:77]
	v_mfma_i32_16x16x64_i8 v[70:73], v[168:171], v[208:211], v[70:73]
	v_mfma_i32_16x16x64_i8 v[66:69], v[176:179], v[208:211], v[66:69]
	v_mfma_i32_16x16x64_i8 v[110:113], v[172:175], v[188:191], v[110:113]
	v_mfma_i32_16x16x64_i8 v[102:105], v[180:183], v[188:191], v[102:105]
	v_mfma_i32_16x16x64_i8 v[94:97], v[172:175], v[196:199], v[94:97]
	v_mfma_i32_16x16x64_i8 v[86:89], v[180:183], v[196:199], v[86:89]
	v_mfma_i32_16x16x64_i8 v[78:81], v[172:175], v[204:207], v[78:81]
	v_mfma_i32_16x16x64_i8 v[74:77], v[180:183], v[204:207], v[74:77]
	v_mfma_i32_16x16x64_i8 v[70:73], v[172:175], v[212:215], v[70:73]
	v_mfma_i32_16x16x64_i8 v[66:69], v[180:183], v[212:215], v[66:69]
	s_setprio 0
	s_barrier
	s_add_i32 s30, s66, s38
	v_lshl_add_u64 v[152:153], v[152:153], 0, s[16:17]
	s_mov_b32 m0, s30
	ds_read_b128 v[184:187], v155 offset:49152
	ds_read_b128 v[188:191], v155 offset:50176
	ds_read_b128 v[192:195], v155 offset:51200
	ds_read_b128 v[196:199], v155 offset:52224
	ds_read_b128 v[200:203], v155 offset:53248
	ds_read_b128 v[204:207], v155 offset:54272
	ds_read_b128 v[208:211], v155 offset:55296
	ds_read_b128 v[212:215], v155 offset:56320
	global_load_lds_dwordx4 v[152:153], off
	v_lshl_add_u64 v[152:153], v[216:217], 0, s[16:17]
	s_add_i32 m0, s30, 0x2000
	s_add_i32 s30, s67, s38
	global_load_lds_dwordx4 v[152:153], off
	v_lshl_add_u64 v[152:153], v[218:219], 0, s[16:17]
	s_mov_b32 m0, s30
	s_nop 0
	global_load_lds_dwordx4 v[152:153], off
	v_lshl_add_u64 v[152:153], v[220:221], 0, s[16:17]
	s_add_i32 m0, s30, 0x2000
	s_nop 0
	global_load_lds_dwordx4 v[152:153], off
	v_lshl_add_u64 v[152:153], v[222:223], 0, s[16:17]
	s_mov_b32 m0, s47
	s_nop 0
	global_load_lds_dwordx4 v[152:153], off
	v_lshl_add_u64 v[152:153], v[224:225], 0, s[16:17]
	s_mov_b32 m0, s48
	s_nop 0
	global_load_lds_dwordx4 v[152:153], off
	s_waitcnt vmcnt(8)
	s_waitcnt lgkmcnt(0)
	s_barrier
	s_setprio 1
	s_waitcnt lgkmcnt(0)
	v_mfma_i32_16x16x64_i8 v[62:65], v[148:151], v[184:187], v[62:65]
	v_mfma_i32_16x16x64_i8 v[58:61], v[160:163], v[184:187], v[58:61]
	v_mfma_i32_16x16x64_i8 v[54:57], v[148:151], v[192:195], v[54:57]
	v_mfma_i32_16x16x64_i8 v[50:53], v[160:163], v[192:195], v[50:53]
	v_mfma_i32_16x16x64_i8 v[42:45], v[148:151], v[200:203], v[42:45]
	v_mfma_i32_16x16x64_i8 v[34:37], v[160:163], v[200:203], v[34:37]
	v_mfma_i32_16x16x64_i8 v[26:29], v[148:151], v[208:211], v[26:29]
	v_mfma_i32_16x16x64_i8 v[18:21], v[160:163], v[208:211], v[18:21]
	v_mfma_i32_16x16x64_i8 v[62:65], v[156:159], v[188:191], v[62:65]
	v_mfma_i32_16x16x64_i8 v[58:61], v[164:167], v[188:191], v[58:61]
	v_mfma_i32_16x16x64_i8 v[54:57], v[156:159], v[196:199], v[54:57]
	v_mfma_i32_16x16x64_i8 v[50:53], v[164:167], v[196:199], v[50:53]
	v_mfma_i32_16x16x64_i8 v[42:45], v[156:159], v[204:207], v[42:45]
	v_mfma_i32_16x16x64_i8 v[34:37], v[164:167], v[204:207], v[34:37]
	v_mfma_i32_16x16x64_i8 v[26:29], v[156:159], v[212:215], v[26:29]
	v_mfma_i32_16x16x64_i8 v[18:21], v[164:167], v[212:215], v[18:21]
	s_setprio 0
	s_setprio 1
	v_mfma_i32_16x16x64_i8 v[46:49], v[168:171], v[184:187], v[46:49]
	v_mfma_i32_16x16x64_i8 v[38:41], v[176:179], v[184:187], v[38:41]
	v_mfma_i32_16x16x64_i8 v[30:33], v[168:171], v[192:195], v[30:33]
	v_mfma_i32_16x16x64_i8 v[22:25], v[176:179], v[192:195], v[22:25]
	v_mfma_i32_16x16x64_i8 v[14:17], v[168:171], v[200:203], v[14:17]
	v_mfma_i32_16x16x64_i8 v[10:13], v[176:179], v[200:203], v[10:13]
	v_mfma_i32_16x16x64_i8 v[6:9], v[168:171], v[208:211], v[6:9]
	v_mfma_i32_16x16x64_i8 v[2:5], v[176:179], v[208:211], v[2:5]
	v_mfma_i32_16x16x64_i8 v[46:49], v[172:175], v[188:191], v[46:49]
	v_mfma_i32_16x16x64_i8 v[38:41], v[180:183], v[188:191], v[38:41]
	v_mfma_i32_16x16x64_i8 v[30:33], v[172:175], v[196:199], v[30:33]
	v_mfma_i32_16x16x64_i8 v[22:25], v[180:183], v[196:199], v[22:25]
	v_mfma_i32_16x16x64_i8 v[14:17], v[172:175], v[204:207], v[14:17]
	v_mfma_i32_16x16x64_i8 v[10:13], v[180:183], v[204:207], v[10:13]
	v_mfma_i32_16x16x64_i8 v[6:9], v[172:175], v[212:215], v[6:9]
	v_mfma_i32_16x16x64_i8 v[2:5], v[180:183], v[212:215], v[2:5]
	s_setprio 0
	s_add_u32 s28, s28, 0x100
	s_addc_u32 s29, s29, 0
	s_add_u32 s63, s63, 0x100
	s_addc_u32 s64, s64, 0
	s_cmp_ge_i32 s65, s49
	s_mov_b32 s30, s65
	s_barrier
	s_cbranch_scc0 .LBB0_2025
	v_cvt_f32_i32_e32 v158, v126
	v_cvt_f32_i32_e32 v159, v127
	v_cvt_f32_i32_e32 v160, v128
	v_cvt_f32_i32_e32 v161, v129
	v_cvt_f32_i32_e32 v156, v122
	v_cvt_f32_i32_e32 v157, v123
	v_cvt_f32_i32_e32 v162, v124
	v_cvt_f32_i32_e32 v163, v125
	v_cvt_f32_i32_e32 v166, v110
	v_cvt_f32_i32_e32 v167, v111
	v_cvt_f32_i32_e32 v170, v112
	v_cvt_f32_i32_e32 v171, v113
	v_cvt_f32_i32_e32 v164, v102
	v_cvt_f32_i32_e32 v165, v103
	v_cvt_f32_i32_e32 v168, v104
	v_cvt_f32_i32_e32 v169, v105
	v_cvt_f32_i32_e32 v122, v118
	v_cvt_f32_i32_e32 v123, v119
	v_cvt_f32_i32_e32 v126, v120
	v_cvt_f32_i32_e32 v127, v121
	v_cvt_f32_i32_e32 v120, v114
	v_cvt_f32_i32_e32 v121, v115
	v_cvt_f32_i32_e32 v124, v116
	v_cvt_f32_i32_e32 v125, v117
	v_cvt_f32_i32_e32 v148, v94
	v_cvt_f32_i32_e32 v149, v95
	v_cvt_f32_i32_e32 v152, v96
	v_cvt_f32_i32_e32 v153, v97
	v_cvt_f32_i32_e32 v128, v86
	v_cvt_f32_i32_e32 v129, v87
	v_cvt_f32_i32_e32 v150, v88
	v_cvt_f32_i32_e32 v151, v89
	v_cvt_f32_i32_e32 v96, v106
	v_cvt_f32_i32_e32 v97, v107
	v_cvt_f32_i32_e32 v102, v108
	v_cvt_f32_i32_e32 v103, v109
	v_cvt_f32_i32_e32 v94, v98
	v_cvt_f32_i32_e32 v95, v99
	v_cvt_f32_i32_e32 v98, v100
	v_cvt_f32_i32_e32 v99, v101
	v_cvt_f32_i32_e32 v110, v78
	v_cvt_f32_i32_e32 v111, v79
	v_cvt_f32_i32_e32 v114, v80
	v_cvt_f32_i32_e32 v115, v81
	v_cvt_f32_i32_e32 v108, v74
	v_cvt_f32_i32_e32 v109, v75
	v_cvt_f32_i32_e32 v112, v76
	v_cvt_f32_i32_e32 v113, v77
	v_cvt_f32_i32_e32 v80, v90
	v_cvt_f32_i32_e32 v81, v91
	v_cvt_f32_i32_e32 v86, v92
	v_cvt_f32_i32_e32 v87, v93
	v_cvt_f32_i32_e32 v78, v82
	v_cvt_f32_i32_e32 v79, v83
	v_cvt_f32_i32_e32 v82, v84
	v_cvt_f32_i32_e32 v83, v85
	v_cvt_f32_i32_e32 v88, v70
	v_cvt_f32_i32_e32 v89, v71
	v_cvt_f32_i32_e32 v92, v72
	v_cvt_f32_i32_e32 v93, v73
	v_cvt_f32_i32_e32 v84, v66
	v_cvt_f32_i32_e32 v85, v67
	v_cvt_f32_i32_e32 v90, v68
	v_cvt_f32_i32_e32 v91, v69
	v_cvt_f32_i32_e32 v66, v62
	v_cvt_f32_i32_e32 v67, v63
	v_cvt_f32_i32_e32 v68, v64
	v_cvt_f32_i32_e32 v69, v65
	v_cvt_f32_i32_e32 v62, v58
	v_cvt_f32_i32_e32 v63, v59
	v_cvt_f32_i32_e32 v64, v60
	v_cvt_f32_i32_e32 v65, v61
	v_cvt_f32_i32_e32 v72, v46
	v_cvt_f32_i32_e32 v73, v47
	v_cvt_f32_i32_e32 v76, v48
	v_cvt_f32_i32_e32 v77, v49
	v_cvt_f32_i32_e32 v70, v38
	v_cvt_f32_i32_e32 v71, v39
	v_cvt_f32_i32_e32 v74, v40
	v_cvt_f32_i32_e32 v75, v41
	v_cvt_f32_i32_e32 v48, v54
	v_cvt_f32_i32_e32 v49, v55
	v_cvt_f32_i32_e32 v54, v56
	v_cvt_f32_i32_e32 v55, v57
	v_cvt_f32_i32_e32 v46, v50
	v_cvt_f32_i32_e32 v47, v51
	v_cvt_f32_i32_e32 v50, v52
	v_cvt_f32_i32_e32 v51, v53
	v_cvt_f32_i32_e32 v56, v30
	v_cvt_f32_i32_e32 v57, v31
	v_cvt_f32_i32_e32 v60, v32
	v_cvt_f32_i32_e32 v61, v33
	v_cvt_f32_i32_e32 v52, v22
	v_cvt_f32_i32_e32 v53, v23
	v_cvt_f32_i32_e32 v58, v24
	v_cvt_f32_i32_e32 v59, v25
	v_cvt_f32_i32_e32 v24, v42
	v_cvt_f32_i32_e32 v25, v43
	v_cvt_f32_i32_e32 v32, v44
	v_cvt_f32_i32_e32 v33, v45
	v_cvt_f32_i32_e32 v22, v34
	v_cvt_f32_i32_e32 v23, v35
	v_cvt_f32_i32_e32 v30, v36
	v_cvt_f32_i32_e32 v31, v37
	v_cvt_f32_i32_e32 v36, v14
	v_cvt_f32_i32_e32 v37, v15
	v_cvt_f32_i32_e32 v40, v16
	v_cvt_f32_i32_e32 v41, v17
	v_cvt_f32_i32_e32 v34, v10
	v_cvt_f32_i32_e32 v35, v11
	v_cvt_f32_i32_e32 v38, v12
	v_cvt_f32_i32_e32 v39, v13
	v_cvt_f32_i32_e32 v12, v26
	v_cvt_f32_i32_e32 v13, v27
	v_cvt_f32_i32_e32 v16, v28
	v_cvt_f32_i32_e32 v17, v29
	v_cvt_f32_i32_e32 v10, v18
	v_cvt_f32_i32_e32 v11, v19
	v_cvt_f32_i32_e32 v14, v20
	v_cvt_f32_i32_e32 v15, v21
	v_cvt_f32_i32_e32 v6, v6
	v_cvt_f32_i32_e32 v7, v7
	v_cvt_f32_i32_e32 v8, v8
	v_cvt_f32_i32_e32 v9, v9
	v_cvt_f32_i32_e32 v2, v2
	v_cvt_f32_i32_e32 v3, v3
	v_cvt_f32_i32_e32 v4, v4
	v_cvt_f32_i32_e32 v5, v5

.LBB0_2098:
	ds_read_b128 v[18:21], v190
	ds_read_b128 v[22:25], v190 offset:1024
	ds_read_b128 v[26:29], v190 offset:2048
	ds_read_b128 v[30:33], v190 offset:3072
	ds_read_b128 v[2:5], v191
	ds_read_b128 v[6:9], v191 offset:1024
	ds_read_b128 v[10:13], v191 offset:2048
	ds_read_b128 v[14:17], v191 offset:3072
	s_add_i32 s67, s34, 2
	s_add_u32 s36, s30, 0x80
	s_addc_u32 s35, s31, 0
	s_cmp_eq_u32 s57, s34
	s_cselect_b32 s34, s2, s36
	s_cselect_b32 s35, s3, s35
	s_cselect_b32 s37, s29, s66
	s_cselect_b32 s36, s28, s65
	v_lshl_add_u64 v[186:187], s[30:31], 0, v[170:171]
	s_add_i32 m0, s45, 0xc000
	ds_read_b128 v[178:181], v192
	ds_read_b128 v[182:185], v192 offset:1024
	ds_read_b128 v[194:197], v192 offset:2048
	ds_read_b128 v[198:201], v192 offset:3072
	ds_read_b128 v[202:205], v192 offset:4096
	ds_read_b128 v[206:209], v192 offset:5120
	ds_read_b128 v[210:213], v192 offset:6144
	ds_read_b128 v[214:217], v192 offset:7168
	global_load_lds_dwordx4 v[186:187], off
	v_lshl_add_u64 v[186:187], s[30:31], 0, v[172:173]
	s_add_i32 m0, s45, 0xe000
	s_nop 0
	global_load_lds_dwordx4 v[186:187], off
	s_waitcnt vmcnt(8)
	s_waitcnt lgkmcnt(0)
	s_barrier
	s_setprio 1
	s_waitcnt lgkmcnt(0)
	v_mfma_scale_f32_16x16x128_f8f6f4 v[154:157], v[18:25], v[178:185], v[154:157], v193, v193 op_sel_hi:[0,0,0]
	v_mfma_scale_f32_16x16x128_f8f6f4 v[158:161], v[26:33], v[178:185], v[158:161], v193, v193 op_sel_hi:[0,0,0]
	v_mfma_scale_f32_16x16x128_f8f6f4 v[142:145], v[18:25], v[194:201], v[142:145], v193, v193 op_sel_hi:[0,0,0]
	v_mfma_scale_f32_16x16x128_f8f6f4 v[138:141], v[26:33], v[194:201], v[138:141], v193, v193 op_sel_hi:[0,0,0]
	v_mfma_scale_f32_16x16x128_f8f6f4 v[126:129], v[18:25], v[202:209], v[126:129], v193, v193 op_sel_hi:[0,0,0]
	v_mfma_scale_f32_16x16x128_f8f6f4 v[122:125], v[26:33], v[202:209], v[122:125], v193, v193 op_sel_hi:[0,0,0]
	v_mfma_scale_f32_16x16x128_f8f6f4 v[110:113], v[18:25], v[210:217], v[110:113], v193, v193 op_sel_hi:[0,0,0]
	v_mfma_scale_f32_16x16x128_f8f6f4 v[106:109], v[26:33], v[210:217], v[106:109], v193, v193 op_sel_hi:[0,0,0]
	s_setprio 0
	s_setprio 1
	v_mfma_scale_f32_16x16x128_f8f6f4 v[150:153], v[2:9], v[178:185], v[150:153], v193, v193 op_sel_hi:[0,0,0]
	v_mfma_scale_f32_16x16x128_f8f6f4 v[146:149], v[10:17], v[178:185], v[146:149], v193, v193 op_sel_hi:[0,0,0]
	v_mfma_scale_f32_16x16x128_f8f6f4 v[134:137], v[2:9], v[194:201], v[134:137], v193, v193 op_sel_hi:[0,0,0]
	v_mfma_scale_f32_16x16x128_f8f6f4 v[130:133], v[10:17], v[194:201], v[130:133], v193, v193 op_sel_hi:[0,0,0]
	v_mfma_scale_f32_16x16x128_f8f6f4 v[118:121], v[2:9], v[202:209], v[118:121], v193, v193 op_sel_hi:[0,0,0]
	v_mfma_scale_f32_16x16x128_f8f6f4 v[114:117], v[10:17], v[202:209], v[114:117], v193, v193 op_sel_hi:[0,0,0]
	v_mfma_scale_f32_16x16x128_f8f6f4 v[102:105], v[2:9], v[210:217], v[102:105], v193, v193 op_sel_hi:[0,0,0]
	v_mfma_scale_f32_16x16x128_f8f6f4 v[98:101], v[10:17], v[210:217], v[98:101], v193, v193 op_sel_hi:[0,0,0]
	s_setprio 0
	s_barrier
	s_add_i32 s68, s59, s42
	v_lshl_add_u64 v[178:179], s[36:37], 0, v[166:167]
	s_mov_b32 m0, s68
	ds_read_b128 v[194:197], v192 offset:16384
	ds_read_b128 v[198:201], v192 offset:17408
	ds_read_b128 v[202:205], v192 offset:18432
	ds_read_b128 v[206:209], v192 offset:19456
	ds_read_b128 v[210:213], v192 offset:20480
	ds_read_b128 v[214:217], v192 offset:21504
	ds_read_b128 v[218:221], v192 offset:22528
	ds_read_b128 v[222:225], v192 offset:23552
	global_load_lds_dwordx4 v[178:179], off
	s_add_i32 m0, s68, 0x2000
	v_lshl_add_u64 v[180:181], s[36:37], 0, v[162:163]
	s_add_u32 s36, s36, s4
	s_addc_u32 s37, s37, s5
	s_add_i32 s68, s60, s42
	global_load_lds_dwordx4 v[180:181], off
	v_lshl_add_u64 v[182:183], s[36:37], 0, v[166:167]
	s_mov_b32 m0, s68
	v_lshl_add_u64 v[184:185], s[36:37], 0, v[162:163]
	global_load_lds_dwordx4 v[182:183], off
	s_add_i32 m0, s68, 0x2000
	v_lshl_add_u64 v[186:187], s[34:35], 0, v[168:169]
	global_load_lds_dwordx4 v[184:185], off
	s_mov_b32 m0, s45
	v_lshl_add_u64 v[188:189], s[34:35], 0, v[164:165]
	global_load_lds_dwordx4 v[186:187], off
	s_mov_b32 m0, s46
	s_nop 0
	global_load_lds_dwordx4 v[188:189], off
	s_waitcnt vmcnt(8)
	s_waitcnt lgkmcnt(0)
	s_barrier
	s_setprio 1
	s_waitcnt lgkmcnt(0)
	v_mfma_scale_f32_16x16x128_f8f6f4 v[94:97], v[18:25], v[194:201], v[94:97], v193, v193 op_sel_hi:[0,0,0]
	v_mfma_scale_f32_16x16x128_f8f6f4 v[90:93], v[26:33], v[194:201], v[90:93], v193, v193 op_sel_hi:[0,0,0]
	v_mfma_scale_f32_16x16x128_f8f6f4 v[78:81], v[18:25], v[202:209], v[78:81], v193, v193 op_sel_hi:[0,0,0]
	v_mfma_scale_f32_16x16x128_f8f6f4 v[74:77], v[26:33], v[202:209], v[74:77], v193, v193 op_sel_hi:[0,0,0]
	v_mfma_scale_f32_16x16x128_f8f6f4 v[62:65], v[18:25], v[210:217], v[62:65], v193, v193 op_sel_hi:[0,0,0]
	v_mfma_scale_f32_16x16x128_f8f6f4 v[58:61], v[26:33], v[210:217], v[58:61], v193, v193 op_sel_hi:[0,0,0]
	v_mfma_scale_f32_16x16x128_f8f6f4 v[46:49], v[18:25], v[218:225], v[46:49], v193, v193 op_sel_hi:[0,0,0]
	v_mfma_scale_f32_16x16x128_f8f6f4 v[42:45], v[26:33], v[218:225], v[42:45], v193, v193 op_sel_hi:[0,0,0]
	s_setprio 0
	s_setprio 1
	v_mfma_scale_f32_16x16x128_f8f6f4 v[86:89], v[2:9], v[194:201], v[86:89], v193, v193 op_sel_hi:[0,0,0]
	v_mfma_scale_f32_16x16x128_f8f6f4 v[82:85], v[10:17], v[194:201], v[82:85], v193, v193 op_sel_hi:[0,0,0]
	v_mfma_scale_f32_16x16x128_f8f6f4 v[70:73], v[2:9], v[202:209], v[70:73], v193, v193 op_sel_hi:[0,0,0]
	v_mfma_scale_f32_16x16x128_f8f6f4 v[66:69], v[10:17], v[202:209], v[66:69], v193, v193 op_sel_hi:[0,0,0]
	v_mfma_scale_f32_16x16x128_f8f6f4 v[54:57], v[2:9], v[210:217], v[54:57], v193, v193 op_sel_hi:[0,0,0]
	v_mfma_scale_f32_16x16x128_f8f6f4 v[50:53], v[10:17], v[210:217], v[50:53], v193, v193 op_sel_hi:[0,0,0]
	v_mfma_scale_f32_16x16x128_f8f6f4 v[38:41], v[2:9], v[218:225], v[38:41], v193, v193 op_sel_hi:[0,0,0]
	v_mfma_scale_f32_16x16x128_f8f6f4 v[34:37], v[10:17], v[218:225], v[34:37], v193, v193 op_sel_hi:[0,0,0]
	s_setprio 0
	s_barrier
	s_add_i32 s36, 0, 0x18000
	s_add_i32 s37, 0, 0x1c000
	v_add_u32_e32 v14, s36, v1
	v_add_u32_e32 v30, s37, v1
	ds_read_b128 v[2:5], v14
	ds_read_b128 v[6:9], v14 offset:1024
	ds_read_b128 v[10:13], v14 offset:2048
	ds_read_b128 v[14:17], v14 offset:3072
	ds_read_b128 v[18:21], v30
	ds_read_b128 v[22:25], v30 offset:1024
	ds_read_b128 v[26:29], v30 offset:2048
	ds_read_b128 v[30:33], v30 offset:3072
	s_add_u32 s34, s34, s4
	s_addc_u32 s35, s35, s5
	s_mov_b32 m0, s47
	v_lshl_add_u64 v[226:227], s[34:35], 0, v[168:169]
	ds_read_b128 v[194:197], v192 offset:32768
	ds_read_b128 v[198:201], v192 offset:33792
	ds_read_b128 v[202:205], v192 offset:34816
	ds_read_b128 v[206:209], v192 offset:35840
	ds_read_b128 v[210:213], v192 offset:36864
	ds_read_b128 v[214:217], v192 offset:37888
	ds_read_b128 v[218:221], v192 offset:38912
	ds_read_b128 v[222:225], v192 offset:39936
	global_load_lds_dwordx4 v[226:227], off
	v_lshl_add_u64 v[226:227], s[34:35], 0, v[164:165]
	s_mov_b32 m0, s48
	s_nop 0
	global_load_lds_dwordx4 v[226:227], off
	s_waitcnt vmcnt(8)
	s_waitcnt lgkmcnt(0)
	s_barrier
	s_setprio 1
	s_waitcnt lgkmcnt(0)
	v_mfma_scale_f32_16x16x128_f8f6f4 v[154:157], v[2:9], v[194:201], v[154:157], v193, v193 op_sel_hi:[0,0,0]
	v_mfma_scale_f32_16x16x128_f8f6f4 v[158:161], v[10:17], v[194:201], v[158:161], v193, v193 op_sel_hi:[0,0,0]
	v_mfma_scale_f32_16x16x128_f8f6f4 v[142:145], v[2:9], v[202:209], v[142:145], v193, v193 op_sel_hi:[0,0,0]
	v_mfma_scale_f32_16x16x128_f8f6f4 v[138:141], v[10:17], v[202:209], v[138:141], v193, v193 op_sel_hi:[0,0,0]
	v_mfma_scale_f32_16x16x128_f8f6f4 v[126:129], v[2:9], v[210:217], v[126:129], v193, v193 op_sel_hi:[0,0,0]
	v_mfma_scale_f32_16x16x128_f8f6f4 v[122:125], v[10:17], v[210:217], v[122:125], v193, v193 op_sel_hi:[0,0,0]
	v_mfma_scale_f32_16x16x128_f8f6f4 v[110:113], v[2:9], v[218:225], v[110:113], v193, v193 op_sel_hi:[0,0,0]
	v_mfma_scale_f32_16x16x128_f8f6f4 v[106:109], v[10:17], v[218:225], v[106:109], v193, v193 op_sel_hi:[0,0,0]
	s_setprio 0
	s_setprio 1
	v_mfma_scale_f32_16x16x128_f8f6f4 v[150:153], v[18:25], v[194:201], v[150:153], v193, v193 op_sel_hi:[0,0,0]
	v_mfma_scale_f32_16x16x128_f8f6f4 v[146:149], v[26:33], v[194:201], v[146:149], v193, v193 op_sel_hi:[0,0,0]
	v_mfma_scale_f32_16x16x128_f8f6f4 v[134:137], v[18:25], v[202:209], v[134:137], v193, v193 op_sel_hi:[0,0,0]
	v_mfma_scale_f32_16x16x128_f8f6f4 v[130:133], v[26:33], v[202:209], v[130:133], v193, v193 op_sel_hi:[0,0,0]
	v_mfma_scale_f32_16x16x128_f8f6f4 v[118:121], v[18:25], v[210:217], v[118:121], v193, v193 op_sel_hi:[0,0,0]
	v_mfma_scale_f32_16x16x128_f8f6f4 v[114:117], v[26:33], v[210:217], v[114:117], v193, v193 op_sel_hi:[0,0,0]
	v_mfma_scale_f32_16x16x128_f8f6f4 v[102:105], v[18:25], v[218:225], v[102:105], v193, v193 op_sel_hi:[0,0,0]
	v_mfma_scale_f32_16x16x128_f8f6f4 v[98:101], v[26:33], v[218:225], v[98:101], v193, v193 op_sel_hi:[0,0,0]
	s_setprio 0
	s_barrier
	s_add_i32 s34, s36, s42
	v_lshl_add_u64 v[178:179], v[178:179], 0, s[12:13]
	s_mov_b32 m0, s34
	ds_read_b128 v[194:197], v192 offset:49152
	ds_read_b128 v[198:201], v192 offset:50176
	ds_read_b128 v[202:205], v192 offset:51200
	ds_read_b128 v[206:209], v192 offset:52224
	ds_read_b128 v[210:213], v192 offset:53248
	ds_read_b128 v[214:217], v192 offset:54272
	ds_read_b128 v[218:221], v192 offset:55296
	ds_read_b128 v[222:225], v192 offset:56320
	global_load_lds_dwordx4 v[178:179], off
	v_lshl_add_u64 v[178:179], v[180:181], 0, s[12:13]
	s_add_i32 m0, s34, 0x2000
	s_add_i32 s34, s37, s42
	global_load_lds_dwordx4 v[178:179], off
	v_lshl_add_u64 v[178:179], v[182:183], 0, s[12:13]
	s_mov_b32 m0, s34
	s_nop 0
	global_load_lds_dwordx4 v[178:179], off
	v_lshl_add_u64 v[178:179], v[184:185], 0, s[12:13]
	s_add_i32 m0, s34, 0x2000
	s_nop 0
	global_load_lds_dwordx4 v[178:179], off
	v_lshl_add_u64 v[178:179], v[186:187], 0, s[12:13]
	s_mov_b32 m0, s51
	s_nop 0
	global_load_lds_dwordx4 v[178:179], off
	v_lshl_add_u64 v[178:179], v[188:189], 0, s[12:13]
	s_mov_b32 m0, s52
	s_nop 0
	global_load_lds_dwordx4 v[178:179], off
	s_waitcnt vmcnt(8)
	s_waitcnt lgkmcnt(0)
	s_barrier
	s_setprio 1
	s_waitcnt lgkmcnt(0)
	v_mfma_scale_f32_16x16x128_f8f6f4 v[94:97], v[2:9], v[194:201], v[94:97], v193, v193 op_sel_hi:[0,0,0]
	v_mfma_scale_f32_16x16x128_f8f6f4 v[90:93], v[10:17], v[194:201], v[90:93], v193, v193 op_sel_hi:[0,0,0]
	v_mfma_scale_f32_16x16x128_f8f6f4 v[78:81], v[2:9], v[202:209], v[78:81], v193, v193 op_sel_hi:[0,0,0]
	v_mfma_scale_f32_16x16x128_f8f6f4 v[74:77], v[10:17], v[202:209], v[74:77], v193, v193 op_sel_hi:[0,0,0]
	v_mfma_scale_f32_16x16x128_f8f6f4 v[62:65], v[2:9], v[210:217], v[62:65], v193, v193 op_sel_hi:[0,0,0]
	v_mfma_scale_f32_16x16x128_f8f6f4 v[58:61], v[10:17], v[210:217], v[58:61], v193, v193 op_sel_hi:[0,0,0]
	v_mfma_scale_f32_16x16x128_f8f6f4 v[46:49], v[2:9], v[218:225], v[46:49], v193, v193 op_sel_hi:[0,0,0]
	v_mfma_scale_f32_16x16x128_f8f6f4 v[42:45], v[10:17], v[218:225], v[42:45], v193, v193 op_sel_hi:[0,0,0]
	s_setprio 0
	s_setprio 1
	v_mfma_scale_f32_16x16x128_f8f6f4 v[86:89], v[18:25], v[194:201], v[86:89], v193, v193 op_sel_hi:[0,0,0]
	v_mfma_scale_f32_16x16x128_f8f6f4 v[82:85], v[26:33], v[194:201], v[82:85], v193, v193 op_sel_hi:[0,0,0]
	v_mfma_scale_f32_16x16x128_f8f6f4 v[70:73], v[18:25], v[202:209], v[70:73], v193, v193 op_sel_hi:[0,0,0]
	v_mfma_scale_f32_16x16x128_f8f6f4 v[66:69], v[26:33], v[202:209], v[66:69], v193, v193 op_sel_hi:[0,0,0]
	v_mfma_scale_f32_16x16x128_f8f6f4 v[54:57], v[18:25], v[210:217], v[54:57], v193, v193 op_sel_hi:[0,0,0]
	v_mfma_scale_f32_16x16x128_f8f6f4 v[50:53], v[26:33], v[210:217], v[50:53], v193, v193 op_sel_hi:[0,0,0]
	v_mfma_scale_f32_16x16x128_f8f6f4 v[38:41], v[18:25], v[218:225], v[38:41], v193, v193 op_sel_hi:[0,0,0]
	v_mfma_scale_f32_16x16x128_f8f6f4 v[34:37], v[26:33], v[218:225], v[34:37], v193, v193 op_sel_hi:[0,0,0]
	s_setprio 0
	s_add_u32 s30, s30, 0x100
	s_addc_u32 s31, s31, 0
	s_add_u32 s65, s65, 0x100
	s_addc_u32 s66, s66, 0
	s_cmp_ge_i32 s67, s53
	s_mov_b32 s34, s67
	s_barrier
	s_cbranch_scc0 .LBB0_2098
